# K-loop LDS-DMA: 136 of 192 VALU address adds removed (saddr form / offset:128 with M0-128); plus setprio+waitcnt trims of v17
# baseline (speedup 1.0000x reference)
.LBB0_556:
	ds_read_b128 v[0:3], v211
	ds_read_b128 v[4:7], v211 offset:1024
	ds_read_b128 v[8:11], v211 offset:2048
	ds_read_b128 v[12:15], v211 offset:3072
	ds_read_b128 v[144:147], v212
	ds_read_b128 v[170:173], v212 offset:1024
	ds_read_b128 v[174:177], v212 offset:2048
	ds_read_b128 v[178:181], v212 offset:3072
	s_add_u32 s8, s6, 0xfff80080
	s_addc_u32 s9, s7, -1
	s_cmp_eq_u32 s61, 28
	s_cselect_b32 s11, s55, s9
	s_cselect_b32 s10, s54, s8
	s_cselect_b32 s9, s57, s60
	s_cselect_b32 s8, s56, s5
	s_nop 0
	s_add_i32 m0, s17, 0xc000
	ds_read_b128 v[182:185], v213
	ds_read_b128 v[186:189], v213 offset:1024
	ds_read_b128 v[190:193], v213 offset:2048
	ds_read_b128 v[194:197], v213 offset:3072
	ds_read_b128 v[198:201], v213 offset:4096
	ds_read_b128 v[218:221], v213 offset:5120
	ds_read_b128 v[222:225], v213 offset:6144
	ds_read_b128 v[226:229], v213 offset:7168
	global_load_lds_dwordx4 v162, s[6:7]
	s_nop 0
	s_add_i32 m0, s17, 0xe000
	s_nop 0
	global_load_lds_dwordx4 v160, s[6:7]
	s_waitcnt vmcnt(8)
	s_waitcnt lgkmcnt(0)
	s_setprio 1
	s_barrier
	v_mfma_f32_16x16x32_bf16 v[92:95], v[0:3], v[182:185], v[92:95]
	v_mfma_f32_16x16x32_bf16 v[88:91], v[8:11], v[182:185], v[88:91]
	v_mfma_f32_16x16x32_bf16 v[116:119], v[0:3], v[190:193], v[116:119]
	v_mfma_f32_16x16x32_bf16 v[108:111], v[8:11], v[190:193], v[108:111]
	v_mfma_f32_16x16x32_bf16 v[124:127], v[0:3], v[198:201], v[124:127]
	v_mfma_f32_16x16x32_bf16 v[120:123], v[8:11], v[198:201], v[120:123]
	v_mfma_f32_16x16x32_bf16 v[100:103], v[0:3], v[222:225], v[100:103]
	v_mfma_f32_16x16x32_bf16 v[96:99], v[8:11], v[222:225], v[96:99]
	v_mfma_f32_16x16x32_bf16 v[92:95], v[4:7], v[186:189], v[92:95]
	v_mfma_f32_16x16x32_bf16 v[88:91], v[12:15], v[186:189], v[88:91]
	v_mfma_f32_16x16x32_bf16 v[116:119], v[4:7], v[194:197], v[116:119]
	v_mfma_f32_16x16x32_bf16 v[108:111], v[12:15], v[194:197], v[108:111]
	v_mfma_f32_16x16x32_bf16 v[124:127], v[4:7], v[218:221], v[124:127]
	v_mfma_f32_16x16x32_bf16 v[120:123], v[12:15], v[218:221], v[120:123]
	v_mfma_f32_16x16x32_bf16 v[100:103], v[4:7], v[226:229], v[100:103]
	v_mfma_f32_16x16x32_bf16 v[96:99], v[12:15], v[226:229], v[96:99]
	v_mfma_f32_16x16x32_bf16 v[140:143], v[144:147], v[182:185], v[140:143]
	v_mfma_f32_16x16x32_bf16 v[136:139], v[174:177], v[182:185], v[136:139]
	v_mfma_f32_16x16x32_bf16 v[132:135], v[144:147], v[190:193], v[132:135]
	v_mfma_f32_16x16x32_bf16 v[128:131], v[174:177], v[190:193], v[128:131]
	v_mfma_f32_16x16x32_bf16 v[112:115], v[144:147], v[198:201], v[112:115]
	v_mfma_f32_16x16x32_bf16 v[104:107], v[174:177], v[198:201], v[104:107]
	v_mfma_f32_16x16x32_bf16 v[84:87], v[144:147], v[222:225], v[84:87]
	v_mfma_f32_16x16x32_bf16 v[80:83], v[174:177], v[222:225], v[80:83]
	v_mfma_f32_16x16x32_bf16 v[140:143], v[170:173], v[186:189], v[140:143]
	v_mfma_f32_16x16x32_bf16 v[136:139], v[178:181], v[186:189], v[136:139]
	v_mfma_f32_16x16x32_bf16 v[132:135], v[170:173], v[194:197], v[132:135]
	v_mfma_f32_16x16x32_bf16 v[128:131], v[178:181], v[194:197], v[128:131]
	v_mfma_f32_16x16x32_bf16 v[112:115], v[170:173], v[218:221], v[112:115]
	v_mfma_f32_16x16x32_bf16 v[104:107], v[178:181], v[218:221], v[104:107]
	v_mfma_f32_16x16x32_bf16 v[84:87], v[170:173], v[226:229], v[84:87]
	v_mfma_f32_16x16x32_bf16 v[80:83], v[178:181], v[226:229], v[80:83]
	s_barrier
	s_setprio 0
	s_add_i32 s62, s77, s23
	v_lshl_add_u64 v[230:231], s[8:9], 0, v[150:151]
	s_mov_b32 m0, s62
	ds_read_b128 v[182:185], v213 offset:16384
	ds_read_b128 v[186:189], v213 offset:17408
	ds_read_b128 v[190:193], v213 offset:18432
	ds_read_b128 v[194:197], v213 offset:19456
	ds_read_b128 v[198:201], v213 offset:20480
	ds_read_b128 v[218:221], v213 offset:21504
	ds_read_b128 v[222:225], v213 offset:22528
	ds_read_b128 v[226:229], v213 offset:23552
	global_load_lds_dwordx4 v[230:231], off
	s_add_i32 m0, s62, 0x2000
	s_add_u32 s62, s8, 0x80000
	v_lshl_add_u64 v[232:233], s[8:9], 0, v[154:155]
	s_addc_u32 s63, s9, 0
	s_add_i32 s92, s78, s23
	global_load_lds_dwordx4 v[232:233], off
	s_nop 0
	s_mov_b32 m0, s92
	v_lshl_add_u64 v[236:237], s[10:11], 0, v[152:153]
	global_load_lds_dwordx4 v150, s[62:63]
	s_nop 0
	s_add_i32 m0, s92, 0x2000
	s_nop 0
	global_load_lds_dwordx4 v154, s[62:63]
	v_lshl_add_u64 v[234:235], s[10:11], 0, v[148:149]
	s_mov_b32 m0, s17
	s_nop 0
	global_load_lds_dwordx4 v[234:235], off
	s_mov_b32 m0, s53
	s_nop 0
	global_load_lds_dwordx4 v[236:237], off
	s_waitcnt vmcnt(8)
	s_waitcnt lgkmcnt(0)
	s_setprio 1
	s_barrier
	v_mfma_f32_16x16x32_bf16 v[76:79], v[0:3], v[182:185], v[76:79]
	v_mfma_f32_16x16x32_bf16 v[72:75], v[8:11], v[182:185], v[72:75]
	v_mfma_f32_16x16x32_bf16 v[60:63], v[0:3], v[190:193], v[60:63]
	v_mfma_f32_16x16x32_bf16 v[56:59], v[8:11], v[190:193], v[56:59]
	v_mfma_f32_16x16x32_bf16 v[44:47], v[0:3], v[198:201], v[44:47]
	v_mfma_f32_16x16x32_bf16 v[40:43], v[8:11], v[198:201], v[40:43]
	v_mfma_f32_16x16x32_bf16 v[0:3], v[0:3], v[222:225], v[28:31]
	v_mfma_f32_16x16x32_bf16 v[76:79], v[4:7], v[186:189], v[76:79]
	v_mfma_f32_16x16x32_bf16 v[72:75], v[12:15], v[186:189], v[72:75]
	v_mfma_f32_16x16x32_bf16 v[60:63], v[4:7], v[194:197], v[60:63]
	v_mfma_f32_16x16x32_bf16 v[56:59], v[12:15], v[194:197], v[56:59]
	v_mfma_f32_16x16x32_bf16 v[44:47], v[4:7], v[218:221], v[44:47]
	v_mfma_f32_16x16x32_bf16 v[40:43], v[12:15], v[218:221], v[40:43]
	v_mfma_f32_16x16x32_bf16 v[0:3], v[4:7], v[226:229], v[0:3]
	v_mfma_f32_16x16x32_bf16 v[4:7], v[8:11], v[222:225], v[20:23]
	v_mfma_f32_16x16x32_bf16 v[4:7], v[12:15], v[226:229], v[4:7]
	v_mfma_f32_16x16x32_bf16 v[20:23], v[144:147], v[190:193], v[52:55]
	v_mfma_f32_16x16x32_bf16 v[52:55], v[170:173], v[194:197], v[20:23]
	v_mfma_f32_16x16x32_bf16 v[20:23], v[174:177], v[190:193], v[48:51]
	v_mfma_f32_16x16x32_bf16 v[48:51], v[178:181], v[194:197], v[20:23]
	v_mfma_f32_16x16x32_bf16 v[20:23], v[144:147], v[198:201], v[36:39]
	v_mfma_f32_16x16x32_bf16 v[36:39], v[170:173], v[218:221], v[20:23]
	v_mfma_f32_16x16x32_bf16 v[20:23], v[174:177], v[198:201], v[32:35]
	v_mfma_f32_16x16x32_bf16 v[32:35], v[178:181], v[218:221], v[20:23]
	v_mfma_f32_16x16x32_bf16 v[20:23], v[144:147], v[222:225], v[24:27]
	v_mfma_f32_16x16x32_bf16 v[16:19], v[174:177], v[222:225], v[16:19]
	v_mfma_f32_16x16x32_bf16 v[8:11], v[144:147], v[182:185], v[68:71]
	v_mfma_f32_16x16x32_bf16 v[12:15], v[174:177], v[182:185], v[64:67]
	v_mfma_f32_16x16x32_bf16 v[24:27], v[170:173], v[226:229], v[20:23]
	v_mfma_f32_16x16x32_bf16 v[16:19], v[178:181], v[226:229], v[16:19]
	v_mfma_f32_16x16x32_bf16 v[8:11], v[170:173], v[186:189], v[8:11]
	v_mfma_f32_16x16x32_bf16 v[12:15], v[178:181], v[186:189], v[12:15]
	s_barrier
	s_setprio 0
	ds_read_b128 v[20:23], v214
	ds_read_b128 v[28:31], v214 offset:1024
	ds_read_b128 v[64:67], v214 offset:2048
	ds_read_b128 v[68:71], v214 offset:3072
	ds_read_b128 v[144:147], v215
	ds_read_b128 v[170:173], v215 offset:1024
	ds_read_b128 v[174:177], v215 offset:2048
	ds_read_b128 v[178:181], v215 offset:3072
	s_add_u32 s10, s10, 0x80000
	s_addc_u32 s11, s11, 0
	s_mov_b32 m0, s64
	s_nop 0
	ds_read_b128 v[182:185], v213 offset:32768
	ds_read_b128 v[186:189], v213 offset:33792
	ds_read_b128 v[190:193], v213 offset:34816
	ds_read_b128 v[194:197], v213 offset:35840
	ds_read_b128 v[198:201], v213 offset:36864
	ds_read_b128 v[218:221], v213 offset:37888
	ds_read_b128 v[222:225], v213 offset:38912
	ds_read_b128 v[226:229], v213 offset:39936
	global_load_lds_dwordx4 v148, s[10:11]
	s_nop 0
	s_mov_b32 m0, s65
	s_nop 0
	global_load_lds_dwordx4 v152, s[10:11]
	s_waitcnt vmcnt(8)
	s_waitcnt lgkmcnt(0)
	s_setprio 1
	s_barrier
	v_mfma_f32_16x16x32_bf16 v[92:95], v[20:23], v[182:185], v[92:95]
	v_mfma_f32_16x16x32_bf16 v[88:91], v[64:67], v[182:185], v[88:91]
	v_mfma_f32_16x16x32_bf16 v[116:119], v[20:23], v[190:193], v[116:119]
	v_mfma_f32_16x16x32_bf16 v[108:111], v[64:67], v[190:193], v[108:111]
	v_mfma_f32_16x16x32_bf16 v[124:127], v[20:23], v[198:201], v[124:127]
	v_mfma_f32_16x16x32_bf16 v[120:123], v[64:67], v[198:201], v[120:123]
	v_mfma_f32_16x16x32_bf16 v[100:103], v[20:23], v[222:225], v[100:103]
	v_mfma_f32_16x16x32_bf16 v[96:99], v[64:67], v[222:225], v[96:99]
	v_mfma_f32_16x16x32_bf16 v[92:95], v[28:31], v[186:189], v[92:95]
	v_mfma_f32_16x16x32_bf16 v[88:91], v[68:71], v[186:189], v[88:91]
	v_mfma_f32_16x16x32_bf16 v[116:119], v[28:31], v[194:197], v[116:119]
	v_mfma_f32_16x16x32_bf16 v[108:111], v[68:71], v[194:197], v[108:111]
	v_mfma_f32_16x16x32_bf16 v[124:127], v[28:31], v[218:221], v[124:127]
	v_mfma_f32_16x16x32_bf16 v[120:123], v[68:71], v[218:221], v[120:123]
	v_mfma_f32_16x16x32_bf16 v[100:103], v[28:31], v[226:229], v[100:103]
	v_mfma_f32_16x16x32_bf16 v[96:99], v[68:71], v[226:229], v[96:99]
	v_mfma_f32_16x16x32_bf16 v[140:143], v[144:147], v[182:185], v[140:143]
	v_mfma_f32_16x16x32_bf16 v[136:139], v[174:177], v[182:185], v[136:139]
	v_mfma_f32_16x16x32_bf16 v[132:135], v[144:147], v[190:193], v[132:135]
	v_mfma_f32_16x16x32_bf16 v[128:131], v[174:177], v[190:193], v[128:131]
	v_mfma_f32_16x16x32_bf16 v[112:115], v[144:147], v[198:201], v[112:115]
	v_mfma_f32_16x16x32_bf16 v[104:107], v[174:177], v[198:201], v[104:107]
	v_mfma_f32_16x16x32_bf16 v[84:87], v[144:147], v[222:225], v[84:87]
	v_mfma_f32_16x16x32_bf16 v[80:83], v[174:177], v[222:225], v[80:83]
	v_mfma_f32_16x16x32_bf16 v[140:143], v[170:173], v[186:189], v[140:143]
	v_mfma_f32_16x16x32_bf16 v[136:139], v[178:181], v[186:189], v[136:139]
	v_mfma_f32_16x16x32_bf16 v[132:135], v[170:173], v[194:197], v[132:135]
	v_mfma_f32_16x16x32_bf16 v[128:131], v[178:181], v[194:197], v[128:131]
	v_mfma_f32_16x16x32_bf16 v[112:115], v[170:173], v[218:221], v[112:115]
	v_mfma_f32_16x16x32_bf16 v[104:107], v[178:181], v[218:221], v[104:107]
	v_mfma_f32_16x16x32_bf16 v[84:87], v[170:173], v[226:229], v[84:87]
	v_mfma_f32_16x16x32_bf16 v[80:83], v[178:181], v[226:229], v[80:83]
	s_barrier
	s_setprio 0
	s_add_i32 s10, s80, s23
	s_nop 0
	s_add_i32 m0, s10, 0xffffff80
	ds_read_b128 v[182:185], v213 offset:49152
	ds_read_b128 v[186:189], v213 offset:50176
	ds_read_b128 v[190:193], v213 offset:51200
	ds_read_b128 v[194:197], v213 offset:52224
	ds_read_b128 v[198:201], v213 offset:53248
	ds_read_b128 v[218:221], v213 offset:54272
	ds_read_b128 v[222:225], v213 offset:55296
	ds_read_b128 v[226:229], v213 offset:56320
	global_load_lds_dwordx4 v[230:231], off offset:128
	s_add_i32 m0, s10, 0x1f80
	s_add_u32 s8, s8, 0x80080
	s_nop 0
	s_addc_u32 s9, s9, 0
	s_add_i32 s10, s81, s23
	global_load_lds_dwordx4 v[232:233], off offset:128
	s_nop 0
	s_mov_b32 m0, s10
	s_nop 0
	global_load_lds_dwordx4 v150, s[8:9]
	s_nop 0
	s_add_i32 m0, s10, 0x2000
	s_nop 0
	global_load_lds_dwordx4 v154, s[8:9]
	s_nop 0
	s_add_i32 m0, s66, 0xffffff80
	s_nop 0
	global_load_lds_dwordx4 v[234:235], off offset:128
	s_nop 0
	s_add_i32 m0, s67, 0xffffff80
	s_nop 0
	global_load_lds_dwordx4 v[236:237], off offset:128
	s_waitcnt vmcnt(8)
	s_waitcnt lgkmcnt(0)
	s_setprio 1
	s_barrier
	v_mfma_f32_16x16x32_bf16 v[76:79], v[20:23], v[182:185], v[76:79]
	v_mfma_f32_16x16x32_bf16 v[60:63], v[20:23], v[190:193], v[60:63]
	v_mfma_f32_16x16x32_bf16 v[44:47], v[20:23], v[198:201], v[44:47]
	v_mfma_f32_16x16x32_bf16 v[0:3], v[20:23], v[222:225], v[0:3]
	v_mfma_f32_16x16x32_bf16 v[76:79], v[28:31], v[186:189], v[76:79]
	v_mfma_f32_16x16x32_bf16 v[72:75], v[64:67], v[182:185], v[72:75]
	v_mfma_f32_16x16x32_bf16 v[60:63], v[28:31], v[194:197], v[60:63]
	v_mfma_f32_16x16x32_bf16 v[56:59], v[64:67], v[190:193], v[56:59]
	v_mfma_f32_16x16x32_bf16 v[44:47], v[28:31], v[218:221], v[44:47]
	v_mfma_f32_16x16x32_bf16 v[40:43], v[64:67], v[198:201], v[40:43]
	v_mfma_f32_16x16x32_bf16 v[28:31], v[28:31], v[226:229], v[0:3]
	v_mfma_f32_16x16x32_bf16 v[0:3], v[64:67], v[222:225], v[4:7]
	v_mfma_f32_16x16x32_bf16 v[72:75], v[68:71], v[186:189], v[72:75]
	v_mfma_f32_16x16x32_bf16 v[56:59], v[68:71], v[194:197], v[56:59]
	v_mfma_f32_16x16x32_bf16 v[40:43], v[68:71], v[218:221], v[40:43]
	v_mfma_f32_16x16x32_bf16 v[20:23], v[68:71], v[226:229], v[0:3]
	v_mfma_f32_16x16x32_bf16 v[0:3], v[144:147], v[182:185], v[8:11]
	v_mfma_f32_16x16x32_bf16 v[68:71], v[170:173], v[186:189], v[0:3]
	v_mfma_f32_16x16x32_bf16 v[0:3], v[174:177], v[182:185], v[12:15]
	v_mfma_f32_16x16x32_bf16 v[64:67], v[178:181], v[186:189], v[0:3]
	v_mfma_f32_16x16x32_bf16 v[0:3], v[144:147], v[190:193], v[52:55]
	v_mfma_f32_16x16x32_bf16 v[52:55], v[170:173], v[194:197], v[0:3]
	v_mfma_f32_16x16x32_bf16 v[0:3], v[174:177], v[190:193], v[48:51]
	v_mfma_f32_16x16x32_bf16 v[48:51], v[178:181], v[194:197], v[0:3]
	v_mfma_f32_16x16x32_bf16 v[0:3], v[144:147], v[198:201], v[36:39]
	v_mfma_f32_16x16x32_bf16 v[36:39], v[170:173], v[218:221], v[0:3]
	v_mfma_f32_16x16x32_bf16 v[0:3], v[174:177], v[198:201], v[32:35]
	v_mfma_f32_16x16x32_bf16 v[32:35], v[178:181], v[218:221], v[0:3]
	v_mfma_f32_16x16x32_bf16 v[0:3], v[144:147], v[222:225], v[24:27]
	v_mfma_f32_16x16x32_bf16 v[24:27], v[170:173], v[226:229], v[0:3]
	v_mfma_f32_16x16x32_bf16 v[0:3], v[174:177], v[222:225], v[16:19]
	v_mfma_f32_16x16x32_bf16 v[16:19], v[178:181], v[226:229], v[0:3]
	s_barrier
	s_setprio 0
	s_add_i32 s61, s61, 2
	s_add_u32 s5, s5, 0x100
	s_addc_u32 s60, s60, 0
	s_add_u32 s6, s6, 0x100
	s_addc_u32 s7, s7, 0
	s_cmp_gt_u32 s61, 29
	s_cbranch_scc0 .LBB0_556
	s_and_b64 vcc, exec, s[34:35]
	s_cbranch_vccz .LBB0_559
	s_barrier

.LBB0_1778:
	s_or_b32 s42, s31, 1
	s_lshl_b64 s[92:93], s[42:43], 7
	s_add_i32 s42, s31, 2
	s_lshl_b64 vcc, s[42:43], 7
	s_add_u32 s40, s62, vcc_lo
	s_addc_u32 s41, s63, vcc_hi
	s_and_b64 s[72:73], s[70:71], exec
	s_cselect_b32 s73, s41, s57
	s_cselect_b32 s72, s40, s56
	s_add_u32 s40, s64, vcc_lo
	s_addc_u32 s41, s65, vcc_hi
	s_add_i32 s55, 0, 0x10000
	s_and_b64 s[70:71], s[70:71], exec
	s_cselect_b32 s71, s41, s59
	s_cselect_b32 s70, s40, s58
	s_add_i32 s40, 0, 0x14000
	v_add_u32_e32 v140, s55, v169
	v_add_u32_e32 v182, s40, v169
	ds_read_b128 v[128:131], v140
	ds_read_b128 v[132:135], v140 offset:1024
	ds_read_b128 v[136:139], v140 offset:2048
	ds_read_b128 v[140:143], v140 offset:3072
	ds_read_b128 v[160:163], v182
	ds_read_b128 v[174:177], v182 offset:1024
	ds_read_b128 v[178:181], v182 offset:2048
	ds_read_b128 v[182:185], v182 offset:3072
	s_add_u32 s41, s62, s92
	s_addc_u32 s61, s63, s93
	s_add_u32 s92, s41, 0x80000
	s_addc_u32 s93, s61, 0
	s_nop 0
	s_add_i32 m0, s7, 0xc000
	ds_read_b128 v[186:189], v173
	ds_read_b128 v[190:193], v173 offset:1024
	ds_read_b128 v[194:197], v173 offset:2048
	ds_read_b128 v[198:201], v173 offset:3072
	ds_read_b128 v[206:209], v173 offset:4096
	ds_read_b128 v[210:213], v173 offset:5120
	ds_read_b128 v[214:217], v173 offset:6144
	ds_read_b128 v[218:221], v173 offset:7168
	global_load_lds_dwordx4 v152, s[92:93]
	s_nop 0
	s_add_i32 m0, s7, 0xe000
	s_nop 0
	global_load_lds_dwordx4 v154, s[92:93]
	s_waitcnt vmcnt(8)
	s_waitcnt lgkmcnt(0)
	s_setprio 1
	s_barrier
	v_mfma_f32_16x16x32_bf16 v[124:127], v[128:131], v[186:189], v[124:127]
	v_mfma_f32_16x16x32_bf16 v[120:123], v[136:139], v[186:189], v[120:123]
	v_mfma_f32_16x16x32_bf16 v[108:111], v[128:131], v[194:197], v[108:111]
	v_mfma_f32_16x16x32_bf16 v[104:107], v[136:139], v[194:197], v[104:107]
	v_mfma_f32_16x16x32_bf16 v[92:95], v[128:131], v[206:209], v[92:95]
	v_mfma_f32_16x16x32_bf16 v[88:91], v[136:139], v[206:209], v[88:91]
	v_mfma_f32_16x16x32_bf16 v[76:79], v[128:131], v[214:217], v[76:79]
	v_mfma_f32_16x16x32_bf16 v[72:75], v[136:139], v[214:217], v[72:75]
	v_mfma_f32_16x16x32_bf16 v[124:127], v[132:135], v[190:193], v[124:127]
	v_mfma_f32_16x16x32_bf16 v[120:123], v[140:143], v[190:193], v[120:123]
	v_mfma_f32_16x16x32_bf16 v[108:111], v[132:135], v[198:201], v[108:111]
	v_mfma_f32_16x16x32_bf16 v[104:107], v[140:143], v[198:201], v[104:107]
	v_mfma_f32_16x16x32_bf16 v[92:95], v[132:135], v[210:213], v[92:95]
	v_mfma_f32_16x16x32_bf16 v[88:91], v[140:143], v[210:213], v[88:91]
	v_mfma_f32_16x16x32_bf16 v[76:79], v[132:135], v[218:221], v[76:79]
	v_mfma_f32_16x16x32_bf16 v[72:75], v[140:143], v[218:221], v[72:75]
	v_mfma_f32_16x16x32_bf16 v[116:119], v[160:163], v[186:189], v[116:119]
	v_mfma_f32_16x16x32_bf16 v[112:115], v[178:181], v[186:189], v[112:115]
	v_mfma_f32_16x16x32_bf16 v[100:103], v[160:163], v[194:197], v[100:103]
	v_mfma_f32_16x16x32_bf16 v[96:99], v[178:181], v[194:197], v[96:99]
	v_mfma_f32_16x16x32_bf16 v[84:87], v[160:163], v[206:209], v[84:87]
	v_mfma_f32_16x16x32_bf16 v[80:83], v[178:181], v[206:209], v[80:83]
	v_mfma_f32_16x16x32_bf16 v[68:71], v[160:163], v[214:217], v[68:71]
	v_mfma_f32_16x16x32_bf16 v[64:67], v[178:181], v[214:217], v[64:67]
	v_mfma_f32_16x16x32_bf16 v[116:119], v[174:177], v[190:193], v[116:119]
	v_mfma_f32_16x16x32_bf16 v[112:115], v[182:185], v[190:193], v[112:115]
	v_mfma_f32_16x16x32_bf16 v[100:103], v[174:177], v[198:201], v[100:103]
	v_mfma_f32_16x16x32_bf16 v[96:99], v[182:185], v[198:201], v[96:99]
	v_mfma_f32_16x16x32_bf16 v[84:87], v[174:177], v[210:213], v[84:87]
	v_mfma_f32_16x16x32_bf16 v[80:83], v[182:185], v[210:213], v[80:83]
	v_mfma_f32_16x16x32_bf16 v[68:71], v[174:177], v[218:221], v[68:71]
	v_mfma_f32_16x16x32_bf16 v[64:67], v[182:185], v[218:221], v[64:67]
	s_barrier
	s_setprio 0
	s_add_i32 s41, s55, s6
	v_lshl_add_u64 v[202:203], s[70:71], 0, v[144:145]
	s_mov_b32 m0, s41
	ds_read_b128 v[186:189], v173 offset:16384
	ds_read_b128 v[190:193], v173 offset:17408
	ds_read_b128 v[194:197], v173 offset:18432
	ds_read_b128 v[198:201], v173 offset:19456
	ds_read_b128 v[206:209], v173 offset:20480
	ds_read_b128 v[210:213], v173 offset:21504
	ds_read_b128 v[214:217], v173 offset:22528
	ds_read_b128 v[218:221], v173 offset:23552
	global_load_lds_dwordx4 v[202:203], off
	s_add_i32 m0, s41, 0x2000
	s_add_u32 s92, s70, 0x80000
	v_lshl_add_u64 v[222:223], s[70:71], 0, v[156:157]
	s_addc_u32 s93, s71, 0
	s_add_i32 s40, s40, s6
	global_load_lds_dwordx4 v[222:223], off
	s_nop 0
	s_mov_b32 m0, s40
	v_lshl_add_u64 v[226:227], s[72:73], 0, v[154:155]
	global_load_lds_dwordx4 v144, s[92:93]
	s_nop 0
	s_add_i32 m0, s40, 0x2000
	s_nop 0
	global_load_lds_dwordx4 v156, s[92:93]
	v_lshl_add_u64 v[224:225], s[72:73], 0, v[152:153]
	s_mov_b32 m0, s7
	s_nop 0
	global_load_lds_dwordx4 v[224:225], off
	s_mov_b32 m0, s8
	s_nop 0
	global_load_lds_dwordx4 v[226:227], off
	s_waitcnt vmcnt(8)
	s_waitcnt lgkmcnt(0)
	s_setprio 1
	s_barrier
	v_mfma_f32_16x16x32_bf16 v[60:63], v[128:131], v[186:189], v[60:63]
	v_mfma_f32_16x16x32_bf16 v[56:59], v[136:139], v[186:189], v[56:59]
	v_mfma_f32_16x16x32_bf16 v[44:47], v[128:131], v[194:197], v[44:47]
	v_mfma_f32_16x16x32_bf16 v[40:43], v[136:139], v[194:197], v[40:43]
	v_mfma_f32_16x16x32_bf16 v[24:27], v[128:131], v[206:209], v[24:27]
	v_mfma_f32_16x16x32_bf16 v[16:19], v[136:139], v[206:209], v[16:19]
	v_mfma_f32_16x16x32_bf16 v[4:7], v[128:131], v[214:217], v[4:7]
	v_mfma_f32_16x16x32_bf16 v[0:3], v[136:139], v[214:217], v[0:3]
	v_mfma_f32_16x16x32_bf16 v[60:63], v[132:135], v[190:193], v[60:63]
	v_mfma_f32_16x16x32_bf16 v[56:59], v[140:143], v[190:193], v[56:59]
	v_mfma_f32_16x16x32_bf16 v[44:47], v[132:135], v[198:201], v[44:47]
	v_mfma_f32_16x16x32_bf16 v[40:43], v[140:143], v[198:201], v[40:43]
	v_mfma_f32_16x16x32_bf16 v[24:27], v[132:135], v[210:213], v[24:27]
	v_mfma_f32_16x16x32_bf16 v[16:19], v[140:143], v[210:213], v[16:19]
	v_mfma_f32_16x16x32_bf16 v[4:7], v[132:135], v[218:221], v[4:7]
	v_mfma_f32_16x16x32_bf16 v[0:3], v[140:143], v[218:221], v[0:3]
	v_mfma_f32_16x16x32_bf16 v[52:55], v[160:163], v[186:189], v[52:55]
	v_mfma_f32_16x16x32_bf16 v[48:51], v[178:181], v[186:189], v[48:51]
	v_mfma_f32_16x16x32_bf16 v[28:31], v[160:163], v[194:197], v[28:31]
	v_mfma_f32_16x16x32_bf16 v[20:23], v[178:181], v[194:197], v[20:23]
	v_mfma_f32_16x16x32_bf16 v[32:35], v[160:163], v[206:209], v[32:35]
	v_mfma_f32_16x16x32_bf16 v[36:39], v[178:181], v[206:209], v[36:39]
	v_mfma_f32_16x16x32_bf16 v[8:11], v[160:163], v[214:217], v[8:11]
	v_mfma_f32_16x16x32_bf16 v[12:15], v[178:181], v[214:217], v[12:15]
	v_mfma_f32_16x16x32_bf16 v[52:55], v[174:177], v[190:193], v[52:55]
	v_mfma_f32_16x16x32_bf16 v[48:51], v[182:185], v[190:193], v[48:51]
	v_mfma_f32_16x16x32_bf16 v[28:31], v[174:177], v[198:201], v[28:31]
	v_mfma_f32_16x16x32_bf16 v[20:23], v[182:185], v[198:201], v[20:23]
	v_mfma_f32_16x16x32_bf16 v[32:35], v[174:177], v[210:213], v[32:35]
	v_mfma_f32_16x16x32_bf16 v[36:39], v[182:185], v[210:213], v[36:39]
	v_mfma_f32_16x16x32_bf16 v[8:11], v[174:177], v[218:221], v[8:11]
	v_mfma_f32_16x16x32_bf16 v[12:15], v[182:185], v[218:221], v[12:15]
	s_barrier
	s_setprio 0
	s_add_i32 s40, 0, 0x18000
	s_add_i32 s41, 0, 0x1c000
	v_add_u32_e32 v140, s40, v169
	v_add_u32_e32 v182, s41, v169
	ds_read_b128 v[128:131], v140
	ds_read_b128 v[132:135], v140 offset:1024
	ds_read_b128 v[136:139], v140 offset:2048
	ds_read_b128 v[140:143], v140 offset:3072
	ds_read_b128 v[160:163], v182
	ds_read_b128 v[174:177], v182 offset:1024
	ds_read_b128 v[178:181], v182 offset:2048
	ds_read_b128 v[182:185], v182 offset:3072
	s_add_u32 s72, s72, 0x80000
	s_addc_u32 s73, s73, 0
	s_mov_b32 m0, s9
	s_nop 0
	ds_read_b128 v[186:189], v173 offset:32768
	ds_read_b128 v[190:193], v173 offset:33792
	ds_read_b128 v[194:197], v173 offset:34816
	ds_read_b128 v[198:201], v173 offset:35840
	ds_read_b128 v[206:209], v173 offset:36864
	ds_read_b128 v[210:213], v173 offset:37888
	ds_read_b128 v[214:217], v173 offset:38912
	ds_read_b128 v[218:221], v173 offset:39936
	global_load_lds_dwordx4 v152, s[72:73]
	s_nop 0
	s_mov_b32 m0, s10
	s_nop 0
	global_load_lds_dwordx4 v154, s[72:73]
	s_waitcnt vmcnt(8)
	s_waitcnt lgkmcnt(0)
	s_setprio 1
	s_barrier
	v_mfma_f32_16x16x32_bf16 v[124:127], v[128:131], v[186:189], v[124:127]
	v_mfma_f32_16x16x32_bf16 v[120:123], v[136:139], v[186:189], v[120:123]
	v_mfma_f32_16x16x32_bf16 v[108:111], v[128:131], v[194:197], v[108:111]
	v_mfma_f32_16x16x32_bf16 v[104:107], v[136:139], v[194:197], v[104:107]
	v_mfma_f32_16x16x32_bf16 v[92:95], v[128:131], v[206:209], v[92:95]
	v_mfma_f32_16x16x32_bf16 v[88:91], v[136:139], v[206:209], v[88:91]
	v_mfma_f32_16x16x32_bf16 v[76:79], v[128:131], v[214:217], v[76:79]
	v_mfma_f32_16x16x32_bf16 v[72:75], v[136:139], v[214:217], v[72:75]
	v_mfma_f32_16x16x32_bf16 v[124:127], v[132:135], v[190:193], v[124:127]
	v_mfma_f32_16x16x32_bf16 v[120:123], v[140:143], v[190:193], v[120:123]
	v_mfma_f32_16x16x32_bf16 v[108:111], v[132:135], v[198:201], v[108:111]
	v_mfma_f32_16x16x32_bf16 v[104:107], v[140:143], v[198:201], v[104:107]
	v_mfma_f32_16x16x32_bf16 v[92:95], v[132:135], v[210:213], v[92:95]
	v_mfma_f32_16x16x32_bf16 v[88:91], v[140:143], v[210:213], v[88:91]
	v_mfma_f32_16x16x32_bf16 v[76:79], v[132:135], v[218:221], v[76:79]
	v_mfma_f32_16x16x32_bf16 v[72:75], v[140:143], v[218:221], v[72:75]
	v_mfma_f32_16x16x32_bf16 v[116:119], v[160:163], v[186:189], v[116:119]
	v_mfma_f32_16x16x32_bf16 v[112:115], v[178:181], v[186:189], v[112:115]
	v_mfma_f32_16x16x32_bf16 v[100:103], v[160:163], v[194:197], v[100:103]
	v_mfma_f32_16x16x32_bf16 v[96:99], v[178:181], v[194:197], v[96:99]
	v_mfma_f32_16x16x32_bf16 v[84:87], v[160:163], v[206:209], v[84:87]
	v_mfma_f32_16x16x32_bf16 v[80:83], v[178:181], v[206:209], v[80:83]
	v_mfma_f32_16x16x32_bf16 v[68:71], v[160:163], v[214:217], v[68:71]
	v_mfma_f32_16x16x32_bf16 v[64:67], v[178:181], v[214:217], v[64:67]
	v_mfma_f32_16x16x32_bf16 v[116:119], v[174:177], v[190:193], v[116:119]
	v_mfma_f32_16x16x32_bf16 v[112:115], v[182:185], v[190:193], v[112:115]
	v_mfma_f32_16x16x32_bf16 v[100:103], v[174:177], v[198:201], v[100:103]
	v_mfma_f32_16x16x32_bf16 v[96:99], v[182:185], v[198:201], v[96:99]
	v_mfma_f32_16x16x32_bf16 v[84:87], v[174:177], v[210:213], v[84:87]
	v_mfma_f32_16x16x32_bf16 v[80:83], v[182:185], v[210:213], v[80:83]
	v_mfma_f32_16x16x32_bf16 v[68:71], v[174:177], v[218:221], v[68:71]
	v_mfma_f32_16x16x32_bf16 v[64:67], v[182:185], v[218:221], v[64:67]
	s_barrier
	s_setprio 0
	s_add_i32 s40, s40, s6
	s_nop 0
	s_add_i32 m0, s40, 0xffffff80
	ds_read_b128 v[186:189], v173 offset:49152
	ds_read_b128 v[190:193], v173 offset:50176
	ds_read_b128 v[194:197], v173 offset:51200
	ds_read_b128 v[198:201], v173 offset:52224
	ds_read_b128 v[206:209], v173 offset:53248
	ds_read_b128 v[210:213], v173 offset:54272
	ds_read_b128 v[214:217], v173 offset:55296
	ds_read_b128 v[218:221], v173 offset:56320
	global_load_lds_dwordx4 v[202:203], off offset:128
	s_add_i32 m0, s40, 0x1f80
	s_add_u32 s70, s70, 0x80080
	s_nop 0
	s_addc_u32 s71, s71, 0
	s_add_i32 s40, s41, s6
	global_load_lds_dwordx4 v[222:223], off offset:128
	s_nop 0
	s_mov_b32 m0, s40
	s_nop 0
	global_load_lds_dwordx4 v144, s[70:71]
	s_nop 0
	s_add_i32 m0, s40, 0x2000
	s_nop 0
	global_load_lds_dwordx4 v156, s[70:71]
	s_nop 0
	s_add_i32 m0, s11, 0xffffff80
	s_nop 0
	global_load_lds_dwordx4 v[224:225], off offset:128
	s_nop 0
	s_add_i32 m0, s12, 0xffffff80
	s_nop 0
	global_load_lds_dwordx4 v[226:227], off offset:128
	s_waitcnt vmcnt(8)
	s_waitcnt lgkmcnt(0)
	s_setprio 1
	s_barrier
	v_mfma_f32_16x16x32_bf16 v[60:63], v[128:131], v[186:189], v[60:63]
	v_mfma_f32_16x16x32_bf16 v[56:59], v[136:139], v[186:189], v[56:59]
	v_mfma_f32_16x16x32_bf16 v[44:47], v[128:131], v[194:197], v[44:47]
	v_mfma_f32_16x16x32_bf16 v[40:43], v[136:139], v[194:197], v[40:43]
	v_mfma_f32_16x16x32_bf16 v[24:27], v[128:131], v[206:209], v[24:27]
	v_mfma_f32_16x16x32_bf16 v[16:19], v[136:139], v[206:209], v[16:19]
	v_mfma_f32_16x16x32_bf16 v[4:7], v[128:131], v[214:217], v[4:7]
	v_mfma_f32_16x16x32_bf16 v[0:3], v[136:139], v[214:217], v[0:3]
	v_mfma_f32_16x16x32_bf16 v[60:63], v[132:135], v[190:193], v[60:63]
	v_mfma_f32_16x16x32_bf16 v[56:59], v[140:143], v[190:193], v[56:59]
	v_mfma_f32_16x16x32_bf16 v[44:47], v[132:135], v[198:201], v[44:47]
	v_mfma_f32_16x16x32_bf16 v[40:43], v[140:143], v[198:201], v[40:43]
	v_mfma_f32_16x16x32_bf16 v[24:27], v[132:135], v[210:213], v[24:27]
	v_mfma_f32_16x16x32_bf16 v[16:19], v[140:143], v[210:213], v[16:19]
	v_mfma_f32_16x16x32_bf16 v[4:7], v[132:135], v[218:221], v[4:7]
	v_mfma_f32_16x16x32_bf16 v[0:3], v[140:143], v[218:221], v[0:3]
	v_mfma_f32_16x16x32_bf16 v[52:55], v[160:163], v[186:189], v[52:55]
	v_mfma_f32_16x16x32_bf16 v[48:51], v[178:181], v[186:189], v[48:51]
	v_mfma_f32_16x16x32_bf16 v[28:31], v[160:163], v[194:197], v[28:31]
	v_mfma_f32_16x16x32_bf16 v[20:23], v[178:181], v[194:197], v[20:23]
	v_mfma_f32_16x16x32_bf16 v[32:35], v[160:163], v[206:209], v[32:35]
	v_mfma_f32_16x16x32_bf16 v[36:39], v[178:181], v[206:209], v[36:39]
	v_mfma_f32_16x16x32_bf16 v[8:11], v[160:163], v[214:217], v[8:11]
	v_mfma_f32_16x16x32_bf16 v[12:15], v[178:181], v[214:217], v[12:15]
	v_mfma_f32_16x16x32_bf16 v[52:55], v[174:177], v[190:193], v[52:55]
	v_mfma_f32_16x16x32_bf16 v[48:51], v[182:185], v[190:193], v[48:51]
	v_mfma_f32_16x16x32_bf16 v[28:31], v[174:177], v[198:201], v[28:31]
	v_mfma_f32_16x16x32_bf16 v[20:23], v[182:185], v[198:201], v[20:23]
	v_mfma_f32_16x16x32_bf16 v[32:35], v[174:177], v[210:213], v[32:35]
	v_mfma_f32_16x16x32_bf16 v[36:39], v[182:185], v[210:213], v[36:39]
	v_mfma_f32_16x16x32_bf16 v[8:11], v[174:177], v[218:221], v[8:11]
	v_mfma_f32_16x16x32_bf16 v[12:15], v[182:185], v[218:221], v[12:15]
	s_barrier
	s_setprio 0
	s_cmp_gt_u32 s31, 29
	s_cbranch_scc1 .LBB0_1780
	s_mov_b32 s31, s42
	s_branch .LBB0_1766

.LBB0_1933:
	s_add_i32 s77, s26, 2
	s_add_u32 s92, s22, 0x80
	s_addc_u32 s27, s23, 0
	s_add_i32 s40, 0, 0x10000
	s_cmp_eq_u32 s73, s26
	s_cselect_b32 s27, s36, s27
	s_cselect_b32 s26, s37, s92
	s_cselect_b32 s93, s42, vcc_hi
	s_cselect_b32 s92, s61, vcc_lo
	s_add_i32 s41, 0, 0x14000
	v_add_u32_e32 v158, s40, v168
	v_add_u32_e32 v162, s41, v168
	ds_read_b128 v[128:131], v158
	ds_read_b128 v[132:135], v158 offset:1024
	ds_read_b128 v[154:157], v158 offset:2048
	ds_read_b128 v[158:161], v158 offset:3072
	ds_read_b128 v[172:175], v162
	ds_read_b128 v[176:179], v162 offset:1024
	ds_read_b128 v[180:183], v162 offset:2048
	ds_read_b128 v[184:187], v162 offset:3072
	s_nop 0
	s_add_i32 m0, s12, 0xc000
	ds_read_b128 v[188:191], v171
	ds_read_b128 v[192:195], v171 offset:1024
	ds_read_b128 v[196:199], v171 offset:2048
	ds_read_b128 v[200:203], v171 offset:3072
	ds_read_b128 v[206:209], v171 offset:4096
	ds_read_b128 v[210:213], v171 offset:5120
	ds_read_b128 v[214:217], v171 offset:6144
	ds_read_b128 v[218:221], v171 offset:7168
	global_load_lds_dwordx4 v152, s[22:23]
	s_nop 0
	s_add_i32 m0, s12, 0xe000
	s_nop 0
	global_load_lds_dwordx4 v142, s[22:23]
	s_waitcnt vmcnt(8)
	s_waitcnt lgkmcnt(0)
	s_setprio 1
	s_barrier
	v_mfma_f32_16x16x32_bf16 v[124:127], v[128:131], v[188:191], v[124:127]
	v_mfma_f32_16x16x32_bf16 v[120:123], v[154:157], v[188:191], v[120:123]
	v_mfma_f32_16x16x32_bf16 v[108:111], v[128:131], v[196:199], v[108:111]
	v_mfma_f32_16x16x32_bf16 v[104:107], v[154:157], v[196:199], v[104:107]
	v_mfma_f32_16x16x32_bf16 v[92:95], v[128:131], v[206:209], v[92:95]
	v_mfma_f32_16x16x32_bf16 v[88:91], v[154:157], v[206:209], v[88:91]
	v_mfma_f32_16x16x32_bf16 v[76:79], v[128:131], v[214:217], v[76:79]
	v_mfma_f32_16x16x32_bf16 v[72:75], v[154:157], v[214:217], v[72:75]
	v_mfma_f32_16x16x32_bf16 v[124:127], v[132:135], v[192:195], v[124:127]
	v_mfma_f32_16x16x32_bf16 v[120:123], v[158:161], v[192:195], v[120:123]
	v_mfma_f32_16x16x32_bf16 v[108:111], v[132:135], v[200:203], v[108:111]
	v_mfma_f32_16x16x32_bf16 v[104:107], v[158:161], v[200:203], v[104:107]
	v_mfma_f32_16x16x32_bf16 v[92:95], v[132:135], v[210:213], v[92:95]
	v_mfma_f32_16x16x32_bf16 v[88:91], v[158:161], v[210:213], v[88:91]
	v_mfma_f32_16x16x32_bf16 v[76:79], v[132:135], v[218:221], v[76:79]
	v_mfma_f32_16x16x32_bf16 v[72:75], v[158:161], v[218:221], v[72:75]
	v_mfma_f32_16x16x32_bf16 v[116:119], v[172:175], v[188:191], v[116:119]
	v_mfma_f32_16x16x32_bf16 v[112:115], v[180:183], v[188:191], v[112:115]
	v_mfma_f32_16x16x32_bf16 v[100:103], v[172:175], v[196:199], v[100:103]
	v_mfma_f32_16x16x32_bf16 v[96:99], v[180:183], v[196:199], v[96:99]
	v_mfma_f32_16x16x32_bf16 v[84:87], v[172:175], v[206:209], v[84:87]
	v_mfma_f32_16x16x32_bf16 v[80:83], v[180:183], v[206:209], v[80:83]
	v_mfma_f32_16x16x32_bf16 v[68:71], v[172:175], v[214:217], v[68:71]
	v_mfma_f32_16x16x32_bf16 v[64:67], v[180:183], v[214:217], v[64:67]
	v_mfma_f32_16x16x32_bf16 v[116:119], v[176:179], v[192:195], v[116:119]
	v_mfma_f32_16x16x32_bf16 v[112:115], v[184:187], v[192:195], v[112:115]
	v_mfma_f32_16x16x32_bf16 v[100:103], v[176:179], v[200:203], v[100:103]
	v_mfma_f32_16x16x32_bf16 v[96:99], v[184:187], v[200:203], v[96:99]
	v_mfma_f32_16x16x32_bf16 v[84:87], v[176:179], v[210:213], v[84:87]
	v_mfma_f32_16x16x32_bf16 v[80:83], v[184:187], v[210:213], v[80:83]
	v_mfma_f32_16x16x32_bf16 v[68:71], v[176:179], v[218:221], v[68:71]
	v_mfma_f32_16x16x32_bf16 v[64:67], v[184:187], v[218:221], v[64:67]
	s_barrier
	s_setprio 0
	s_add_i32 s40, s40, s11
	v_lshl_add_u64 v[162:163], s[92:93], 0, v[144:145]
	s_mov_b32 m0, s40
	ds_read_b128 v[188:191], v171 offset:16384
	ds_read_b128 v[192:195], v171 offset:17408
	ds_read_b128 v[196:199], v171 offset:18432
	ds_read_b128 v[200:203], v171 offset:19456
	ds_read_b128 v[206:209], v171 offset:20480
	ds_read_b128 v[210:213], v171 offset:21504
	ds_read_b128 v[214:217], v171 offset:22528
	ds_read_b128 v[218:221], v171 offset:23552
	global_load_lds_dwordx4 v[162:163], off
	s_add_i32 m0, s40, 0x2000
	v_lshl_add_u64 v[222:223], s[92:93], 0, v[140:141]
	s_add_u32 s92, s92, s48
	s_addc_u32 s93, s93, 0
	s_add_i32 s40, s41, s11
	global_load_lds_dwordx4 v[222:223], off
	v_lshl_add_u64 v[224:225], s[92:93], 0, v[144:145]
	s_mov_b32 m0, s40
	v_lshl_add_u64 v[226:227], s[92:93], 0, v[140:141]
	global_load_lds_dwordx4 v[224:225], off
	s_add_i32 m0, s40, 0x2000
	v_lshl_add_u64 v[228:229], s[26:27], 0, v[136:137]
	global_load_lds_dwordx4 v[226:227], off
	s_mov_b32 m0, s12
	v_lshl_add_u64 v[230:231], s[26:27], 0, v[138:139]
	global_load_lds_dwordx4 v[228:229], off
	s_mov_b32 m0, s13
	s_nop 0
	global_load_lds_dwordx4 v[230:231], off
	s_waitcnt vmcnt(8)
	s_waitcnt lgkmcnt(0)
	s_setprio 1
	s_barrier
	v_mfma_f32_16x16x32_bf16 v[60:63], v[128:131], v[188:191], v[60:63]
	v_mfma_f32_16x16x32_bf16 v[56:59], v[154:157], v[188:191], v[56:59]
	v_mfma_f32_16x16x32_bf16 v[44:47], v[128:131], v[196:199], v[44:47]
	v_mfma_f32_16x16x32_bf16 v[40:43], v[154:157], v[196:199], v[40:43]
	v_mfma_f32_16x16x32_bf16 v[28:31], v[128:131], v[206:209], v[28:31]
	v_mfma_f32_16x16x32_bf16 v[24:27], v[154:157], v[206:209], v[24:27]
	v_mfma_f32_16x16x32_bf16 v[12:15], v[128:131], v[214:217], v[12:15]
	v_mfma_f32_16x16x32_bf16 v[8:11], v[154:157], v[214:217], v[8:11]
	v_mfma_f32_16x16x32_bf16 v[60:63], v[132:135], v[192:195], v[60:63]
	v_mfma_f32_16x16x32_bf16 v[56:59], v[158:161], v[192:195], v[56:59]
	v_mfma_f32_16x16x32_bf16 v[44:47], v[132:135], v[200:203], v[44:47]
	v_mfma_f32_16x16x32_bf16 v[40:43], v[158:161], v[200:203], v[40:43]
	v_mfma_f32_16x16x32_bf16 v[28:31], v[132:135], v[210:213], v[28:31]
	v_mfma_f32_16x16x32_bf16 v[24:27], v[158:161], v[210:213], v[24:27]
	v_mfma_f32_16x16x32_bf16 v[12:15], v[132:135], v[218:221], v[12:15]
	v_mfma_f32_16x16x32_bf16 v[8:11], v[158:161], v[218:221], v[8:11]
	v_mfma_f32_16x16x32_bf16 v[52:55], v[172:175], v[188:191], v[52:55]
	v_mfma_f32_16x16x32_bf16 v[48:51], v[180:183], v[188:191], v[48:51]
	v_mfma_f32_16x16x32_bf16 v[36:39], v[172:175], v[196:199], v[36:39]
	v_mfma_f32_16x16x32_bf16 v[32:35], v[180:183], v[196:199], v[32:35]
	v_mfma_f32_16x16x32_bf16 v[20:23], v[172:175], v[206:209], v[20:23]
	v_mfma_f32_16x16x32_bf16 v[16:19], v[180:183], v[206:209], v[16:19]
	v_mfma_f32_16x16x32_bf16 v[4:7], v[172:175], v[214:217], v[4:7]
	v_mfma_f32_16x16x32_bf16 v[0:3], v[180:183], v[214:217], v[0:3]
	v_mfma_f32_16x16x32_bf16 v[52:55], v[176:179], v[192:195], v[52:55]
	v_mfma_f32_16x16x32_bf16 v[48:51], v[184:187], v[192:195], v[48:51]
	v_mfma_f32_16x16x32_bf16 v[36:39], v[176:179], v[200:203], v[36:39]
	v_mfma_f32_16x16x32_bf16 v[32:35], v[184:187], v[200:203], v[32:35]
	v_mfma_f32_16x16x32_bf16 v[20:23], v[176:179], v[210:213], v[20:23]
	v_mfma_f32_16x16x32_bf16 v[16:19], v[184:187], v[210:213], v[16:19]
	v_mfma_f32_16x16x32_bf16 v[4:7], v[176:179], v[218:221], v[4:7]
	v_mfma_f32_16x16x32_bf16 v[0:3], v[184:187], v[218:221], v[0:3]
	s_barrier
	s_setprio 0
	s_add_i32 s40, 0, 0x18000
	s_add_i32 s41, 0, 0x1c000
	v_add_u32_e32 v158, s40, v168
	v_add_u32_e32 v184, s41, v168
	ds_read_b128 v[128:131], v158
	ds_read_b128 v[132:135], v158 offset:1024
	ds_read_b128 v[154:157], v158 offset:2048
	ds_read_b128 v[158:161], v158 offset:3072
	ds_read_b128 v[172:175], v184
	ds_read_b128 v[176:179], v184 offset:1024
	ds_read_b128 v[180:183], v184 offset:2048
	ds_read_b128 v[184:187], v184 offset:3072
	s_add_u32 s26, s26, s48
	s_addc_u32 s27, s27, 0
	s_mov_b32 m0, s28
	s_nop 0
	ds_read_b128 v[188:191], v171 offset:32768
	ds_read_b128 v[192:195], v171 offset:33792
	ds_read_b128 v[196:199], v171 offset:34816
	ds_read_b128 v[200:203], v171 offset:35840
	ds_read_b128 v[206:209], v171 offset:36864
	ds_read_b128 v[210:213], v171 offset:37888
	ds_read_b128 v[214:217], v171 offset:38912
	ds_read_b128 v[218:221], v171 offset:39936
	global_load_lds_dwordx4 v136, s[26:27]
	s_nop 0
	s_mov_b32 m0, s29
	s_nop 0
	global_load_lds_dwordx4 v138, s[26:27]
	s_waitcnt vmcnt(8)
	s_waitcnt lgkmcnt(0)
	s_setprio 1
	s_barrier
	v_mfma_f32_16x16x32_bf16 v[124:127], v[128:131], v[188:191], v[124:127]
	v_mfma_f32_16x16x32_bf16 v[120:123], v[154:157], v[188:191], v[120:123]
	v_mfma_f32_16x16x32_bf16 v[108:111], v[128:131], v[196:199], v[108:111]
	v_mfma_f32_16x16x32_bf16 v[104:107], v[154:157], v[196:199], v[104:107]
	v_mfma_f32_16x16x32_bf16 v[92:95], v[128:131], v[206:209], v[92:95]
	v_mfma_f32_16x16x32_bf16 v[88:91], v[154:157], v[206:209], v[88:91]
	v_mfma_f32_16x16x32_bf16 v[76:79], v[128:131], v[214:217], v[76:79]
	v_mfma_f32_16x16x32_bf16 v[72:75], v[154:157], v[214:217], v[72:75]
	v_mfma_f32_16x16x32_bf16 v[124:127], v[132:135], v[192:195], v[124:127]
	v_mfma_f32_16x16x32_bf16 v[120:123], v[158:161], v[192:195], v[120:123]
	v_mfma_f32_16x16x32_bf16 v[108:111], v[132:135], v[200:203], v[108:111]
	v_mfma_f32_16x16x32_bf16 v[104:107], v[158:161], v[200:203], v[104:107]
	v_mfma_f32_16x16x32_bf16 v[92:95], v[132:135], v[210:213], v[92:95]
	v_mfma_f32_16x16x32_bf16 v[88:91], v[158:161], v[210:213], v[88:91]
	v_mfma_f32_16x16x32_bf16 v[76:79], v[132:135], v[218:221], v[76:79]
	v_mfma_f32_16x16x32_bf16 v[72:75], v[158:161], v[218:221], v[72:75]
	v_mfma_f32_16x16x32_bf16 v[116:119], v[172:175], v[188:191], v[116:119]
	v_mfma_f32_16x16x32_bf16 v[112:115], v[180:183], v[188:191], v[112:115]
	v_mfma_f32_16x16x32_bf16 v[100:103], v[172:175], v[196:199], v[100:103]
	v_mfma_f32_16x16x32_bf16 v[96:99], v[180:183], v[196:199], v[96:99]
	v_mfma_f32_16x16x32_bf16 v[84:87], v[172:175], v[206:209], v[84:87]
	v_mfma_f32_16x16x32_bf16 v[80:83], v[180:183], v[206:209], v[80:83]
	v_mfma_f32_16x16x32_bf16 v[68:71], v[172:175], v[214:217], v[68:71]
	v_mfma_f32_16x16x32_bf16 v[64:67], v[180:183], v[214:217], v[64:67]
	v_mfma_f32_16x16x32_bf16 v[116:119], v[176:179], v[192:195], v[116:119]
	v_mfma_f32_16x16x32_bf16 v[112:115], v[184:187], v[192:195], v[112:115]
	v_mfma_f32_16x16x32_bf16 v[100:103], v[176:179], v[200:203], v[100:103]
	v_mfma_f32_16x16x32_bf16 v[96:99], v[184:187], v[200:203], v[96:99]
	v_mfma_f32_16x16x32_bf16 v[84:87], v[176:179], v[210:213], v[84:87]
	v_mfma_f32_16x16x32_bf16 v[80:83], v[184:187], v[210:213], v[80:83]
	v_mfma_f32_16x16x32_bf16 v[68:71], v[176:179], v[218:221], v[68:71]
	v_mfma_f32_16x16x32_bf16 v[64:67], v[184:187], v[218:221], v[64:67]
	s_barrier
	s_setprio 0
	s_add_i32 s26, s40, s11
	s_nop 0
	s_add_i32 m0, s26, 0xffffff80
	ds_read_b128 v[188:191], v171 offset:49152
	ds_read_b128 v[192:195], v171 offset:50176
	ds_read_b128 v[196:199], v171 offset:51200
	ds_read_b128 v[200:203], v171 offset:52224
	ds_read_b128 v[206:209], v171 offset:53248
	ds_read_b128 v[210:213], v171 offset:54272
	ds_read_b128 v[214:217], v171 offset:55296
	ds_read_b128 v[218:221], v171 offset:56320
	global_load_lds_dwordx4 v[162:163], off offset:128
	s_nop 0
	s_add_i32 m0, s26, 0x1f80
	s_add_i32 s26, s41, s11
	global_load_lds_dwordx4 v[222:223], off offset:128
	s_nop 0
	s_add_i32 m0, s26, 0xffffff80
	s_nop 0
	global_load_lds_dwordx4 v[224:225], off offset:128
	s_nop 0
	s_add_i32 m0, s26, 0x1f80
	s_nop 0
	global_load_lds_dwordx4 v[226:227], off offset:128
	s_nop 0
	s_add_i32 m0, s68, 0xffffff80
	s_nop 0
	global_load_lds_dwordx4 v[228:229], off offset:128
	s_nop 0
	s_add_i32 m0, s69, 0xffffff80
	s_nop 0
	global_load_lds_dwordx4 v[230:231], off offset:128
	s_waitcnt vmcnt(8)
	s_waitcnt lgkmcnt(0)
	s_setprio 1
	s_barrier
	v_mfma_f32_16x16x32_bf16 v[60:63], v[128:131], v[188:191], v[60:63]
	v_mfma_f32_16x16x32_bf16 v[56:59], v[154:157], v[188:191], v[56:59]
	v_mfma_f32_16x16x32_bf16 v[44:47], v[128:131], v[196:199], v[44:47]
	v_mfma_f32_16x16x32_bf16 v[40:43], v[154:157], v[196:199], v[40:43]
	v_mfma_f32_16x16x32_bf16 v[28:31], v[128:131], v[206:209], v[28:31]
	v_mfma_f32_16x16x32_bf16 v[24:27], v[154:157], v[206:209], v[24:27]
	v_mfma_f32_16x16x32_bf16 v[12:15], v[128:131], v[214:217], v[12:15]
	v_mfma_f32_16x16x32_bf16 v[8:11], v[154:157], v[214:217], v[8:11]
	v_mfma_f32_16x16x32_bf16 v[60:63], v[132:135], v[192:195], v[60:63]
	v_mfma_f32_16x16x32_bf16 v[56:59], v[158:161], v[192:195], v[56:59]
	v_mfma_f32_16x16x32_bf16 v[44:47], v[132:135], v[200:203], v[44:47]
	v_mfma_f32_16x16x32_bf16 v[40:43], v[158:161], v[200:203], v[40:43]
	v_mfma_f32_16x16x32_bf16 v[28:31], v[132:135], v[210:213], v[28:31]
	v_mfma_f32_16x16x32_bf16 v[24:27], v[158:161], v[210:213], v[24:27]
	v_mfma_f32_16x16x32_bf16 v[12:15], v[132:135], v[218:221], v[12:15]
	v_mfma_f32_16x16x32_bf16 v[8:11], v[158:161], v[218:221], v[8:11]
	v_mfma_f32_16x16x32_bf16 v[52:55], v[172:175], v[188:191], v[52:55]
	v_mfma_f32_16x16x32_bf16 v[48:51], v[180:183], v[188:191], v[48:51]
	v_mfma_f32_16x16x32_bf16 v[36:39], v[172:175], v[196:199], v[36:39]
	v_mfma_f32_16x16x32_bf16 v[32:35], v[180:183], v[196:199], v[32:35]
	v_mfma_f32_16x16x32_bf16 v[20:23], v[172:175], v[206:209], v[20:23]
	v_mfma_f32_16x16x32_bf16 v[16:19], v[180:183], v[206:209], v[16:19]
	v_mfma_f32_16x16x32_bf16 v[4:7], v[172:175], v[214:217], v[4:7]
	v_mfma_f32_16x16x32_bf16 v[0:3], v[180:183], v[214:217], v[0:3]
	v_mfma_f32_16x16x32_bf16 v[52:55], v[176:179], v[192:195], v[52:55]
	v_mfma_f32_16x16x32_bf16 v[48:51], v[184:187], v[192:195], v[48:51]
	v_mfma_f32_16x16x32_bf16 v[36:39], v[176:179], v[200:203], v[36:39]
	v_mfma_f32_16x16x32_bf16 v[32:35], v[184:187], v[200:203], v[32:35]
	v_mfma_f32_16x16x32_bf16 v[20:23], v[176:179], v[210:213], v[20:23]
	v_mfma_f32_16x16x32_bf16 v[16:19], v[184:187], v[210:213], v[16:19]
	v_mfma_f32_16x16x32_bf16 v[4:7], v[176:179], v[218:221], v[4:7]
	v_mfma_f32_16x16x32_bf16 v[0:3], v[184:187], v[218:221], v[0:3]
	s_barrier
	s_setprio 0
	s_add_u32 vcc_lo, vcc_lo, 0x100
	s_addc_u32 vcc_hi, vcc_hi, 0
	s_add_u32 s22, s22, 0x100
	s_addc_u32 s23, s23, 0
	s_cmp_ge_i32 s77, s1
	s_mov_b32 s26, s77
	s_cbranch_scc0 .LBB0_1933
	s_and_b64 vcc, exec, s[52:53]
	s_cbranch_vccz .LBB0_1936

.LBB0_2145:
	s_or_b32 s50, s23, 1
	s_lshl_b64 s[88:89], s[50:51], 7
	s_add_i32 s50, s23, 2
	s_lshl_b64 s[90:91], s[50:51], 7
	v_add_u32_e32 v116, s74, v197
	v_add_u32_e32 v174, s75, v197
	s_add_u32 s43, s26, s90
	ds_read_b128 v[104:107], v116
	ds_read_b128 v[108:111], v116 offset:1024
	ds_read_b128 v[112:115], v116 offset:2048
	ds_read_b128 v[116:119], v116 offset:3072
	ds_read_b128 v[144:147], v174
	ds_read_b128 v[166:169], v174 offset:1024
	ds_read_b128 v[170:173], v174 offset:2048
	ds_read_b128 v[174:177], v174 offset:3072
	s_addc_u32 s87, s27, s91
	s_and_b64 s[72:73], s[70:71], exec
	s_cselect_b32 s73, s87, s63
	s_cselect_b32 s72, s43, s62
	s_add_u32 s43, s40, s90
	s_addc_u32 s87, s41, s91
	s_and_b64 s[70:71], s[70:71], exec
	s_cselect_b32 s71, s87, s65
	s_cselect_b32 s70, s43, s64
	s_add_u32 s43, s26, s88
	s_addc_u32 s87, s27, s89
	s_add_u32 s88, s43, 0x80000
	s_addc_u32 s89, s87, 0
	s_nop 0
	s_add_i32 m0, s7, 0xc000
	ds_read_b128 v[178:181], v156
	ds_read_b128 v[182:185], v156 offset:1024
	ds_read_b128 v[186:189], v156 offset:2048
	ds_read_b128 v[190:193], v156 offset:3072
	ds_read_b128 v[200:203], v156 offset:4096
	ds_read_b128 v[206:209], v156 offset:5120
	ds_read_b128 v[210:213], v156 offset:6144
	ds_read_b128 v[214:217], v156 offset:7168
	global_load_lds_dwordx4 v148, s[88:89]
	s_nop 0
	s_add_i32 m0, s7, 0xe000
	s_nop 0
	global_load_lds_dwordx4 v152, s[88:89]
	s_waitcnt vmcnt(8)
	s_waitcnt lgkmcnt(0)
	s_setprio 1
	s_barrier
	v_mfma_f32_16x16x32_bf16 v[140:143], v[104:107], v[178:181], v[140:143]
	v_mfma_f32_16x16x32_bf16 v[136:139], v[112:115], v[178:181], v[136:139]
	v_mfma_f32_16x16x32_bf16 v[124:127], v[104:107], v[186:189], v[124:127]
	v_mfma_f32_16x16x32_bf16 v[120:123], v[112:115], v[186:189], v[120:123]
	v_mfma_f32_16x16x32_bf16 v[92:95], v[104:107], v[200:203], v[92:95]
	v_mfma_f32_16x16x32_bf16 v[88:91], v[112:115], v[200:203], v[88:91]
	v_mfma_f32_16x16x32_bf16 v[76:79], v[104:107], v[210:213], v[76:79]
	v_mfma_f32_16x16x32_bf16 v[72:75], v[112:115], v[210:213], v[72:75]
	v_mfma_f32_16x16x32_bf16 v[140:143], v[108:111], v[182:185], v[140:143]
	v_mfma_f32_16x16x32_bf16 v[136:139], v[116:119], v[182:185], v[136:139]
	v_mfma_f32_16x16x32_bf16 v[124:127], v[108:111], v[190:193], v[124:127]
	v_mfma_f32_16x16x32_bf16 v[120:123], v[116:119], v[190:193], v[120:123]
	v_mfma_f32_16x16x32_bf16 v[92:95], v[108:111], v[206:209], v[92:95]
	v_mfma_f32_16x16x32_bf16 v[88:91], v[116:119], v[206:209], v[88:91]
	v_mfma_f32_16x16x32_bf16 v[76:79], v[108:111], v[214:217], v[76:79]
	v_mfma_f32_16x16x32_bf16 v[72:75], v[116:119], v[214:217], v[72:75]
	v_mfma_f32_16x16x32_bf16 v[132:135], v[144:147], v[178:181], v[132:135]
	v_mfma_f32_16x16x32_bf16 v[128:131], v[170:173], v[178:181], v[128:131]
	v_mfma_f32_16x16x32_bf16 v[100:103], v[144:147], v[186:189], v[100:103]
	v_mfma_f32_16x16x32_bf16 v[96:99], v[170:173], v[186:189], v[96:99]
	v_mfma_f32_16x16x32_bf16 v[84:87], v[144:147], v[200:203], v[84:87]
	v_mfma_f32_16x16x32_bf16 v[80:83], v[170:173], v[200:203], v[80:83]
	v_mfma_f32_16x16x32_bf16 v[68:71], v[144:147], v[210:213], v[68:71]
	v_mfma_f32_16x16x32_bf16 v[64:67], v[170:173], v[210:213], v[64:67]
	v_mfma_f32_16x16x32_bf16 v[132:135], v[166:169], v[182:185], v[132:135]
	v_mfma_f32_16x16x32_bf16 v[128:131], v[174:177], v[182:185], v[128:131]
	v_mfma_f32_16x16x32_bf16 v[100:103], v[166:169], v[190:193], v[100:103]
	v_mfma_f32_16x16x32_bf16 v[96:99], v[174:177], v[190:193], v[96:99]
	v_mfma_f32_16x16x32_bf16 v[84:87], v[166:169], v[206:209], v[84:87]
	v_mfma_f32_16x16x32_bf16 v[80:83], v[174:177], v[206:209], v[80:83]
	v_mfma_f32_16x16x32_bf16 v[68:71], v[166:169], v[214:217], v[68:71]
	v_mfma_f32_16x16x32_bf16 v[64:67], v[174:177], v[214:217], v[64:67]
	s_barrier
	s_setprio 0
	s_add_i32 s43, s74, s6
	v_lshl_add_u64 v[218:219], s[70:71], 0, v[150:151]
	s_mov_b32 m0, s43
	ds_read_b128 v[178:181], v156 offset:16384
	ds_read_b128 v[182:185], v156 offset:17408
	ds_read_b128 v[186:189], v156 offset:18432
	ds_read_b128 v[190:193], v156 offset:19456
	ds_read_b128 v[200:203], v156 offset:20480
	ds_read_b128 v[206:209], v156 offset:21504
	ds_read_b128 v[210:213], v156 offset:22528
	ds_read_b128 v[214:217], v156 offset:23552
	global_load_lds_dwordx4 v[218:219], off
	s_add_i32 m0, s43, 0x2000
	s_add_u32 s88, s70, 0x80000
	v_lshl_add_u64 v[220:221], s[70:71], 0, v[154:155]
	s_addc_u32 s89, s71, 0
	s_add_i32 s43, s75, s6
	global_load_lds_dwordx4 v[220:221], off
	s_nop 0
	s_mov_b32 m0, s43
	v_lshl_add_u64 v[224:225], s[72:73], 0, v[152:153]
	global_load_lds_dwordx4 v150, s[88:89]
	s_nop 0
	s_add_i32 m0, s43, 0x2000
	s_nop 0
	global_load_lds_dwordx4 v154, s[88:89]
	v_lshl_add_u64 v[222:223], s[72:73], 0, v[148:149]
	s_mov_b32 m0, s7
	s_nop 0
	global_load_lds_dwordx4 v[222:223], off
	s_mov_b32 m0, s8
	s_nop 0
	global_load_lds_dwordx4 v[224:225], off
	s_waitcnt vmcnt(8)
	s_waitcnt lgkmcnt(0)
	s_setprio 1
	s_barrier
	v_mfma_f32_16x16x32_bf16 v[60:63], v[104:107], v[178:181], v[60:63]
	v_mfma_f32_16x16x32_bf16 v[56:59], v[112:115], v[178:181], v[56:59]
	v_mfma_f32_16x16x32_bf16 v[44:47], v[104:107], v[186:189], v[44:47]
	v_mfma_f32_16x16x32_bf16 v[40:43], v[112:115], v[186:189], v[40:43]
	v_mfma_f32_16x16x32_bf16 v[20:23], v[104:107], v[200:203], v[20:23]
	v_mfma_f32_16x16x32_bf16 v[16:19], v[112:115], v[200:203], v[16:19]
	v_mfma_f32_16x16x32_bf16 v[4:7], v[104:107], v[210:213], v[4:7]
	v_mfma_f32_16x16x32_bf16 v[0:3], v[112:115], v[210:213], v[0:3]
	v_mfma_f32_16x16x32_bf16 v[60:63], v[108:111], v[182:185], v[60:63]
	v_mfma_f32_16x16x32_bf16 v[56:59], v[116:119], v[182:185], v[56:59]
	v_mfma_f32_16x16x32_bf16 v[44:47], v[108:111], v[190:193], v[44:47]
	v_mfma_f32_16x16x32_bf16 v[40:43], v[116:119], v[190:193], v[40:43]
	v_mfma_f32_16x16x32_bf16 v[20:23], v[108:111], v[206:209], v[20:23]
	v_mfma_f32_16x16x32_bf16 v[16:19], v[116:119], v[206:209], v[16:19]
	v_mfma_f32_16x16x32_bf16 v[4:7], v[108:111], v[214:217], v[4:7]
	v_mfma_f32_16x16x32_bf16 v[0:3], v[116:119], v[214:217], v[0:3]
	v_mfma_f32_16x16x32_bf16 v[52:55], v[144:147], v[178:181], v[52:55]
	v_mfma_f32_16x16x32_bf16 v[48:51], v[170:173], v[178:181], v[48:51]
	v_mfma_f32_16x16x32_bf16 v[36:39], v[144:147], v[186:189], v[36:39]
	v_mfma_f32_16x16x32_bf16 v[32:35], v[170:173], v[186:189], v[32:35]
	v_mfma_f32_16x16x32_bf16 v[28:31], v[144:147], v[200:203], v[28:31]
	v_mfma_f32_16x16x32_bf16 v[24:27], v[170:173], v[200:203], v[24:27]
	v_mfma_f32_16x16x32_bf16 v[12:15], v[144:147], v[210:213], v[12:15]
	v_mfma_f32_16x16x32_bf16 v[8:11], v[170:173], v[210:213], v[8:11]
	v_mfma_f32_16x16x32_bf16 v[52:55], v[166:169], v[182:185], v[52:55]
	v_mfma_f32_16x16x32_bf16 v[48:51], v[174:177], v[182:185], v[48:51]
	v_mfma_f32_16x16x32_bf16 v[36:39], v[166:169], v[190:193], v[36:39]
	v_mfma_f32_16x16x32_bf16 v[32:35], v[174:177], v[190:193], v[32:35]
	v_mfma_f32_16x16x32_bf16 v[28:31], v[166:169], v[206:209], v[28:31]
	v_mfma_f32_16x16x32_bf16 v[24:27], v[174:177], v[206:209], v[24:27]
	v_mfma_f32_16x16x32_bf16 v[12:15], v[166:169], v[214:217], v[12:15]
	v_mfma_f32_16x16x32_bf16 v[8:11], v[174:177], v[214:217], v[8:11]
	s_barrier
	s_setprio 0
	v_add_u32_e32 v116, s76, v197
	v_add_u32_e32 v174, s77, v197
	ds_read_b128 v[104:107], v116
	ds_read_b128 v[108:111], v116 offset:1024
	ds_read_b128 v[112:115], v116 offset:2048
	ds_read_b128 v[116:119], v116 offset:3072
	ds_read_b128 v[144:147], v174
	ds_read_b128 v[166:169], v174 offset:1024
	ds_read_b128 v[170:173], v174 offset:2048
	ds_read_b128 v[174:177], v174 offset:3072
	s_add_u32 s72, s72, 0x80000
	s_addc_u32 s73, s73, 0
	s_mov_b32 m0, s9
	s_nop 0
	ds_read_b128 v[178:181], v156 offset:32768
	ds_read_b128 v[182:185], v156 offset:33792
	ds_read_b128 v[186:189], v156 offset:34816
	ds_read_b128 v[190:193], v156 offset:35840
	ds_read_b128 v[200:203], v156 offset:36864
	ds_read_b128 v[206:209], v156 offset:37888
	ds_read_b128 v[210:213], v156 offset:38912
	ds_read_b128 v[214:217], v156 offset:39936
	global_load_lds_dwordx4 v148, s[72:73]
	s_nop 0
	s_mov_b32 m0, s10
	s_nop 0
	global_load_lds_dwordx4 v152, s[72:73]
	s_waitcnt vmcnt(8)
	s_waitcnt lgkmcnt(0)
	s_setprio 1
	s_barrier
	v_mfma_f32_16x16x32_bf16 v[140:143], v[104:107], v[178:181], v[140:143]
	v_mfma_f32_16x16x32_bf16 v[136:139], v[112:115], v[178:181], v[136:139]
	v_mfma_f32_16x16x32_bf16 v[124:127], v[104:107], v[186:189], v[124:127]
	v_mfma_f32_16x16x32_bf16 v[120:123], v[112:115], v[186:189], v[120:123]
	v_mfma_f32_16x16x32_bf16 v[92:95], v[104:107], v[200:203], v[92:95]
	v_mfma_f32_16x16x32_bf16 v[88:91], v[112:115], v[200:203], v[88:91]
	v_mfma_f32_16x16x32_bf16 v[76:79], v[104:107], v[210:213], v[76:79]
	v_mfma_f32_16x16x32_bf16 v[72:75], v[112:115], v[210:213], v[72:75]
	v_mfma_f32_16x16x32_bf16 v[140:143], v[108:111], v[182:185], v[140:143]
	v_mfma_f32_16x16x32_bf16 v[136:139], v[116:119], v[182:185], v[136:139]
	v_mfma_f32_16x16x32_bf16 v[124:127], v[108:111], v[190:193], v[124:127]
	v_mfma_f32_16x16x32_bf16 v[120:123], v[116:119], v[190:193], v[120:123]
	v_mfma_f32_16x16x32_bf16 v[92:95], v[108:111], v[206:209], v[92:95]
	v_mfma_f32_16x16x32_bf16 v[88:91], v[116:119], v[206:209], v[88:91]
	v_mfma_f32_16x16x32_bf16 v[76:79], v[108:111], v[214:217], v[76:79]
	v_mfma_f32_16x16x32_bf16 v[72:75], v[116:119], v[214:217], v[72:75]
	v_mfma_f32_16x16x32_bf16 v[132:135], v[144:147], v[178:181], v[132:135]
	v_mfma_f32_16x16x32_bf16 v[128:131], v[170:173], v[178:181], v[128:131]
	v_mfma_f32_16x16x32_bf16 v[100:103], v[144:147], v[186:189], v[100:103]
	v_mfma_f32_16x16x32_bf16 v[96:99], v[170:173], v[186:189], v[96:99]
	v_mfma_f32_16x16x32_bf16 v[84:87], v[144:147], v[200:203], v[84:87]
	v_mfma_f32_16x16x32_bf16 v[80:83], v[170:173], v[200:203], v[80:83]
	v_mfma_f32_16x16x32_bf16 v[68:71], v[144:147], v[210:213], v[68:71]
	v_mfma_f32_16x16x32_bf16 v[64:67], v[170:173], v[210:213], v[64:67]
	v_mfma_f32_16x16x32_bf16 v[132:135], v[166:169], v[182:185], v[132:135]
	v_mfma_f32_16x16x32_bf16 v[128:131], v[174:177], v[182:185], v[128:131]
	v_mfma_f32_16x16x32_bf16 v[100:103], v[166:169], v[190:193], v[100:103]
	v_mfma_f32_16x16x32_bf16 v[96:99], v[174:177], v[190:193], v[96:99]
	v_mfma_f32_16x16x32_bf16 v[84:87], v[166:169], v[206:209], v[84:87]
	v_mfma_f32_16x16x32_bf16 v[80:83], v[174:177], v[206:209], v[80:83]
	v_mfma_f32_16x16x32_bf16 v[68:71], v[166:169], v[214:217], v[68:71]
	v_mfma_f32_16x16x32_bf16 v[64:67], v[174:177], v[214:217], v[64:67]
	s_barrier
	s_setprio 0
	s_add_i32 s43, s76, s6
	s_nop 0
	s_add_i32 m0, s43, 0xffffff80
	ds_read_b128 v[178:181], v156 offset:49152
	ds_read_b128 v[182:185], v156 offset:50176
	ds_read_b128 v[186:189], v156 offset:51200
	ds_read_b128 v[190:193], v156 offset:52224
	ds_read_b128 v[200:203], v156 offset:53248
	ds_read_b128 v[206:209], v156 offset:54272
	ds_read_b128 v[210:213], v156 offset:55296
	ds_read_b128 v[214:217], v156 offset:56320
	global_load_lds_dwordx4 v[218:219], off offset:128
	s_add_i32 m0, s43, 0x1f80
	s_add_u32 s70, s70, 0x80080
	s_nop 0
	s_addc_u32 s71, s71, 0
	s_add_i32 s43, s77, s6
	global_load_lds_dwordx4 v[220:221], off offset:128
	s_nop 0
	s_mov_b32 m0, s43
	s_nop 0
	global_load_lds_dwordx4 v150, s[70:71]
	s_nop 0
	s_add_i32 m0, s43, 0x2000
	s_nop 0
	global_load_lds_dwordx4 v154, s[70:71]
	s_nop 0
	s_add_i32 m0, s11, 0xffffff80
	s_nop 0
	global_load_lds_dwordx4 v[222:223], off offset:128
	s_nop 0
	s_add_i32 m0, s12, 0xffffff80
	s_nop 0
	global_load_lds_dwordx4 v[224:225], off offset:128
	s_waitcnt vmcnt(8)
	s_waitcnt lgkmcnt(0)
	s_setprio 1
	s_barrier
	v_mfma_f32_16x16x32_bf16 v[60:63], v[104:107], v[178:181], v[60:63]
	v_mfma_f32_16x16x32_bf16 v[56:59], v[112:115], v[178:181], v[56:59]
	v_mfma_f32_16x16x32_bf16 v[44:47], v[104:107], v[186:189], v[44:47]
	v_mfma_f32_16x16x32_bf16 v[40:43], v[112:115], v[186:189], v[40:43]
	v_mfma_f32_16x16x32_bf16 v[20:23], v[104:107], v[200:203], v[20:23]
	v_mfma_f32_16x16x32_bf16 v[16:19], v[112:115], v[200:203], v[16:19]
	v_mfma_f32_16x16x32_bf16 v[4:7], v[104:107], v[210:213], v[4:7]
	v_mfma_f32_16x16x32_bf16 v[0:3], v[112:115], v[210:213], v[0:3]
	v_mfma_f32_16x16x32_bf16 v[60:63], v[108:111], v[182:185], v[60:63]
	v_mfma_f32_16x16x32_bf16 v[56:59], v[116:119], v[182:185], v[56:59]
	v_mfma_f32_16x16x32_bf16 v[44:47], v[108:111], v[190:193], v[44:47]
	v_mfma_f32_16x16x32_bf16 v[40:43], v[116:119], v[190:193], v[40:43]
	v_mfma_f32_16x16x32_bf16 v[20:23], v[108:111], v[206:209], v[20:23]
	v_mfma_f32_16x16x32_bf16 v[16:19], v[116:119], v[206:209], v[16:19]
	v_mfma_f32_16x16x32_bf16 v[4:7], v[108:111], v[214:217], v[4:7]
	v_mfma_f32_16x16x32_bf16 v[0:3], v[116:119], v[214:217], v[0:3]
	v_mfma_f32_16x16x32_bf16 v[52:55], v[144:147], v[178:181], v[52:55]
	v_mfma_f32_16x16x32_bf16 v[48:51], v[170:173], v[178:181], v[48:51]
	v_mfma_f32_16x16x32_bf16 v[36:39], v[144:147], v[186:189], v[36:39]
	v_mfma_f32_16x16x32_bf16 v[32:35], v[170:173], v[186:189], v[32:35]
	v_mfma_f32_16x16x32_bf16 v[28:31], v[144:147], v[200:203], v[28:31]
	v_mfma_f32_16x16x32_bf16 v[24:27], v[170:173], v[200:203], v[24:27]
	v_mfma_f32_16x16x32_bf16 v[12:15], v[144:147], v[210:213], v[12:15]
	v_mfma_f32_16x16x32_bf16 v[8:11], v[170:173], v[210:213], v[8:11]
	v_mfma_f32_16x16x32_bf16 v[52:55], v[166:169], v[182:185], v[52:55]
	v_mfma_f32_16x16x32_bf16 v[48:51], v[174:177], v[182:185], v[48:51]
	v_mfma_f32_16x16x32_bf16 v[36:39], v[166:169], v[190:193], v[36:39]
	v_mfma_f32_16x16x32_bf16 v[32:35], v[174:177], v[190:193], v[32:35]
	v_mfma_f32_16x16x32_bf16 v[28:31], v[166:169], v[206:209], v[28:31]
	v_mfma_f32_16x16x32_bf16 v[24:27], v[174:177], v[206:209], v[24:27]
	v_mfma_f32_16x16x32_bf16 v[12:15], v[166:169], v[214:217], v[12:15]
	v_mfma_f32_16x16x32_bf16 v[8:11], v[174:177], v[214:217], v[8:11]
	s_barrier
	s_setprio 0
	s_cmp_gt_u32 s23, 29
	s_cbranch_scc1 .LBB0_2147
	s_mov_b32 s23, s50
	s_branch .LBB0_2133

.LBB0_3142:
	s_or_b32 s40, s31, 1
	s_lshl_b64 s[96:97], s[40:41], 7
	s_add_i32 s40, s31, 2
	s_lshl_b64 vcc, s[40:41], 7
	s_add_u32 s53, s60, vcc_lo
	s_addc_u32 s59, s61, vcc_hi
	s_and_b64 s[70:71], s[68:69], exec
	s_cselect_b32 s71, s59, s55
	s_cselect_b32 s70, s53, s54
	s_add_u32 s53, s62, vcc_lo
	s_addc_u32 s59, s63, vcc_hi
	s_add_i32 s65, 0, 0x10000
	s_and_b64 s[68:69], s[68:69], exec
	s_cselect_b32 s69, s59, s57
	s_cselect_b32 s68, s53, s56
	s_add_i32 s53, 0, 0x14000
	v_add_u32_e32 v140, s65, v169
	v_add_u32_e32 v182, s53, v169
	ds_read_b128 v[128:131], v140
	ds_read_b128 v[132:135], v140 offset:1024
	ds_read_b128 v[136:139], v140 offset:2048
	ds_read_b128 v[140:143], v140 offset:3072
	ds_read_b128 v[160:163], v182
	ds_read_b128 v[174:177], v182 offset:1024
	ds_read_b128 v[178:181], v182 offset:2048
	ds_read_b128 v[182:185], v182 offset:3072
	s_add_u32 s59, s60, s96
	s_addc_u32 s95, s61, s97
	s_add_u32 s96, s59, 0x80000
	s_addc_u32 s97, s95, 0
	s_nop 0
	s_add_i32 m0, s7, 0xc000
	ds_read_b128 v[186:189], v173
	ds_read_b128 v[190:193], v173 offset:1024
	ds_read_b128 v[194:197], v173 offset:2048
	ds_read_b128 v[198:201], v173 offset:3072
	ds_read_b128 v[206:209], v173 offset:4096
	ds_read_b128 v[210:213], v173 offset:5120
	ds_read_b128 v[214:217], v173 offset:6144
	ds_read_b128 v[218:221], v173 offset:7168
	global_load_lds_dwordx4 v152, s[96:97]
	s_nop 0
	s_add_i32 m0, s7, 0xe000
	s_nop 0
	global_load_lds_dwordx4 v154, s[96:97]
	s_waitcnt vmcnt(8)
	s_waitcnt lgkmcnt(0)
	s_setprio 1
	s_barrier
	v_mfma_f32_16x16x32_bf16 v[124:127], v[128:131], v[186:189], v[124:127]
	v_mfma_f32_16x16x32_bf16 v[120:123], v[136:139], v[186:189], v[120:123]
	v_mfma_f32_16x16x32_bf16 v[108:111], v[128:131], v[194:197], v[108:111]
	v_mfma_f32_16x16x32_bf16 v[104:107], v[136:139], v[194:197], v[104:107]
	v_mfma_f32_16x16x32_bf16 v[92:95], v[128:131], v[206:209], v[92:95]
	v_mfma_f32_16x16x32_bf16 v[88:91], v[136:139], v[206:209], v[88:91]
	v_mfma_f32_16x16x32_bf16 v[76:79], v[128:131], v[214:217], v[76:79]
	v_mfma_f32_16x16x32_bf16 v[72:75], v[136:139], v[214:217], v[72:75]
	v_mfma_f32_16x16x32_bf16 v[124:127], v[132:135], v[190:193], v[124:127]
	v_mfma_f32_16x16x32_bf16 v[120:123], v[140:143], v[190:193], v[120:123]
	v_mfma_f32_16x16x32_bf16 v[108:111], v[132:135], v[198:201], v[108:111]
	v_mfma_f32_16x16x32_bf16 v[104:107], v[140:143], v[198:201], v[104:107]
	v_mfma_f32_16x16x32_bf16 v[92:95], v[132:135], v[210:213], v[92:95]
	v_mfma_f32_16x16x32_bf16 v[88:91], v[140:143], v[210:213], v[88:91]
	v_mfma_f32_16x16x32_bf16 v[76:79], v[132:135], v[218:221], v[76:79]
	v_mfma_f32_16x16x32_bf16 v[72:75], v[140:143], v[218:221], v[72:75]
	v_mfma_f32_16x16x32_bf16 v[116:119], v[160:163], v[186:189], v[116:119]
	v_mfma_f32_16x16x32_bf16 v[112:115], v[178:181], v[186:189], v[112:115]
	v_mfma_f32_16x16x32_bf16 v[100:103], v[160:163], v[194:197], v[100:103]
	v_mfma_f32_16x16x32_bf16 v[96:99], v[178:181], v[194:197], v[96:99]
	v_mfma_f32_16x16x32_bf16 v[84:87], v[160:163], v[206:209], v[84:87]
	v_mfma_f32_16x16x32_bf16 v[80:83], v[178:181], v[206:209], v[80:83]
	v_mfma_f32_16x16x32_bf16 v[68:71], v[160:163], v[214:217], v[68:71]
	v_mfma_f32_16x16x32_bf16 v[64:67], v[178:181], v[214:217], v[64:67]
	v_mfma_f32_16x16x32_bf16 v[116:119], v[174:177], v[190:193], v[116:119]
	v_mfma_f32_16x16x32_bf16 v[112:115], v[182:185], v[190:193], v[112:115]
	v_mfma_f32_16x16x32_bf16 v[100:103], v[174:177], v[198:201], v[100:103]
	v_mfma_f32_16x16x32_bf16 v[96:99], v[182:185], v[198:201], v[96:99]
	v_mfma_f32_16x16x32_bf16 v[84:87], v[174:177], v[210:213], v[84:87]
	v_mfma_f32_16x16x32_bf16 v[80:83], v[182:185], v[210:213], v[80:83]
	v_mfma_f32_16x16x32_bf16 v[68:71], v[174:177], v[218:221], v[68:71]
	v_mfma_f32_16x16x32_bf16 v[64:67], v[182:185], v[218:221], v[64:67]
	s_barrier
	s_setprio 0
	s_add_i32 s59, s65, s6
	v_lshl_add_u64 v[202:203], s[68:69], 0, v[144:145]
	s_mov_b32 m0, s59
	ds_read_b128 v[186:189], v173 offset:16384
	ds_read_b128 v[190:193], v173 offset:17408
	ds_read_b128 v[194:197], v173 offset:18432
	ds_read_b128 v[198:201], v173 offset:19456
	ds_read_b128 v[206:209], v173 offset:20480
	ds_read_b128 v[210:213], v173 offset:21504
	ds_read_b128 v[214:217], v173 offset:22528
	ds_read_b128 v[218:221], v173 offset:23552
	global_load_lds_dwordx4 v[202:203], off
	s_add_i32 m0, s59, 0x2000
	s_add_u32 s96, s68, 0x80000
	v_lshl_add_u64 v[222:223], s[68:69], 0, v[156:157]
	s_addc_u32 s97, s69, 0
	s_add_i32 s53, s53, s6
	global_load_lds_dwordx4 v[222:223], off
	s_nop 0
	s_mov_b32 m0, s53
	v_lshl_add_u64 v[226:227], s[70:71], 0, v[154:155]
	global_load_lds_dwordx4 v144, s[96:97]
	s_nop 0
	s_add_i32 m0, s53, 0x2000
	s_nop 0
	global_load_lds_dwordx4 v156, s[96:97]
	v_lshl_add_u64 v[224:225], s[70:71], 0, v[152:153]
	s_mov_b32 m0, s7
	s_nop 0
	global_load_lds_dwordx4 v[224:225], off
	s_mov_b32 m0, s8
	s_nop 0
	global_load_lds_dwordx4 v[226:227], off
	s_waitcnt vmcnt(8)
	s_waitcnt lgkmcnt(0)
	s_setprio 1
	s_barrier
	v_mfma_f32_16x16x32_bf16 v[60:63], v[128:131], v[186:189], v[60:63]
	v_mfma_f32_16x16x32_bf16 v[56:59], v[136:139], v[186:189], v[56:59]
	v_mfma_f32_16x16x32_bf16 v[44:47], v[128:131], v[194:197], v[44:47]
	v_mfma_f32_16x16x32_bf16 v[40:43], v[136:139], v[194:197], v[40:43]
	v_mfma_f32_16x16x32_bf16 v[24:27], v[128:131], v[206:209], v[24:27]
	v_mfma_f32_16x16x32_bf16 v[16:19], v[136:139], v[206:209], v[16:19]
	v_mfma_f32_16x16x32_bf16 v[4:7], v[128:131], v[214:217], v[4:7]
	v_mfma_f32_16x16x32_bf16 v[0:3], v[136:139], v[214:217], v[0:3]
	v_mfma_f32_16x16x32_bf16 v[60:63], v[132:135], v[190:193], v[60:63]
	v_mfma_f32_16x16x32_bf16 v[56:59], v[140:143], v[190:193], v[56:59]
	v_mfma_f32_16x16x32_bf16 v[44:47], v[132:135], v[198:201], v[44:47]
	v_mfma_f32_16x16x32_bf16 v[40:43], v[140:143], v[198:201], v[40:43]
	v_mfma_f32_16x16x32_bf16 v[24:27], v[132:135], v[210:213], v[24:27]
	v_mfma_f32_16x16x32_bf16 v[16:19], v[140:143], v[210:213], v[16:19]
	v_mfma_f32_16x16x32_bf16 v[4:7], v[132:135], v[218:221], v[4:7]
	v_mfma_f32_16x16x32_bf16 v[0:3], v[140:143], v[218:221], v[0:3]
	v_mfma_f32_16x16x32_bf16 v[52:55], v[160:163], v[186:189], v[52:55]
	v_mfma_f32_16x16x32_bf16 v[48:51], v[178:181], v[186:189], v[48:51]
	v_mfma_f32_16x16x32_bf16 v[28:31], v[160:163], v[194:197], v[28:31]
	v_mfma_f32_16x16x32_bf16 v[20:23], v[178:181], v[194:197], v[20:23]
	v_mfma_f32_16x16x32_bf16 v[32:35], v[160:163], v[206:209], v[32:35]
	v_mfma_f32_16x16x32_bf16 v[36:39], v[178:181], v[206:209], v[36:39]
	v_mfma_f32_16x16x32_bf16 v[8:11], v[160:163], v[214:217], v[8:11]
	v_mfma_f32_16x16x32_bf16 v[12:15], v[178:181], v[214:217], v[12:15]
	v_mfma_f32_16x16x32_bf16 v[52:55], v[174:177], v[190:193], v[52:55]
	v_mfma_f32_16x16x32_bf16 v[48:51], v[182:185], v[190:193], v[48:51]
	v_mfma_f32_16x16x32_bf16 v[28:31], v[174:177], v[198:201], v[28:31]
	v_mfma_f32_16x16x32_bf16 v[20:23], v[182:185], v[198:201], v[20:23]
	v_mfma_f32_16x16x32_bf16 v[32:35], v[174:177], v[210:213], v[32:35]
	v_mfma_f32_16x16x32_bf16 v[36:39], v[182:185], v[210:213], v[36:39]
	v_mfma_f32_16x16x32_bf16 v[8:11], v[174:177], v[218:221], v[8:11]
	v_mfma_f32_16x16x32_bf16 v[12:15], v[182:185], v[218:221], v[12:15]
	s_barrier
	s_setprio 0
	s_add_i32 s53, 0, 0x18000
	s_add_i32 s59, 0, 0x1c000
	v_add_u32_e32 v140, s53, v169
	v_add_u32_e32 v182, s59, v169
	ds_read_b128 v[128:131], v140
	ds_read_b128 v[132:135], v140 offset:1024
	ds_read_b128 v[136:139], v140 offset:2048
	ds_read_b128 v[140:143], v140 offset:3072
	ds_read_b128 v[160:163], v182
	ds_read_b128 v[174:177], v182 offset:1024
	ds_read_b128 v[178:181], v182 offset:2048
	ds_read_b128 v[182:185], v182 offset:3072
	s_add_u32 s70, s70, 0x80000
	s_addc_u32 s71, s71, 0
	s_mov_b32 m0, s9
	s_nop 0
	ds_read_b128 v[186:189], v173 offset:32768
	ds_read_b128 v[190:193], v173 offset:33792
	ds_read_b128 v[194:197], v173 offset:34816
	ds_read_b128 v[198:201], v173 offset:35840
	ds_read_b128 v[206:209], v173 offset:36864
	ds_read_b128 v[210:213], v173 offset:37888
	ds_read_b128 v[214:217], v173 offset:38912
	ds_read_b128 v[218:221], v173 offset:39936
	global_load_lds_dwordx4 v152, s[70:71]
	s_nop 0
	s_mov_b32 m0, s10
	s_nop 0
	global_load_lds_dwordx4 v154, s[70:71]
	s_waitcnt vmcnt(8)
	s_waitcnt lgkmcnt(0)
	s_setprio 1
	s_barrier
	v_mfma_f32_16x16x32_bf16 v[124:127], v[128:131], v[186:189], v[124:127]
	v_mfma_f32_16x16x32_bf16 v[120:123], v[136:139], v[186:189], v[120:123]
	v_mfma_f32_16x16x32_bf16 v[108:111], v[128:131], v[194:197], v[108:111]
	v_mfma_f32_16x16x32_bf16 v[104:107], v[136:139], v[194:197], v[104:107]
	v_mfma_f32_16x16x32_bf16 v[92:95], v[128:131], v[206:209], v[92:95]
	v_mfma_f32_16x16x32_bf16 v[88:91], v[136:139], v[206:209], v[88:91]
	v_mfma_f32_16x16x32_bf16 v[76:79], v[128:131], v[214:217], v[76:79]
	v_mfma_f32_16x16x32_bf16 v[72:75], v[136:139], v[214:217], v[72:75]
	v_mfma_f32_16x16x32_bf16 v[124:127], v[132:135], v[190:193], v[124:127]
	v_mfma_f32_16x16x32_bf16 v[120:123], v[140:143], v[190:193], v[120:123]
	v_mfma_f32_16x16x32_bf16 v[108:111], v[132:135], v[198:201], v[108:111]
	v_mfma_f32_16x16x32_bf16 v[104:107], v[140:143], v[198:201], v[104:107]
	v_mfma_f32_16x16x32_bf16 v[92:95], v[132:135], v[210:213], v[92:95]
	v_mfma_f32_16x16x32_bf16 v[88:91], v[140:143], v[210:213], v[88:91]
	v_mfma_f32_16x16x32_bf16 v[76:79], v[132:135], v[218:221], v[76:79]
	v_mfma_f32_16x16x32_bf16 v[72:75], v[140:143], v[218:221], v[72:75]
	v_mfma_f32_16x16x32_bf16 v[116:119], v[160:163], v[186:189], v[116:119]
	v_mfma_f32_16x16x32_bf16 v[112:115], v[178:181], v[186:189], v[112:115]
	v_mfma_f32_16x16x32_bf16 v[100:103], v[160:163], v[194:197], v[100:103]
	v_mfma_f32_16x16x32_bf16 v[96:99], v[178:181], v[194:197], v[96:99]
	v_mfma_f32_16x16x32_bf16 v[84:87], v[160:163], v[206:209], v[84:87]
	v_mfma_f32_16x16x32_bf16 v[80:83], v[178:181], v[206:209], v[80:83]
	v_mfma_f32_16x16x32_bf16 v[68:71], v[160:163], v[214:217], v[68:71]
	v_mfma_f32_16x16x32_bf16 v[64:67], v[178:181], v[214:217], v[64:67]
	v_mfma_f32_16x16x32_bf16 v[116:119], v[174:177], v[190:193], v[116:119]
	v_mfma_f32_16x16x32_bf16 v[112:115], v[182:185], v[190:193], v[112:115]
	v_mfma_f32_16x16x32_bf16 v[100:103], v[174:177], v[198:201], v[100:103]
	v_mfma_f32_16x16x32_bf16 v[96:99], v[182:185], v[198:201], v[96:99]
	v_mfma_f32_16x16x32_bf16 v[84:87], v[174:177], v[210:213], v[84:87]
	v_mfma_f32_16x16x32_bf16 v[80:83], v[182:185], v[210:213], v[80:83]
	v_mfma_f32_16x16x32_bf16 v[68:71], v[174:177], v[218:221], v[68:71]
	v_mfma_f32_16x16x32_bf16 v[64:67], v[182:185], v[218:221], v[64:67]
	s_barrier
	s_setprio 0
	s_add_i32 s53, s53, s6
	s_nop 0
	s_add_i32 m0, s53, 0xffffff80
	ds_read_b128 v[186:189], v173 offset:49152
	ds_read_b128 v[190:193], v173 offset:50176
	ds_read_b128 v[194:197], v173 offset:51200
	ds_read_b128 v[198:201], v173 offset:52224
	ds_read_b128 v[206:209], v173 offset:53248
	ds_read_b128 v[210:213], v173 offset:54272
	ds_read_b128 v[214:217], v173 offset:55296
	ds_read_b128 v[218:221], v173 offset:56320
	global_load_lds_dwordx4 v[202:203], off offset:128
	s_add_i32 m0, s53, 0x1f80
	s_add_u32 s68, s68, 0x80080
	s_nop 0
	s_addc_u32 s69, s69, 0
	s_add_i32 s53, s59, s6
	global_load_lds_dwordx4 v[222:223], off offset:128
	s_nop 0
	s_mov_b32 m0, s53
	s_nop 0
	global_load_lds_dwordx4 v144, s[68:69]
	s_nop 0
	s_add_i32 m0, s53, 0x2000
	s_nop 0
	global_load_lds_dwordx4 v156, s[68:69]
	s_nop 0
	s_add_i32 m0, s11, 0xffffff80
	s_nop 0
	global_load_lds_dwordx4 v[224:225], off offset:128
	s_nop 0
	s_add_i32 m0, s12, 0xffffff80
	s_nop 0
	global_load_lds_dwordx4 v[226:227], off offset:128
	s_waitcnt vmcnt(8)
	s_waitcnt lgkmcnt(0)
	s_setprio 1
	s_barrier
	v_mfma_f32_16x16x32_bf16 v[60:63], v[128:131], v[186:189], v[60:63]
	v_mfma_f32_16x16x32_bf16 v[56:59], v[136:139], v[186:189], v[56:59]
	v_mfma_f32_16x16x32_bf16 v[44:47], v[128:131], v[194:197], v[44:47]
	v_mfma_f32_16x16x32_bf16 v[40:43], v[136:139], v[194:197], v[40:43]
	v_mfma_f32_16x16x32_bf16 v[24:27], v[128:131], v[206:209], v[24:27]
	v_mfma_f32_16x16x32_bf16 v[16:19], v[136:139], v[206:209], v[16:19]
	v_mfma_f32_16x16x32_bf16 v[4:7], v[128:131], v[214:217], v[4:7]
	v_mfma_f32_16x16x32_bf16 v[0:3], v[136:139], v[214:217], v[0:3]
	v_mfma_f32_16x16x32_bf16 v[60:63], v[132:135], v[190:193], v[60:63]
	v_mfma_f32_16x16x32_bf16 v[56:59], v[140:143], v[190:193], v[56:59]
	v_mfma_f32_16x16x32_bf16 v[44:47], v[132:135], v[198:201], v[44:47]
	v_mfma_f32_16x16x32_bf16 v[40:43], v[140:143], v[198:201], v[40:43]
	v_mfma_f32_16x16x32_bf16 v[24:27], v[132:135], v[210:213], v[24:27]
	v_mfma_f32_16x16x32_bf16 v[16:19], v[140:143], v[210:213], v[16:19]
	v_mfma_f32_16x16x32_bf16 v[4:7], v[132:135], v[218:221], v[4:7]
	v_mfma_f32_16x16x32_bf16 v[0:3], v[140:143], v[218:221], v[0:3]
	v_mfma_f32_16x16x32_bf16 v[52:55], v[160:163], v[186:189], v[52:55]
	v_mfma_f32_16x16x32_bf16 v[48:51], v[178:181], v[186:189], v[48:51]
	v_mfma_f32_16x16x32_bf16 v[28:31], v[160:163], v[194:197], v[28:31]
	v_mfma_f32_16x16x32_bf16 v[20:23], v[178:181], v[194:197], v[20:23]
	v_mfma_f32_16x16x32_bf16 v[32:35], v[160:163], v[206:209], v[32:35]
	v_mfma_f32_16x16x32_bf16 v[36:39], v[178:181], v[206:209], v[36:39]
	v_mfma_f32_16x16x32_bf16 v[8:11], v[160:163], v[214:217], v[8:11]
	v_mfma_f32_16x16x32_bf16 v[12:15], v[178:181], v[214:217], v[12:15]
	v_mfma_f32_16x16x32_bf16 v[52:55], v[174:177], v[190:193], v[52:55]
	v_mfma_f32_16x16x32_bf16 v[48:51], v[182:185], v[190:193], v[48:51]
	v_mfma_f32_16x16x32_bf16 v[28:31], v[174:177], v[198:201], v[28:31]
	v_mfma_f32_16x16x32_bf16 v[20:23], v[182:185], v[198:201], v[20:23]
	v_mfma_f32_16x16x32_bf16 v[32:35], v[174:177], v[210:213], v[32:35]
	v_mfma_f32_16x16x32_bf16 v[36:39], v[182:185], v[210:213], v[36:39]
	v_mfma_f32_16x16x32_bf16 v[8:11], v[174:177], v[218:221], v[8:11]
	v_mfma_f32_16x16x32_bf16 v[12:15], v[182:185], v[218:221], v[12:15]
	s_barrier
	s_setprio 0
	s_cmp_gt_u32 s31, 29
	s_cbranch_scc1 .LBB0_3144
	s_mov_b32 s31, s40
	s_branch .LBB0_3130

.LBB0_3613:
	s_add_i32 s70, s26, 2
	s_add_u32 s71, s22, 0x80
	s_addc_u32 s27, s23, 0
	s_add_i32 s95, 0, 0x10000
	s_cmp_eq_u32 s67, s26
	s_cselect_b32 s27, s40, s27
	s_cselect_b32 s26, s53, s71
	v_add_u32_e32 v155, s95, v143
	s_cselect_b32 s97, s58, s69
	s_cselect_b32 s96, s59, s68
	s_add_i32 s71, 0, 0x14000
	ds_read_b128 v[138:141], v155
	ds_read_b128 v[156:159], v155 offset:1024
	ds_read_b128 v[160:163], v155 offset:2048
	ds_read_b128 v[168:171], v155 offset:3072
	v_add_u32_e32 v155, s71, v143
	ds_read_b128 v[172:175], v155
	ds_read_b128 v[176:179], v155 offset:1024
	ds_read_b128 v[180:183], v155 offset:2048
	ds_read_b128 v[184:187], v155 offset:3072
	s_nop 0
	s_add_i32 m0, s12, 0xc000
	ds_read_b128 v[188:191], v154
	ds_read_b128 v[192:195], v154 offset:1024
	ds_read_b128 v[196:199], v154 offset:2048
	ds_read_b128 v[200:203], v154 offset:3072
	ds_read_b128 v[206:209], v154 offset:4096
	ds_read_b128 v[210:213], v154 offset:5120
	ds_read_b128 v[214:217], v154 offset:6144
	ds_read_b128 v[218:221], v154 offset:7168
	global_load_lds_dwordx4 v136, s[22:23]
	s_nop 0
	s_add_i32 m0, s12, 0xe000
	s_nop 0
	global_load_lds_dwordx4 v134, s[22:23]
	s_waitcnt vmcnt(8)
	s_waitcnt lgkmcnt(0)
	s_setprio 1
	s_barrier
	v_mfma_f32_16x16x32_bf16 v[124:127], v[138:141], v[188:191], v[124:127]
	v_mfma_f32_16x16x32_bf16 v[120:123], v[160:163], v[188:191], v[120:123]
	v_mfma_f32_16x16x32_bf16 v[108:111], v[138:141], v[196:199], v[108:111]
	v_mfma_f32_16x16x32_bf16 v[104:107], v[160:163], v[196:199], v[104:107]
	v_mfma_f32_16x16x32_bf16 v[92:95], v[138:141], v[206:209], v[92:95]
	v_mfma_f32_16x16x32_bf16 v[88:91], v[160:163], v[206:209], v[88:91]
	v_mfma_f32_16x16x32_bf16 v[76:79], v[138:141], v[214:217], v[76:79]
	v_mfma_f32_16x16x32_bf16 v[72:75], v[160:163], v[214:217], v[72:75]
	v_mfma_f32_16x16x32_bf16 v[124:127], v[156:159], v[192:195], v[124:127]
	v_mfma_f32_16x16x32_bf16 v[120:123], v[168:171], v[192:195], v[120:123]
	v_mfma_f32_16x16x32_bf16 v[108:111], v[156:159], v[200:203], v[108:111]
	v_mfma_f32_16x16x32_bf16 v[104:107], v[168:171], v[200:203], v[104:107]
	v_mfma_f32_16x16x32_bf16 v[92:95], v[156:159], v[210:213], v[92:95]
	v_mfma_f32_16x16x32_bf16 v[88:91], v[168:171], v[210:213], v[88:91]
	v_mfma_f32_16x16x32_bf16 v[76:79], v[156:159], v[218:221], v[76:79]
	v_mfma_f32_16x16x32_bf16 v[72:75], v[168:171], v[218:221], v[72:75]
	v_mfma_f32_16x16x32_bf16 v[116:119], v[172:175], v[188:191], v[116:119]
	v_mfma_f32_16x16x32_bf16 v[112:115], v[180:183], v[188:191], v[112:115]
	v_mfma_f32_16x16x32_bf16 v[100:103], v[172:175], v[196:199], v[100:103]
	v_mfma_f32_16x16x32_bf16 v[96:99], v[180:183], v[196:199], v[96:99]
	v_mfma_f32_16x16x32_bf16 v[84:87], v[172:175], v[206:209], v[84:87]
	v_mfma_f32_16x16x32_bf16 v[80:83], v[180:183], v[206:209], v[80:83]
	v_mfma_f32_16x16x32_bf16 v[68:71], v[172:175], v[214:217], v[68:71]
	v_mfma_f32_16x16x32_bf16 v[64:67], v[180:183], v[214:217], v[64:67]
	v_mfma_f32_16x16x32_bf16 v[116:119], v[176:179], v[192:195], v[116:119]
	v_mfma_f32_16x16x32_bf16 v[112:115], v[184:187], v[192:195], v[112:115]
	v_mfma_f32_16x16x32_bf16 v[100:103], v[176:179], v[200:203], v[100:103]
	v_mfma_f32_16x16x32_bf16 v[96:99], v[184:187], v[200:203], v[96:99]
	v_mfma_f32_16x16x32_bf16 v[84:87], v[176:179], v[210:213], v[84:87]
	v_mfma_f32_16x16x32_bf16 v[80:83], v[184:187], v[210:213], v[80:83]
	v_mfma_f32_16x16x32_bf16 v[68:71], v[176:179], v[218:221], v[68:71]
	v_mfma_f32_16x16x32_bf16 v[64:67], v[184:187], v[218:221], v[64:67]
	s_barrier
	s_setprio 0
	s_add_i32 s95, s95, s11
	v_lshl_add_u64 v[222:223], s[96:97], 0, v[144:145]
	s_mov_b32 m0, s95
	ds_read_b128 v[188:191], v154 offset:16384
	ds_read_b128 v[192:195], v154 offset:17408
	ds_read_b128 v[196:199], v154 offset:18432
	ds_read_b128 v[200:203], v154 offset:19456
	ds_read_b128 v[206:209], v154 offset:20480
	ds_read_b128 v[210:213], v154 offset:21504
	ds_read_b128 v[214:217], v154 offset:22528
	ds_read_b128 v[218:221], v154 offset:23552
	global_load_lds_dwordx4 v[222:223], off
	s_add_i32 m0, s95, 0x2000
	v_lshl_add_u64 v[224:225], s[96:97], 0, v[132:133]
	s_add_u32 s96, s96, s20
	s_addc_u32 s97, s97, 0
	s_add_i32 s71, s71, s11
	global_load_lds_dwordx4 v[224:225], off
	v_lshl_add_u64 v[226:227], s[96:97], 0, v[144:145]
	s_mov_b32 m0, s71
	v_lshl_add_u64 v[228:229], s[96:97], 0, v[132:133]
	global_load_lds_dwordx4 v[226:227], off
	s_add_i32 m0, s71, 0x2000
	v_lshl_add_u64 v[230:231], s[26:27], 0, v[128:129]
	global_load_lds_dwordx4 v[228:229], off
	s_mov_b32 m0, s12
	v_lshl_add_u64 v[232:233], s[26:27], 0, v[130:131]
	global_load_lds_dwordx4 v[230:231], off
	s_mov_b32 m0, s13
	s_nop 0
	global_load_lds_dwordx4 v[232:233], off
	s_waitcnt vmcnt(8)
	s_waitcnt lgkmcnt(0)
	s_setprio 1
	s_barrier
	v_mfma_f32_16x16x32_bf16 v[60:63], v[138:141], v[188:191], v[60:63]
	v_mfma_f32_16x16x32_bf16 v[56:59], v[160:163], v[188:191], v[56:59]
	v_mfma_f32_16x16x32_bf16 v[44:47], v[138:141], v[196:199], v[44:47]
	v_mfma_f32_16x16x32_bf16 v[40:43], v[160:163], v[196:199], v[40:43]
	v_mfma_f32_16x16x32_bf16 v[28:31], v[138:141], v[206:209], v[28:31]
	v_mfma_f32_16x16x32_bf16 v[24:27], v[160:163], v[206:209], v[24:27]
	v_mfma_f32_16x16x32_bf16 v[12:15], v[138:141], v[214:217], v[12:15]
	v_mfma_f32_16x16x32_bf16 v[8:11], v[160:163], v[214:217], v[8:11]
	v_mfma_f32_16x16x32_bf16 v[60:63], v[156:159], v[192:195], v[60:63]
	v_mfma_f32_16x16x32_bf16 v[56:59], v[168:171], v[192:195], v[56:59]
	v_mfma_f32_16x16x32_bf16 v[44:47], v[156:159], v[200:203], v[44:47]
	v_mfma_f32_16x16x32_bf16 v[40:43], v[168:171], v[200:203], v[40:43]
	v_mfma_f32_16x16x32_bf16 v[28:31], v[156:159], v[210:213], v[28:31]
	v_mfma_f32_16x16x32_bf16 v[24:27], v[168:171], v[210:213], v[24:27]
	v_mfma_f32_16x16x32_bf16 v[12:15], v[156:159], v[218:221], v[12:15]
	v_mfma_f32_16x16x32_bf16 v[8:11], v[168:171], v[218:221], v[8:11]
	v_mfma_f32_16x16x32_bf16 v[52:55], v[172:175], v[188:191], v[52:55]
	v_mfma_f32_16x16x32_bf16 v[48:51], v[180:183], v[188:191], v[48:51]
	v_mfma_f32_16x16x32_bf16 v[36:39], v[172:175], v[196:199], v[36:39]
	v_mfma_f32_16x16x32_bf16 v[32:35], v[180:183], v[196:199], v[32:35]
	v_mfma_f32_16x16x32_bf16 v[20:23], v[172:175], v[206:209], v[20:23]
	v_mfma_f32_16x16x32_bf16 v[16:19], v[180:183], v[206:209], v[16:19]
	v_mfma_f32_16x16x32_bf16 v[4:7], v[172:175], v[214:217], v[4:7]
	v_mfma_f32_16x16x32_bf16 v[0:3], v[180:183], v[214:217], v[0:3]
	v_mfma_f32_16x16x32_bf16 v[52:55], v[176:179], v[192:195], v[52:55]
	v_mfma_f32_16x16x32_bf16 v[48:51], v[184:187], v[192:195], v[48:51]
	v_mfma_f32_16x16x32_bf16 v[36:39], v[176:179], v[200:203], v[36:39]
	v_mfma_f32_16x16x32_bf16 v[32:35], v[184:187], v[200:203], v[32:35]
	v_mfma_f32_16x16x32_bf16 v[20:23], v[176:179], v[210:213], v[20:23]
	v_mfma_f32_16x16x32_bf16 v[16:19], v[184:187], v[210:213], v[16:19]
	v_mfma_f32_16x16x32_bf16 v[4:7], v[176:179], v[218:221], v[4:7]
	v_mfma_f32_16x16x32_bf16 v[0:3], v[184:187], v[218:221], v[0:3]
	s_barrier
	s_setprio 0
	s_add_i32 s71, 0, 0x18000
	v_add_u32_e32 v155, s71, v143
	s_add_i32 s95, 0, 0x1c000
	ds_read_b128 v[138:141], v155
	ds_read_b128 v[156:159], v155 offset:1024
	ds_read_b128 v[160:163], v155 offset:2048
	ds_read_b128 v[168:171], v155 offset:3072
	v_add_u32_e32 v155, s95, v143
	ds_read_b128 v[172:175], v155
	ds_read_b128 v[176:179], v155 offset:1024
	ds_read_b128 v[180:183], v155 offset:2048
	ds_read_b128 v[184:187], v155 offset:3072
	s_add_u32 s26, s26, s20
	s_addc_u32 s27, s27, 0
	s_mov_b32 m0, s28
	s_nop 0
	ds_read_b128 v[188:191], v154 offset:32768
	ds_read_b128 v[192:195], v154 offset:33792
	ds_read_b128 v[196:199], v154 offset:34816
	ds_read_b128 v[200:203], v154 offset:35840
	ds_read_b128 v[206:209], v154 offset:36864
	ds_read_b128 v[210:213], v154 offset:37888
	ds_read_b128 v[214:217], v154 offset:38912
	ds_read_b128 v[218:221], v154 offset:39936
	global_load_lds_dwordx4 v128, s[26:27]
	s_nop 0
	s_mov_b32 m0, s29
	s_nop 0
	global_load_lds_dwordx4 v130, s[26:27]
	s_waitcnt vmcnt(8)
	s_waitcnt lgkmcnt(0)
	s_setprio 1
	s_barrier
	v_mfma_f32_16x16x32_bf16 v[124:127], v[138:141], v[188:191], v[124:127]
	v_mfma_f32_16x16x32_bf16 v[120:123], v[160:163], v[188:191], v[120:123]
	v_mfma_f32_16x16x32_bf16 v[108:111], v[138:141], v[196:199], v[108:111]
	v_mfma_f32_16x16x32_bf16 v[104:107], v[160:163], v[196:199], v[104:107]
	v_mfma_f32_16x16x32_bf16 v[92:95], v[138:141], v[206:209], v[92:95]
	v_mfma_f32_16x16x32_bf16 v[88:91], v[160:163], v[206:209], v[88:91]
	v_mfma_f32_16x16x32_bf16 v[76:79], v[138:141], v[214:217], v[76:79]
	v_mfma_f32_16x16x32_bf16 v[72:75], v[160:163], v[214:217], v[72:75]
	v_mfma_f32_16x16x32_bf16 v[124:127], v[156:159], v[192:195], v[124:127]
	v_mfma_f32_16x16x32_bf16 v[120:123], v[168:171], v[192:195], v[120:123]
	v_mfma_f32_16x16x32_bf16 v[108:111], v[156:159], v[200:203], v[108:111]
	v_mfma_f32_16x16x32_bf16 v[104:107], v[168:171], v[200:203], v[104:107]
	v_mfma_f32_16x16x32_bf16 v[92:95], v[156:159], v[210:213], v[92:95]
	v_mfma_f32_16x16x32_bf16 v[88:91], v[168:171], v[210:213], v[88:91]
	v_mfma_f32_16x16x32_bf16 v[76:79], v[156:159], v[218:221], v[76:79]
	v_mfma_f32_16x16x32_bf16 v[72:75], v[168:171], v[218:221], v[72:75]
	v_mfma_f32_16x16x32_bf16 v[116:119], v[172:175], v[188:191], v[116:119]
	v_mfma_f32_16x16x32_bf16 v[112:115], v[180:183], v[188:191], v[112:115]
	v_mfma_f32_16x16x32_bf16 v[100:103], v[172:175], v[196:199], v[100:103]
	v_mfma_f32_16x16x32_bf16 v[96:99], v[180:183], v[196:199], v[96:99]
	v_mfma_f32_16x16x32_bf16 v[84:87], v[172:175], v[206:209], v[84:87]
	v_mfma_f32_16x16x32_bf16 v[80:83], v[180:183], v[206:209], v[80:83]
	v_mfma_f32_16x16x32_bf16 v[68:71], v[172:175], v[214:217], v[68:71]
	v_mfma_f32_16x16x32_bf16 v[64:67], v[180:183], v[214:217], v[64:67]
	v_mfma_f32_16x16x32_bf16 v[116:119], v[176:179], v[192:195], v[116:119]
	v_mfma_f32_16x16x32_bf16 v[112:115], v[184:187], v[192:195], v[112:115]
	v_mfma_f32_16x16x32_bf16 v[100:103], v[176:179], v[200:203], v[100:103]
	v_mfma_f32_16x16x32_bf16 v[96:99], v[184:187], v[200:203], v[96:99]
	v_mfma_f32_16x16x32_bf16 v[84:87], v[176:179], v[210:213], v[84:87]
	v_mfma_f32_16x16x32_bf16 v[80:83], v[184:187], v[210:213], v[80:83]
	v_mfma_f32_16x16x32_bf16 v[68:71], v[176:179], v[218:221], v[68:71]
	v_mfma_f32_16x16x32_bf16 v[64:67], v[184:187], v[218:221], v[64:67]
	s_barrier
	s_setprio 0
	s_add_i32 s26, s71, s11
	s_nop 0
	s_add_i32 m0, s26, 0xffffff80
	ds_read_b128 v[188:191], v154 offset:49152
	ds_read_b128 v[192:195], v154 offset:50176
	ds_read_b128 v[196:199], v154 offset:51200
	ds_read_b128 v[200:203], v154 offset:52224
	ds_read_b128 v[206:209], v154 offset:53248
	ds_read_b128 v[210:213], v154 offset:54272
	ds_read_b128 v[214:217], v154 offset:55296
	ds_read_b128 v[218:221], v154 offset:56320
	global_load_lds_dwordx4 v[222:223], off offset:128
	s_nop 0
	s_add_i32 m0, s26, 0x1f80
	s_add_i32 s26, s95, s11
	global_load_lds_dwordx4 v[224:225], off offset:128
	s_nop 0
	s_add_i32 m0, s26, 0xffffff80
	s_nop 0
	global_load_lds_dwordx4 v[226:227], off offset:128
	s_nop 0
	s_add_i32 m0, s26, 0x1f80
	s_nop 0
	global_load_lds_dwordx4 v[228:229], off offset:128
	s_nop 0
	s_add_i32 m0, s62, 0xffffff80
	s_nop 0
	global_load_lds_dwordx4 v[230:231], off offset:128
	s_nop 0
	s_add_i32 m0, s63, 0xffffff80
	s_nop 0
	global_load_lds_dwordx4 v[232:233], off offset:128
	s_waitcnt vmcnt(8)
	s_waitcnt lgkmcnt(0)
	s_setprio 1
	s_barrier
	v_mfma_f32_16x16x32_bf16 v[60:63], v[138:141], v[188:191], v[60:63]
	v_mfma_f32_16x16x32_bf16 v[56:59], v[160:163], v[188:191], v[56:59]
	v_mfma_f32_16x16x32_bf16 v[44:47], v[138:141], v[196:199], v[44:47]
	v_mfma_f32_16x16x32_bf16 v[40:43], v[160:163], v[196:199], v[40:43]
	v_mfma_f32_16x16x32_bf16 v[28:31], v[138:141], v[206:209], v[28:31]
	v_mfma_f32_16x16x32_bf16 v[24:27], v[160:163], v[206:209], v[24:27]
	v_mfma_f32_16x16x32_bf16 v[12:15], v[138:141], v[214:217], v[12:15]
	v_mfma_f32_16x16x32_bf16 v[8:11], v[160:163], v[214:217], v[8:11]
	v_mfma_f32_16x16x32_bf16 v[60:63], v[156:159], v[192:195], v[60:63]
	v_mfma_f32_16x16x32_bf16 v[56:59], v[168:171], v[192:195], v[56:59]
	v_mfma_f32_16x16x32_bf16 v[44:47], v[156:159], v[200:203], v[44:47]
	v_mfma_f32_16x16x32_bf16 v[40:43], v[168:171], v[200:203], v[40:43]
	v_mfma_f32_16x16x32_bf16 v[28:31], v[156:159], v[210:213], v[28:31]
	v_mfma_f32_16x16x32_bf16 v[24:27], v[168:171], v[210:213], v[24:27]
	v_mfma_f32_16x16x32_bf16 v[12:15], v[156:159], v[218:221], v[12:15]
	v_mfma_f32_16x16x32_bf16 v[8:11], v[168:171], v[218:221], v[8:11]
	v_mfma_f32_16x16x32_bf16 v[52:55], v[172:175], v[188:191], v[52:55]
	v_mfma_f32_16x16x32_bf16 v[48:51], v[180:183], v[188:191], v[48:51]
	v_mfma_f32_16x16x32_bf16 v[36:39], v[172:175], v[196:199], v[36:39]
	v_mfma_f32_16x16x32_bf16 v[32:35], v[180:183], v[196:199], v[32:35]
	v_mfma_f32_16x16x32_bf16 v[20:23], v[172:175], v[206:209], v[20:23]
	v_mfma_f32_16x16x32_bf16 v[16:19], v[180:183], v[206:209], v[16:19]
	v_mfma_f32_16x16x32_bf16 v[4:7], v[172:175], v[214:217], v[4:7]
	v_mfma_f32_16x16x32_bf16 v[0:3], v[180:183], v[214:217], v[0:3]
	v_mfma_f32_16x16x32_bf16 v[52:55], v[176:179], v[192:195], v[52:55]
	v_mfma_f32_16x16x32_bf16 v[48:51], v[184:187], v[192:195], v[48:51]
	v_mfma_f32_16x16x32_bf16 v[36:39], v[176:179], v[200:203], v[36:39]
	v_mfma_f32_16x16x32_bf16 v[32:35], v[184:187], v[200:203], v[32:35]
	v_mfma_f32_16x16x32_bf16 v[20:23], v[176:179], v[210:213], v[20:23]
	v_mfma_f32_16x16x32_bf16 v[16:19], v[184:187], v[210:213], v[16:19]
	v_mfma_f32_16x16x32_bf16 v[4:7], v[176:179], v[218:221], v[4:7]
	v_mfma_f32_16x16x32_bf16 v[0:3], v[184:187], v[218:221], v[0:3]
	s_barrier
	s_setprio 0
	s_add_u32 s68, s68, 0x100
	s_addc_u32 s69, s69, 0
	s_add_u32 s22, s22, 0x100
	s_addc_u32 s23, s23, 0
	s_cmp_ge_i32 s70, s1
	s_mov_b32 s26, s70
	s_cbranch_scc0 .LBB0_3613
	s_and_b64 vcc, exec, s[46:47]
	s_cbranch_vccz .LBB0_3616
	s_barrier

.LBB0_3760:
	s_or_b32 s40, s63, 1
	s_lshl_b64 s[80:81], s[40:41], 7
	s_add_i32 s40, s63, 2
	s_lshl_b64 s[82:83], s[40:41], 7
	v_add_u32_e32 v140, s30, v177
	v_add_u32_e32 v180, s31, v177
	s_add_u32 s79, s58, s82
	ds_read_b128 v[128:131], v140
	ds_read_b128 v[132:135], v140 offset:1024
	ds_read_b128 v[136:139], v140 offset:2048
	ds_read_b128 v[140:143], v140 offset:3072
	ds_read_b128 v[162:165], v180
	ds_read_b128 v[166:169], v180 offset:1024
	ds_read_b128 v[170:173], v180 offset:2048
	ds_read_b128 v[180:183], v180 offset:3072
	s_addc_u32 s84, s59, s83
	s_and_b64 s[70:71], s[68:69], exec
	s_cselect_b32 s71, s84, s51
	s_cselect_b32 s70, s79, s50
	s_add_u32 s79, s60, s82
	s_addc_u32 s82, s61, s83
	s_and_b64 s[68:69], s[68:69], exec
	s_cselect_b32 s69, s82, s53
	s_cselect_b32 s68, s79, s52
	s_add_u32 s79, s58, s80
	s_addc_u32 s81, s59, s81
	s_add_u32 s80, s79, 0x80000
	s_addc_u32 s81, s81, 0
	s_nop 0
	s_add_i32 m0, s7, 0xc000
	ds_read_b128 v[184:187], v152
	ds_read_b128 v[188:191], v152 offset:1024
	ds_read_b128 v[192:195], v152 offset:2048
	ds_read_b128 v[196:199], v152 offset:3072
	ds_read_b128 v[200:203], v152 offset:4096
	ds_read_b128 v[206:209], v152 offset:5120
	ds_read_b128 v[210:213], v152 offset:6144
	ds_read_b128 v[214:217], v152 offset:7168
	global_load_lds_dwordx4 v144, s[80:81]
	s_nop 0
	s_add_i32 m0, s7, 0xe000
	s_nop 0
	global_load_lds_dwordx4 v148, s[80:81]
	s_waitcnt vmcnt(8)
	s_waitcnt lgkmcnt(0)
	s_setprio 1
	s_barrier
	v_mfma_f32_16x16x32_bf16 v[124:127], v[128:131], v[184:187], v[124:127]
	v_mfma_f32_16x16x32_bf16 v[120:123], v[136:139], v[184:187], v[120:123]
	v_mfma_f32_16x16x32_bf16 v[112:115], v[128:131], v[192:195], v[112:115]
	v_mfma_f32_16x16x32_bf16 v[104:107], v[136:139], v[192:195], v[104:107]
	v_mfma_f32_16x16x32_bf16 v[96:99], v[128:131], v[200:203], v[96:99]
	v_mfma_f32_16x16x32_bf16 v[88:91], v[136:139], v[200:203], v[88:91]
	v_mfma_f32_16x16x32_bf16 v[80:83], v[128:131], v[210:213], v[80:83]
	v_mfma_f32_16x16x32_bf16 v[72:75], v[136:139], v[210:213], v[72:75]
	v_mfma_f32_16x16x32_bf16 v[124:127], v[132:135], v[188:191], v[124:127]
	v_mfma_f32_16x16x32_bf16 v[120:123], v[140:143], v[188:191], v[120:123]
	v_mfma_f32_16x16x32_bf16 v[112:115], v[132:135], v[196:199], v[112:115]
	v_mfma_f32_16x16x32_bf16 v[104:107], v[140:143], v[196:199], v[104:107]
	v_mfma_f32_16x16x32_bf16 v[96:99], v[132:135], v[206:209], v[96:99]
	v_mfma_f32_16x16x32_bf16 v[88:91], v[140:143], v[206:209], v[88:91]
	v_mfma_f32_16x16x32_bf16 v[80:83], v[132:135], v[214:217], v[80:83]
	v_mfma_f32_16x16x32_bf16 v[72:75], v[140:143], v[214:217], v[72:75]
	v_mfma_f32_16x16x32_bf16 v[116:119], v[162:165], v[184:187], v[116:119]
	v_mfma_f32_16x16x32_bf16 v[108:111], v[170:173], v[184:187], v[108:111]
	v_mfma_f32_16x16x32_bf16 v[100:103], v[162:165], v[192:195], v[100:103]
	v_mfma_f32_16x16x32_bf16 v[92:95], v[170:173], v[192:195], v[92:95]
	v_mfma_f32_16x16x32_bf16 v[84:87], v[162:165], v[200:203], v[84:87]
	v_mfma_f32_16x16x32_bf16 v[76:79], v[170:173], v[200:203], v[76:79]
	v_mfma_f32_16x16x32_bf16 v[68:71], v[162:165], v[210:213], v[68:71]
	v_mfma_f32_16x16x32_bf16 v[64:67], v[170:173], v[210:213], v[64:67]
	v_mfma_f32_16x16x32_bf16 v[116:119], v[166:169], v[188:191], v[116:119]
	v_mfma_f32_16x16x32_bf16 v[108:111], v[180:183], v[188:191], v[108:111]
	v_mfma_f32_16x16x32_bf16 v[100:103], v[166:169], v[196:199], v[100:103]
	v_mfma_f32_16x16x32_bf16 v[92:95], v[180:183], v[196:199], v[92:95]
	v_mfma_f32_16x16x32_bf16 v[84:87], v[166:169], v[206:209], v[84:87]
	v_mfma_f32_16x16x32_bf16 v[76:79], v[180:183], v[206:209], v[76:79]
	v_mfma_f32_16x16x32_bf16 v[68:71], v[166:169], v[214:217], v[68:71]
	v_mfma_f32_16x16x32_bf16 v[64:67], v[180:183], v[214:217], v[64:67]
	s_barrier
	s_setprio 0
	s_add_i32 s79, s30, s6
	v_lshl_add_u64 v[218:219], s[68:69], 0, v[146:147]
	s_mov_b32 m0, s79
	ds_read_b128 v[184:187], v152 offset:16384
	ds_read_b128 v[188:191], v152 offset:17408
	ds_read_b128 v[192:195], v152 offset:18432
	ds_read_b128 v[196:199], v152 offset:19456
	ds_read_b128 v[200:203], v152 offset:20480
	ds_read_b128 v[206:209], v152 offset:21504
	ds_read_b128 v[210:213], v152 offset:22528
	ds_read_b128 v[214:217], v152 offset:23552
	global_load_lds_dwordx4 v[218:219], off
	s_add_i32 m0, s79, 0x2000
	s_add_u32 s80, s68, 0x80000
	v_lshl_add_u64 v[220:221], s[68:69], 0, v[150:151]
	s_addc_u32 s81, s69, 0
	s_add_i32 s79, s31, s6
	global_load_lds_dwordx4 v[220:221], off
	s_nop 0
	s_mov_b32 m0, s79
	v_lshl_add_u64 v[224:225], s[70:71], 0, v[148:149]
	global_load_lds_dwordx4 v146, s[80:81]
	s_nop 0
	s_add_i32 m0, s79, 0x2000
	s_nop 0
	global_load_lds_dwordx4 v150, s[80:81]
	v_lshl_add_u64 v[222:223], s[70:71], 0, v[144:145]
	s_mov_b32 m0, s7
	s_nop 0
	global_load_lds_dwordx4 v[222:223], off
	s_mov_b32 m0, s8
	s_nop 0
	global_load_lds_dwordx4 v[224:225], off
	s_waitcnt vmcnt(8)
	s_waitcnt lgkmcnt(0)
	s_setprio 1
	s_barrier
	v_mfma_f32_16x16x32_bf16 v[60:63], v[128:131], v[184:187], v[60:63]
	v_mfma_f32_16x16x32_bf16 v[56:59], v[136:139], v[184:187], v[56:59]
	v_mfma_f32_16x16x32_bf16 v[48:51], v[128:131], v[192:195], v[48:51]
	v_mfma_f32_16x16x32_bf16 v[32:35], v[136:139], v[192:195], v[32:35]
	v_mfma_f32_16x16x32_bf16 v[16:19], v[128:131], v[200:203], v[16:19]
	v_mfma_f32_16x16x32_bf16 v[12:15], v[136:139], v[200:203], v[12:15]
	v_mfma_f32_16x16x32_bf16 v[4:7], v[128:131], v[210:213], v[4:7]
	v_mfma_f32_16x16x32_bf16 v[0:3], v[136:139], v[210:213], v[0:3]
	v_mfma_f32_16x16x32_bf16 v[60:63], v[132:135], v[188:191], v[60:63]
	v_mfma_f32_16x16x32_bf16 v[56:59], v[140:143], v[188:191], v[56:59]
	v_mfma_f32_16x16x32_bf16 v[48:51], v[132:135], v[196:199], v[48:51]
	v_mfma_f32_16x16x32_bf16 v[32:35], v[140:143], v[196:199], v[32:35]
	v_mfma_f32_16x16x32_bf16 v[16:19], v[132:135], v[206:209], v[16:19]
	v_mfma_f32_16x16x32_bf16 v[12:15], v[140:143], v[206:209], v[12:15]
	v_mfma_f32_16x16x32_bf16 v[4:7], v[132:135], v[214:217], v[4:7]
	v_mfma_f32_16x16x32_bf16 v[0:3], v[140:143], v[214:217], v[0:3]
	v_mfma_f32_16x16x32_bf16 v[52:55], v[162:165], v[184:187], v[52:55]
	v_mfma_f32_16x16x32_bf16 v[36:39], v[170:173], v[184:187], v[36:39]
	v_mfma_f32_16x16x32_bf16 v[20:23], v[162:165], v[192:195], v[20:23]
	v_mfma_f32_16x16x32_bf16 v[8:11], v[170:173], v[192:195], v[8:11]
	v_mfma_f32_16x16x32_bf16 v[40:43], v[162:165], v[200:203], v[40:43]
	v_mfma_f32_16x16x32_bf16 v[44:47], v[170:173], v[200:203], v[44:47]
	v_mfma_f32_16x16x32_bf16 v[24:27], v[162:165], v[210:213], v[24:27]
	v_mfma_f32_16x16x32_bf16 v[28:31], v[170:173], v[210:213], v[28:31]
	v_mfma_f32_16x16x32_bf16 v[52:55], v[166:169], v[188:191], v[52:55]
	v_mfma_f32_16x16x32_bf16 v[36:39], v[180:183], v[188:191], v[36:39]
	v_mfma_f32_16x16x32_bf16 v[20:23], v[166:169], v[196:199], v[20:23]
	v_mfma_f32_16x16x32_bf16 v[8:11], v[180:183], v[196:199], v[8:11]
	v_mfma_f32_16x16x32_bf16 v[40:43], v[166:169], v[206:209], v[40:43]
	v_mfma_f32_16x16x32_bf16 v[44:47], v[180:183], v[206:209], v[44:47]
	v_mfma_f32_16x16x32_bf16 v[24:27], v[166:169], v[214:217], v[24:27]
	v_mfma_f32_16x16x32_bf16 v[28:31], v[180:183], v[214:217], v[28:31]
	s_barrier
	s_setprio 0
	v_add_u32_e32 v140, s55, v177
	v_add_u32_e32 v180, s57, v177
	ds_read_b128 v[128:131], v140
	ds_read_b128 v[132:135], v140 offset:1024
	ds_read_b128 v[136:139], v140 offset:2048
	ds_read_b128 v[140:143], v140 offset:3072
	ds_read_b128 v[162:165], v180
	ds_read_b128 v[166:169], v180 offset:1024
	ds_read_b128 v[170:173], v180 offset:2048
	ds_read_b128 v[180:183], v180 offset:3072
	s_add_u32 s70, s70, 0x80000
	s_addc_u32 s71, s71, 0
	s_mov_b32 m0, s9
	s_nop 0
	ds_read_b128 v[184:187], v152 offset:32768
	ds_read_b128 v[188:191], v152 offset:33792
	ds_read_b128 v[192:195], v152 offset:34816
	ds_read_b128 v[196:199], v152 offset:35840
	ds_read_b128 v[200:203], v152 offset:36864
	ds_read_b128 v[206:209], v152 offset:37888
	ds_read_b128 v[210:213], v152 offset:38912
	ds_read_b128 v[214:217], v152 offset:39936
	global_load_lds_dwordx4 v144, s[70:71]
	s_nop 0
	s_mov_b32 m0, s10
	s_nop 0
	global_load_lds_dwordx4 v148, s[70:71]
	s_waitcnt vmcnt(8)
	s_waitcnt lgkmcnt(0)
	s_setprio 1
	s_barrier
	v_mfma_f32_16x16x32_bf16 v[124:127], v[128:131], v[184:187], v[124:127]
	v_mfma_f32_16x16x32_bf16 v[120:123], v[136:139], v[184:187], v[120:123]
	v_mfma_f32_16x16x32_bf16 v[112:115], v[128:131], v[192:195], v[112:115]
	v_mfma_f32_16x16x32_bf16 v[104:107], v[136:139], v[192:195], v[104:107]
	v_mfma_f32_16x16x32_bf16 v[96:99], v[128:131], v[200:203], v[96:99]
	v_mfma_f32_16x16x32_bf16 v[88:91], v[136:139], v[200:203], v[88:91]
	v_mfma_f32_16x16x32_bf16 v[80:83], v[128:131], v[210:213], v[80:83]
	v_mfma_f32_16x16x32_bf16 v[72:75], v[136:139], v[210:213], v[72:75]
	v_mfma_f32_16x16x32_bf16 v[124:127], v[132:135], v[188:191], v[124:127]
	v_mfma_f32_16x16x32_bf16 v[120:123], v[140:143], v[188:191], v[120:123]
	v_mfma_f32_16x16x32_bf16 v[112:115], v[132:135], v[196:199], v[112:115]
	v_mfma_f32_16x16x32_bf16 v[104:107], v[140:143], v[196:199], v[104:107]
	v_mfma_f32_16x16x32_bf16 v[96:99], v[132:135], v[206:209], v[96:99]
	v_mfma_f32_16x16x32_bf16 v[88:91], v[140:143], v[206:209], v[88:91]
	v_mfma_f32_16x16x32_bf16 v[80:83], v[132:135], v[214:217], v[80:83]
	v_mfma_f32_16x16x32_bf16 v[72:75], v[140:143], v[214:217], v[72:75]
	v_mfma_f32_16x16x32_bf16 v[116:119], v[162:165], v[184:187], v[116:119]
	v_mfma_f32_16x16x32_bf16 v[108:111], v[170:173], v[184:187], v[108:111]
	v_mfma_f32_16x16x32_bf16 v[100:103], v[162:165], v[192:195], v[100:103]
	v_mfma_f32_16x16x32_bf16 v[92:95], v[170:173], v[192:195], v[92:95]
	v_mfma_f32_16x16x32_bf16 v[84:87], v[162:165], v[200:203], v[84:87]
	v_mfma_f32_16x16x32_bf16 v[76:79], v[170:173], v[200:203], v[76:79]
	v_mfma_f32_16x16x32_bf16 v[68:71], v[162:165], v[210:213], v[68:71]
	v_mfma_f32_16x16x32_bf16 v[64:67], v[170:173], v[210:213], v[64:67]
	v_mfma_f32_16x16x32_bf16 v[116:119], v[166:169], v[188:191], v[116:119]
	v_mfma_f32_16x16x32_bf16 v[108:111], v[180:183], v[188:191], v[108:111]
	v_mfma_f32_16x16x32_bf16 v[100:103], v[166:169], v[196:199], v[100:103]
	v_mfma_f32_16x16x32_bf16 v[92:95], v[180:183], v[196:199], v[92:95]
	v_mfma_f32_16x16x32_bf16 v[84:87], v[166:169], v[206:209], v[84:87]
	v_mfma_f32_16x16x32_bf16 v[76:79], v[180:183], v[206:209], v[76:79]
	v_mfma_f32_16x16x32_bf16 v[68:71], v[166:169], v[214:217], v[68:71]
	v_mfma_f32_16x16x32_bf16 v[64:67], v[180:183], v[214:217], v[64:67]
	s_barrier
	s_setprio 0
	s_add_i32 s70, s55, s6
	s_nop 0
	s_add_i32 m0, s70, 0xffffff80
	ds_read_b128 v[184:187], v152 offset:49152
	ds_read_b128 v[188:191], v152 offset:50176
	ds_read_b128 v[192:195], v152 offset:51200
	ds_read_b128 v[196:199], v152 offset:52224
	ds_read_b128 v[200:203], v152 offset:53248
	ds_read_b128 v[206:209], v152 offset:54272
	ds_read_b128 v[210:213], v152 offset:55296
	ds_read_b128 v[214:217], v152 offset:56320
	global_load_lds_dwordx4 v[218:219], off offset:128
	s_add_i32 m0, s70, 0x1f80
	s_add_u32 s68, s68, 0x80080
	s_nop 0
	s_addc_u32 s69, s69, 0
	s_add_i32 s70, s57, s6
	global_load_lds_dwordx4 v[220:221], off offset:128
	s_nop 0
	s_mov_b32 m0, s70
	s_nop 0
	global_load_lds_dwordx4 v146, s[68:69]
	s_nop 0
	s_add_i32 m0, s70, 0x2000
	s_nop 0
	global_load_lds_dwordx4 v150, s[68:69]
	s_nop 0
	s_add_i32 m0, s11, 0xffffff80
	s_nop 0
	global_load_lds_dwordx4 v[222:223], off offset:128
	s_nop 0
	s_add_i32 m0, s12, 0xffffff80
	s_nop 0
	global_load_lds_dwordx4 v[224:225], off offset:128
	s_waitcnt vmcnt(8)
	s_waitcnt lgkmcnt(0)
	s_setprio 1
	s_barrier
	v_mfma_f32_16x16x32_bf16 v[60:63], v[128:131], v[184:187], v[60:63]
	v_mfma_f32_16x16x32_bf16 v[56:59], v[136:139], v[184:187], v[56:59]
	v_mfma_f32_16x16x32_bf16 v[48:51], v[128:131], v[192:195], v[48:51]
	v_mfma_f32_16x16x32_bf16 v[32:35], v[136:139], v[192:195], v[32:35]
	v_mfma_f32_16x16x32_bf16 v[16:19], v[128:131], v[200:203], v[16:19]
	v_mfma_f32_16x16x32_bf16 v[12:15], v[136:139], v[200:203], v[12:15]
	v_mfma_f32_16x16x32_bf16 v[4:7], v[128:131], v[210:213], v[4:7]
	v_mfma_f32_16x16x32_bf16 v[0:3], v[136:139], v[210:213], v[0:3]
	v_mfma_f32_16x16x32_bf16 v[60:63], v[132:135], v[188:191], v[60:63]
	v_mfma_f32_16x16x32_bf16 v[56:59], v[140:143], v[188:191], v[56:59]
	v_mfma_f32_16x16x32_bf16 v[48:51], v[132:135], v[196:199], v[48:51]
	v_mfma_f32_16x16x32_bf16 v[32:35], v[140:143], v[196:199], v[32:35]
	v_mfma_f32_16x16x32_bf16 v[16:19], v[132:135], v[206:209], v[16:19]
	v_mfma_f32_16x16x32_bf16 v[12:15], v[140:143], v[206:209], v[12:15]
	v_mfma_f32_16x16x32_bf16 v[4:7], v[132:135], v[214:217], v[4:7]
	v_mfma_f32_16x16x32_bf16 v[0:3], v[140:143], v[214:217], v[0:3]
	v_mfma_f32_16x16x32_bf16 v[52:55], v[162:165], v[184:187], v[52:55]
	v_mfma_f32_16x16x32_bf16 v[36:39], v[170:173], v[184:187], v[36:39]
	v_mfma_f32_16x16x32_bf16 v[20:23], v[162:165], v[192:195], v[20:23]
	v_mfma_f32_16x16x32_bf16 v[8:11], v[170:173], v[192:195], v[8:11]
	v_mfma_f32_16x16x32_bf16 v[40:43], v[162:165], v[200:203], v[40:43]
	v_mfma_f32_16x16x32_bf16 v[44:47], v[170:173], v[200:203], v[44:47]
	v_mfma_f32_16x16x32_bf16 v[24:27], v[162:165], v[210:213], v[24:27]
	v_mfma_f32_16x16x32_bf16 v[28:31], v[170:173], v[210:213], v[28:31]
	v_mfma_f32_16x16x32_bf16 v[52:55], v[166:169], v[188:191], v[52:55]
	v_mfma_f32_16x16x32_bf16 v[36:39], v[180:183], v[188:191], v[36:39]
	v_mfma_f32_16x16x32_bf16 v[20:23], v[166:169], v[196:199], v[20:23]
	v_mfma_f32_16x16x32_bf16 v[8:11], v[180:183], v[196:199], v[8:11]
	v_mfma_f32_16x16x32_bf16 v[40:43], v[166:169], v[206:209], v[40:43]
	v_mfma_f32_16x16x32_bf16 v[44:47], v[180:183], v[206:209], v[44:47]
	v_mfma_f32_16x16x32_bf16 v[24:27], v[166:169], v[214:217], v[24:27]
	v_mfma_f32_16x16x32_bf16 v[28:31], v[180:183], v[214:217], v[28:31]
	s_barrier
	s_setprio 0
	s_cmp_gt_u32 s63, 29
	s_cbranch_scc1 .LBB0_3762
	s_mov_b32 s63, s40
	s_branch .LBB0_3748

.LBB0_6333:
	s_or_b32 s62, s23, 1
	s_lshl_b64 vcc, s[62:63], 7
	s_add_i32 s62, s23, 2
	s_lshl_b64 s[76:77], s[62:63], 7
	v_add_u32_e32 v12, s53, v201
	v_add_u32_e32 v157, s57, v201
	s_add_u32 s28, s0, s76
	ds_read_b128 v[0:3], v12
	ds_read_b128 v[4:7], v12 offset:1024
	ds_read_b128 v[8:11], v12 offset:2048
	ds_read_b128 v[12:15], v12 offset:3072
	ds_read_b128 v[144:147], v157
	ds_read_b128 v[166:169], v157 offset:1024
	ds_read_b128 v[170:173], v157 offset:2048
	ds_read_b128 v[174:177], v157 offset:3072
	s_addc_u32 s93, s1, s77
	s_and_b64 s[44:45], s[42:43], exec
	s_cselect_b32 s45, s93, s81
	s_cselect_b32 s44, s28, s80
	s_add_u32 s28, s20, s76
	s_addc_u32 s76, s21, s77
	s_and_b64 s[42:43], s[42:43], exec
	s_cselect_b32 s43, s76, s83
	s_cselect_b32 s42, s28, s82
	s_add_u32 s28, s0, vcc_lo
	s_addc_u32 s77, s1, vcc_hi
	s_add_u32 s76, s28, 0x80000
	s_addc_u32 s77, s77, 0
	s_nop 0
	s_add_i32 m0, s5, 0xc000
	ds_read_b128 v[178:181], v209
	ds_read_b128 v[182:185], v209 offset:1024
	ds_read_b128 v[186:189], v209 offset:2048
	ds_read_b128 v[190:193], v209 offset:3072
	ds_read_b128 v[194:197], v209 offset:4096
	ds_read_b128 v[212:215], v209 offset:5120
	ds_read_b128 v[216:219], v209 offset:6144
	ds_read_b128 v[220:223], v209 offset:7168
	global_load_lds_dwordx4 v148, s[76:77]
	s_nop 0
	s_add_i32 m0, s5, 0xe000
	s_nop 0
	global_load_lds_dwordx4 v152, s[76:77]
	s_waitcnt vmcnt(8)
	s_waitcnt lgkmcnt(0)
	s_setprio 1
	s_barrier
	v_mfma_f32_16x16x32_bf16 v[108:111], v[0:3], v[178:181], v[108:111]
	v_mfma_f32_16x16x32_bf16 v[104:107], v[8:11], v[178:181], v[104:107]
	v_mfma_f32_16x16x32_bf16 v[124:127], v[0:3], v[186:189], v[124:127]
	v_mfma_f32_16x16x32_bf16 v[116:119], v[8:11], v[186:189], v[116:119]
	v_mfma_f32_16x16x32_bf16 v[120:123], v[0:3], v[194:197], v[120:123]
	v_mfma_f32_16x16x32_bf16 v[112:115], v[8:11], v[194:197], v[112:115]
	v_mfma_f32_16x16x32_bf16 v[92:95], v[0:3], v[216:219], v[92:95]
	v_mfma_f32_16x16x32_bf16 v[88:91], v[8:11], v[216:219], v[88:91]
	v_mfma_f32_16x16x32_bf16 v[108:111], v[4:7], v[182:185], v[108:111]
	v_mfma_f32_16x16x32_bf16 v[104:107], v[12:15], v[182:185], v[104:107]
	v_mfma_f32_16x16x32_bf16 v[124:127], v[4:7], v[190:193], v[124:127]
	v_mfma_f32_16x16x32_bf16 v[116:119], v[12:15], v[190:193], v[116:119]
	v_mfma_f32_16x16x32_bf16 v[120:123], v[4:7], v[212:215], v[120:123]
	v_mfma_f32_16x16x32_bf16 v[112:115], v[12:15], v[212:215], v[112:115]
	v_mfma_f32_16x16x32_bf16 v[92:95], v[4:7], v[220:223], v[92:95]
	v_mfma_f32_16x16x32_bf16 v[88:91], v[12:15], v[220:223], v[88:91]
	v_mfma_f32_16x16x32_bf16 v[140:143], v[144:147], v[178:181], v[140:143]
	v_mfma_f32_16x16x32_bf16 v[136:139], v[170:173], v[178:181], v[136:139]
	v_mfma_f32_16x16x32_bf16 v[132:135], v[144:147], v[186:189], v[132:135]
	v_mfma_f32_16x16x32_bf16 v[128:131], v[170:173], v[186:189], v[128:131]
	v_mfma_f32_16x16x32_bf16 v[100:103], v[144:147], v[194:197], v[100:103]
	v_mfma_f32_16x16x32_bf16 v[96:99], v[170:173], v[194:197], v[96:99]
	v_mfma_f32_16x16x32_bf16 v[84:87], v[144:147], v[216:219], v[84:87]
	v_mfma_f32_16x16x32_bf16 v[80:83], v[170:173], v[216:219], v[80:83]
	v_mfma_f32_16x16x32_bf16 v[140:143], v[166:169], v[182:185], v[140:143]
	v_mfma_f32_16x16x32_bf16 v[136:139], v[174:177], v[182:185], v[136:139]
	v_mfma_f32_16x16x32_bf16 v[132:135], v[166:169], v[190:193], v[132:135]
	v_mfma_f32_16x16x32_bf16 v[128:131], v[174:177], v[190:193], v[128:131]
	v_mfma_f32_16x16x32_bf16 v[100:103], v[166:169], v[212:215], v[100:103]
	v_mfma_f32_16x16x32_bf16 v[96:99], v[174:177], v[212:215], v[96:99]
	v_mfma_f32_16x16x32_bf16 v[84:87], v[166:169], v[220:223], v[84:87]
	v_mfma_f32_16x16x32_bf16 v[80:83], v[174:177], v[220:223], v[80:83]
	s_barrier
	s_setprio 0
	s_add_i32 s28, s53, s4
	v_lshl_add_u64 v[224:225], s[42:43], 0, v[150:151]
	s_mov_b32 m0, s28
	ds_read_b128 v[178:181], v209 offset:16384
	ds_read_b128 v[182:185], v209 offset:17408
	ds_read_b128 v[186:189], v209 offset:18432
	ds_read_b128 v[190:193], v209 offset:19456
	ds_read_b128 v[194:197], v209 offset:20480
	ds_read_b128 v[212:215], v209 offset:21504
	ds_read_b128 v[216:219], v209 offset:22528
	ds_read_b128 v[220:223], v209 offset:23552
	global_load_lds_dwordx4 v[224:225], off
	s_add_i32 m0, s28, 0x2000
	s_add_u32 s76, s42, 0x80000
	v_lshl_add_u64 v[226:227], s[42:43], 0, v[154:155]
	s_addc_u32 s77, s43, 0
	s_add_i32 s28, s57, s4
	global_load_lds_dwordx4 v[226:227], off
	s_nop 0
	s_mov_b32 m0, s28
	v_lshl_add_u64 v[230:231], s[44:45], 0, v[152:153]
	global_load_lds_dwordx4 v150, s[76:77]
	s_nop 0
	s_add_i32 m0, s28, 0x2000
	s_nop 0
	global_load_lds_dwordx4 v154, s[76:77]
	v_lshl_add_u64 v[228:229], s[44:45], 0, v[148:149]
	s_mov_b32 m0, s5
	s_nop 0
	global_load_lds_dwordx4 v[228:229], off
	s_mov_b32 m0, s6
	s_nop 0
	global_load_lds_dwordx4 v[230:231], off
	s_waitcnt vmcnt(8)
	s_waitcnt lgkmcnt(0)
	s_setprio 1
	s_barrier
	v_mfma_f32_16x16x32_bf16 v[76:79], v[0:3], v[178:181], v[76:79]
	v_mfma_f32_16x16x32_bf16 v[72:75], v[8:11], v[178:181], v[72:75]
	v_mfma_f32_16x16x32_bf16 v[60:63], v[0:3], v[186:189], v[60:63]
	v_mfma_f32_16x16x32_bf16 v[56:59], v[8:11], v[186:189], v[56:59]
	v_mfma_f32_16x16x32_bf16 v[44:47], v[0:3], v[194:197], v[44:47]
	v_mfma_f32_16x16x32_bf16 v[40:43], v[8:11], v[194:197], v[40:43]
	v_mfma_f32_16x16x32_bf16 v[0:3], v[0:3], v[216:219], v[28:31]
	v_mfma_f32_16x16x32_bf16 v[76:79], v[4:7], v[182:185], v[76:79]
	v_mfma_f32_16x16x32_bf16 v[72:75], v[12:15], v[182:185], v[72:75]
	v_mfma_f32_16x16x32_bf16 v[60:63], v[4:7], v[190:193], v[60:63]
	v_mfma_f32_16x16x32_bf16 v[56:59], v[12:15], v[190:193], v[56:59]
	v_mfma_f32_16x16x32_bf16 v[44:47], v[4:7], v[212:215], v[44:47]
	v_mfma_f32_16x16x32_bf16 v[40:43], v[12:15], v[212:215], v[40:43]
	v_mfma_f32_16x16x32_bf16 v[0:3], v[4:7], v[220:223], v[0:3]
	v_mfma_f32_16x16x32_bf16 v[4:7], v[8:11], v[216:219], v[20:23]
	v_mfma_f32_16x16x32_bf16 v[4:7], v[12:15], v[220:223], v[4:7]
	v_mfma_f32_16x16x32_bf16 v[20:23], v[144:147], v[186:189], v[52:55]
	v_mfma_f32_16x16x32_bf16 v[52:55], v[166:169], v[190:193], v[20:23]
	v_mfma_f32_16x16x32_bf16 v[20:23], v[170:173], v[186:189], v[48:51]
	v_mfma_f32_16x16x32_bf16 v[48:51], v[174:177], v[190:193], v[20:23]
	v_mfma_f32_16x16x32_bf16 v[20:23], v[144:147], v[194:197], v[36:39]
	v_mfma_f32_16x16x32_bf16 v[36:39], v[166:169], v[212:215], v[20:23]
	v_mfma_f32_16x16x32_bf16 v[20:23], v[170:173], v[194:197], v[32:35]
	v_mfma_f32_16x16x32_bf16 v[32:35], v[174:177], v[212:215], v[20:23]
	v_mfma_f32_16x16x32_bf16 v[20:23], v[144:147], v[216:219], v[24:27]
	v_mfma_f32_16x16x32_bf16 v[16:19], v[170:173], v[216:219], v[16:19]
	v_mfma_f32_16x16x32_bf16 v[8:11], v[144:147], v[178:181], v[68:71]
	v_mfma_f32_16x16x32_bf16 v[12:15], v[170:173], v[178:181], v[64:67]
	v_mfma_f32_16x16x32_bf16 v[24:27], v[166:169], v[220:223], v[20:23]
	v_mfma_f32_16x16x32_bf16 v[16:19], v[174:177], v[220:223], v[16:19]
	v_mfma_f32_16x16x32_bf16 v[8:11], v[166:169], v[182:185], v[8:11]
	v_mfma_f32_16x16x32_bf16 v[12:15], v[174:177], v[182:185], v[12:15]
	s_barrier
	s_setprio 0
	v_add_u32_e32 v68, s86, v201
	v_add_u32_e32 v157, s87, v201
	ds_read_b128 v[20:23], v68
	ds_read_b128 v[28:31], v68 offset:1024
	ds_read_b128 v[64:67], v68 offset:2048
	ds_read_b128 v[68:71], v68 offset:3072
	ds_read_b128 v[144:147], v157
	ds_read_b128 v[166:169], v157 offset:1024
	ds_read_b128 v[170:173], v157 offset:2048
	ds_read_b128 v[174:177], v157 offset:3072
	s_add_u32 s44, s44, 0x80000
	s_addc_u32 s45, s45, 0
	s_mov_b32 m0, s7
	s_nop 0
	ds_read_b128 v[178:181], v209 offset:32768
	ds_read_b128 v[182:185], v209 offset:33792
	ds_read_b128 v[186:189], v209 offset:34816
	ds_read_b128 v[190:193], v209 offset:35840
	ds_read_b128 v[194:197], v209 offset:36864
	ds_read_b128 v[212:215], v209 offset:37888
	ds_read_b128 v[216:219], v209 offset:38912
	ds_read_b128 v[220:223], v209 offset:39936
	global_load_lds_dwordx4 v148, s[44:45]
	s_nop 0
	s_mov_b32 m0, s8
	s_nop 0
	global_load_lds_dwordx4 v152, s[44:45]
	s_waitcnt vmcnt(8)
	s_waitcnt lgkmcnt(0)
	s_setprio 1
	s_barrier
	v_mfma_f32_16x16x32_bf16 v[108:111], v[20:23], v[178:181], v[108:111]
	v_mfma_f32_16x16x32_bf16 v[104:107], v[64:67], v[178:181], v[104:107]
	v_mfma_f32_16x16x32_bf16 v[124:127], v[20:23], v[186:189], v[124:127]
	v_mfma_f32_16x16x32_bf16 v[116:119], v[64:67], v[186:189], v[116:119]
	v_mfma_f32_16x16x32_bf16 v[120:123], v[20:23], v[194:197], v[120:123]
	v_mfma_f32_16x16x32_bf16 v[112:115], v[64:67], v[194:197], v[112:115]
	v_mfma_f32_16x16x32_bf16 v[92:95], v[20:23], v[216:219], v[92:95]
	v_mfma_f32_16x16x32_bf16 v[88:91], v[64:67], v[216:219], v[88:91]
	v_mfma_f32_16x16x32_bf16 v[108:111], v[28:31], v[182:185], v[108:111]
	v_mfma_f32_16x16x32_bf16 v[104:107], v[68:71], v[182:185], v[104:107]
	v_mfma_f32_16x16x32_bf16 v[124:127], v[28:31], v[190:193], v[124:127]
	v_mfma_f32_16x16x32_bf16 v[116:119], v[68:71], v[190:193], v[116:119]
	v_mfma_f32_16x16x32_bf16 v[120:123], v[28:31], v[212:215], v[120:123]
	v_mfma_f32_16x16x32_bf16 v[112:115], v[68:71], v[212:215], v[112:115]
	v_mfma_f32_16x16x32_bf16 v[92:95], v[28:31], v[220:223], v[92:95]
	v_mfma_f32_16x16x32_bf16 v[88:91], v[68:71], v[220:223], v[88:91]
	v_mfma_f32_16x16x32_bf16 v[140:143], v[144:147], v[178:181], v[140:143]
	v_mfma_f32_16x16x32_bf16 v[136:139], v[170:173], v[178:181], v[136:139]
	v_mfma_f32_16x16x32_bf16 v[132:135], v[144:147], v[186:189], v[132:135]
	v_mfma_f32_16x16x32_bf16 v[128:131], v[170:173], v[186:189], v[128:131]
	v_mfma_f32_16x16x32_bf16 v[100:103], v[144:147], v[194:197], v[100:103]
	v_mfma_f32_16x16x32_bf16 v[96:99], v[170:173], v[194:197], v[96:99]
	v_mfma_f32_16x16x32_bf16 v[84:87], v[144:147], v[216:219], v[84:87]
	v_mfma_f32_16x16x32_bf16 v[80:83], v[170:173], v[216:219], v[80:83]
	v_mfma_f32_16x16x32_bf16 v[140:143], v[166:169], v[182:185], v[140:143]
	v_mfma_f32_16x16x32_bf16 v[136:139], v[174:177], v[182:185], v[136:139]
	v_mfma_f32_16x16x32_bf16 v[132:135], v[166:169], v[190:193], v[132:135]
	v_mfma_f32_16x16x32_bf16 v[128:131], v[174:177], v[190:193], v[128:131]
	v_mfma_f32_16x16x32_bf16 v[100:103], v[166:169], v[212:215], v[100:103]
	v_mfma_f32_16x16x32_bf16 v[96:99], v[174:177], v[212:215], v[96:99]
	v_mfma_f32_16x16x32_bf16 v[84:87], v[166:169], v[220:223], v[84:87]
	v_mfma_f32_16x16x32_bf16 v[80:83], v[174:177], v[220:223], v[80:83]
	s_barrier
	s_setprio 0
	s_add_i32 s28, s86, s4
	s_nop 0
	s_add_i32 m0, s28, 0xffffff80
	ds_read_b128 v[178:181], v209 offset:49152
	ds_read_b128 v[182:185], v209 offset:50176
	ds_read_b128 v[186:189], v209 offset:51200
	ds_read_b128 v[190:193], v209 offset:52224
	ds_read_b128 v[194:197], v209 offset:53248
	ds_read_b128 v[212:215], v209 offset:54272
	ds_read_b128 v[216:219], v209 offset:55296
	ds_read_b128 v[220:223], v209 offset:56320
	global_load_lds_dwordx4 v[224:225], off offset:128
	s_add_i32 m0, s28, 0x1f80
	s_add_u32 s42, s42, 0x80080
	s_nop 0
	s_addc_u32 s43, s43, 0
	s_add_i32 s28, s87, s4
	global_load_lds_dwordx4 v[226:227], off offset:128
	s_nop 0
	s_mov_b32 m0, s28
	s_nop 0
	global_load_lds_dwordx4 v150, s[42:43]
	s_nop 0
	s_add_i32 m0, s28, 0x2000
	s_nop 0
	global_load_lds_dwordx4 v154, s[42:43]
	s_nop 0
	s_add_i32 m0, s9, 0xffffff80
	s_nop 0
	global_load_lds_dwordx4 v[228:229], off offset:128
	s_nop 0
	s_add_i32 m0, s10, 0xffffff80
	s_nop 0
	global_load_lds_dwordx4 v[230:231], off offset:128
	s_waitcnt vmcnt(8)
	s_waitcnt lgkmcnt(0)
	s_setprio 1
	s_barrier
	v_mfma_f32_16x16x32_bf16 v[76:79], v[20:23], v[178:181], v[76:79]
	v_mfma_f32_16x16x32_bf16 v[60:63], v[20:23], v[186:189], v[60:63]
	v_mfma_f32_16x16x32_bf16 v[44:47], v[20:23], v[194:197], v[44:47]
	v_mfma_f32_16x16x32_bf16 v[0:3], v[20:23], v[216:219], v[0:3]
	v_mfma_f32_16x16x32_bf16 v[76:79], v[28:31], v[182:185], v[76:79]
	v_mfma_f32_16x16x32_bf16 v[72:75], v[64:67], v[178:181], v[72:75]
	v_mfma_f32_16x16x32_bf16 v[60:63], v[28:31], v[190:193], v[60:63]
	v_mfma_f32_16x16x32_bf16 v[56:59], v[64:67], v[186:189], v[56:59]
	v_mfma_f32_16x16x32_bf16 v[44:47], v[28:31], v[212:215], v[44:47]
	v_mfma_f32_16x16x32_bf16 v[40:43], v[64:67], v[194:197], v[40:43]
	v_mfma_f32_16x16x32_bf16 v[28:31], v[28:31], v[220:223], v[0:3]
	v_mfma_f32_16x16x32_bf16 v[0:3], v[64:67], v[216:219], v[4:7]
	v_mfma_f32_16x16x32_bf16 v[72:75], v[68:71], v[182:185], v[72:75]
	v_mfma_f32_16x16x32_bf16 v[56:59], v[68:71], v[190:193], v[56:59]
	v_mfma_f32_16x16x32_bf16 v[40:43], v[68:71], v[212:215], v[40:43]
	v_mfma_f32_16x16x32_bf16 v[20:23], v[68:71], v[220:223], v[0:3]
	v_mfma_f32_16x16x32_bf16 v[0:3], v[144:147], v[178:181], v[8:11]
	v_mfma_f32_16x16x32_bf16 v[68:71], v[166:169], v[182:185], v[0:3]
	v_mfma_f32_16x16x32_bf16 v[0:3], v[170:173], v[178:181], v[12:15]
	v_mfma_f32_16x16x32_bf16 v[64:67], v[174:177], v[182:185], v[0:3]
	v_mfma_f32_16x16x32_bf16 v[0:3], v[144:147], v[186:189], v[52:55]
	v_mfma_f32_16x16x32_bf16 v[52:55], v[166:169], v[190:193], v[0:3]
	v_mfma_f32_16x16x32_bf16 v[0:3], v[170:173], v[186:189], v[48:51]
	v_mfma_f32_16x16x32_bf16 v[48:51], v[174:177], v[190:193], v[0:3]
	v_mfma_f32_16x16x32_bf16 v[0:3], v[144:147], v[194:197], v[36:39]
	v_mfma_f32_16x16x32_bf16 v[36:39], v[166:169], v[212:215], v[0:3]
	v_mfma_f32_16x16x32_bf16 v[0:3], v[170:173], v[194:197], v[32:35]
	v_mfma_f32_16x16x32_bf16 v[32:35], v[174:177], v[212:215], v[0:3]
	v_mfma_f32_16x16x32_bf16 v[0:3], v[144:147], v[216:219], v[24:27]
	v_mfma_f32_16x16x32_bf16 v[24:27], v[166:169], v[220:223], v[0:3]
	v_mfma_f32_16x16x32_bf16 v[0:3], v[170:173], v[216:219], v[16:19]
	v_mfma_f32_16x16x32_bf16 v[16:19], v[174:177], v[220:223], v[0:3]
	s_barrier
	s_setprio 0
	s_cmp_gt_u32 s23, 29
	s_cbranch_scc1 .LBB0_6335
	s_mov_b32 s23, s62
	s_branch .LBB0_6321

.LBB0_7545:
	s_or_b32 s44, s69, 1
	s_lshl_b64 s[94:95], s[44:45], 7
	s_add_i32 s44, s69, 2
	s_lshl_b64 vcc, s[44:45], 7
	s_add_u32 s42, s64, vcc_lo
	s_addc_u32 s93, s65, vcc_hi
	s_and_b64 s[74:75], s[72:73], exec
	s_cselect_b32 s75, s93, s59
	s_cselect_b32 s74, s42, s58
	s_add_u32 s42, s66, vcc_lo
	s_addc_u32 s93, s67, vcc_hi
	s_add_i32 vcc_lo, 0, 0x10000
	s_and_b64 s[72:73], s[72:73], exec
	s_cselect_b32 s73, s93, s61
	s_cselect_b32 s72, s42, s60
	s_add_i32 s42, 0, 0x14000
	v_add_u32_e32 v140, vcc_lo, v168
	v_add_u32_e32 v173, s42, v168
	ds_read_b128 v[128:131], v140
	ds_read_b128 v[132:135], v140 offset:1024
	ds_read_b128 v[136:139], v140 offset:2048
	ds_read_b128 v[140:143], v140 offset:3072
	ds_read_b128 v[160:163], v173
	ds_read_b128 v[174:177], v173 offset:1024
	ds_read_b128 v[178:181], v173 offset:2048
	ds_read_b128 v[182:185], v173 offset:3072
	s_add_u32 s93, s64, s94
	s_addc_u32 s95, s65, s95
	s_add_u32 s94, s93, 0x80000
	s_addc_u32 s95, s95, 0
	s_nop 0
	s_add_i32 m0, s63, 0xc000
	ds_read_b128 v[186:189], v172
	ds_read_b128 v[190:193], v172 offset:1024
	ds_read_b128 v[194:197], v172 offset:2048
	ds_read_b128 v[198:201], v172 offset:3072
	ds_read_b128 v[206:209], v172 offset:4096
	ds_read_b128 v[210:213], v172 offset:5120
	ds_read_b128 v[214:217], v172 offset:6144
	ds_read_b128 v[218:221], v172 offset:7168
	global_load_lds_dwordx4 v152, s[94:95]
	s_nop 0
	s_add_i32 m0, s63, 0xe000
	s_nop 0
	global_load_lds_dwordx4 v154, s[94:95]
	s_waitcnt vmcnt(8)
	s_waitcnt lgkmcnt(0)
	s_setprio 1
	s_barrier
	v_mfma_f32_16x16x32_bf16 v[124:127], v[128:131], v[186:189], v[124:127]
	v_mfma_f32_16x16x32_bf16 v[120:123], v[136:139], v[186:189], v[120:123]
	v_mfma_f32_16x16x32_bf16 v[108:111], v[128:131], v[194:197], v[108:111]
	v_mfma_f32_16x16x32_bf16 v[104:107], v[136:139], v[194:197], v[104:107]
	v_mfma_f32_16x16x32_bf16 v[92:95], v[128:131], v[206:209], v[92:95]
	v_mfma_f32_16x16x32_bf16 v[88:91], v[136:139], v[206:209], v[88:91]
	v_mfma_f32_16x16x32_bf16 v[76:79], v[128:131], v[214:217], v[76:79]
	v_mfma_f32_16x16x32_bf16 v[72:75], v[136:139], v[214:217], v[72:75]
	v_mfma_f32_16x16x32_bf16 v[124:127], v[132:135], v[190:193], v[124:127]
	v_mfma_f32_16x16x32_bf16 v[120:123], v[140:143], v[190:193], v[120:123]
	v_mfma_f32_16x16x32_bf16 v[108:111], v[132:135], v[198:201], v[108:111]
	v_mfma_f32_16x16x32_bf16 v[104:107], v[140:143], v[198:201], v[104:107]
	v_mfma_f32_16x16x32_bf16 v[92:95], v[132:135], v[210:213], v[92:95]
	v_mfma_f32_16x16x32_bf16 v[88:91], v[140:143], v[210:213], v[88:91]
	v_mfma_f32_16x16x32_bf16 v[76:79], v[132:135], v[218:221], v[76:79]
	v_mfma_f32_16x16x32_bf16 v[72:75], v[140:143], v[218:221], v[72:75]
	v_mfma_f32_16x16x32_bf16 v[116:119], v[160:163], v[186:189], v[116:119]
	v_mfma_f32_16x16x32_bf16 v[112:115], v[178:181], v[186:189], v[112:115]
	v_mfma_f32_16x16x32_bf16 v[100:103], v[160:163], v[194:197], v[100:103]
	v_mfma_f32_16x16x32_bf16 v[96:99], v[178:181], v[194:197], v[96:99]
	v_mfma_f32_16x16x32_bf16 v[84:87], v[160:163], v[206:209], v[84:87]
	v_mfma_f32_16x16x32_bf16 v[80:83], v[178:181], v[206:209], v[80:83]
	v_mfma_f32_16x16x32_bf16 v[68:71], v[160:163], v[214:217], v[68:71]
	v_mfma_f32_16x16x32_bf16 v[64:67], v[178:181], v[214:217], v[64:67]
	v_mfma_f32_16x16x32_bf16 v[116:119], v[174:177], v[190:193], v[116:119]
	v_mfma_f32_16x16x32_bf16 v[112:115], v[182:185], v[190:193], v[112:115]
	v_mfma_f32_16x16x32_bf16 v[100:103], v[174:177], v[198:201], v[100:103]
	v_mfma_f32_16x16x32_bf16 v[96:99], v[182:185], v[198:201], v[96:99]
	v_mfma_f32_16x16x32_bf16 v[84:87], v[174:177], v[210:213], v[84:87]
	v_mfma_f32_16x16x32_bf16 v[80:83], v[182:185], v[210:213], v[80:83]
	v_mfma_f32_16x16x32_bf16 v[68:71], v[174:177], v[218:221], v[68:71]
	v_mfma_f32_16x16x32_bf16 v[64:67], v[182:185], v[218:221], v[64:67]
	s_barrier
	s_setprio 0
	s_add_i32 s93, vcc_lo, s83
	v_lshl_add_u64 v[202:203], s[72:73], 0, v[144:145]
	s_mov_b32 m0, s93
	ds_read_b128 v[186:189], v172 offset:16384
	ds_read_b128 v[190:193], v172 offset:17408
	ds_read_b128 v[194:197], v172 offset:18432
	ds_read_b128 v[198:201], v172 offset:19456
	ds_read_b128 v[206:209], v172 offset:20480
	ds_read_b128 v[210:213], v172 offset:21504
	ds_read_b128 v[214:217], v172 offset:22528
	ds_read_b128 v[218:221], v172 offset:23552
	global_load_lds_dwordx4 v[202:203], off
	s_add_i32 m0, s93, 0x2000
	s_add_u32 s94, s72, 0x80000
	v_lshl_add_u64 v[222:223], s[72:73], 0, v[156:157]
	s_addc_u32 s95, s73, 0
	s_add_i32 s42, s42, s83
	global_load_lds_dwordx4 v[222:223], off
	s_nop 0
	s_mov_b32 m0, s42
	v_lshl_add_u64 v[226:227], s[74:75], 0, v[154:155]
	global_load_lds_dwordx4 v144, s[94:95]
	s_nop 0
	s_add_i32 m0, s42, 0x2000
	s_nop 0
	global_load_lds_dwordx4 v156, s[94:95]
	v_lshl_add_u64 v[224:225], s[74:75], 0, v[152:153]
	s_mov_b32 m0, s63
	s_nop 0
	global_load_lds_dwordx4 v[224:225], off
	s_mov_b32 m0, s84
	s_nop 0
	global_load_lds_dwordx4 v[226:227], off
	s_waitcnt vmcnt(8)
	s_waitcnt lgkmcnt(0)
	s_setprio 1
	s_barrier
	v_mfma_f32_16x16x32_bf16 v[60:63], v[128:131], v[186:189], v[60:63]
	v_mfma_f32_16x16x32_bf16 v[56:59], v[136:139], v[186:189], v[56:59]
	v_mfma_f32_16x16x32_bf16 v[44:47], v[128:131], v[194:197], v[44:47]
	v_mfma_f32_16x16x32_bf16 v[40:43], v[136:139], v[194:197], v[40:43]
	v_mfma_f32_16x16x32_bf16 v[24:27], v[128:131], v[206:209], v[24:27]
	v_mfma_f32_16x16x32_bf16 v[16:19], v[136:139], v[206:209], v[16:19]
	v_mfma_f32_16x16x32_bf16 v[4:7], v[128:131], v[214:217], v[4:7]
	v_mfma_f32_16x16x32_bf16 v[0:3], v[136:139], v[214:217], v[0:3]
	v_mfma_f32_16x16x32_bf16 v[60:63], v[132:135], v[190:193], v[60:63]
	v_mfma_f32_16x16x32_bf16 v[56:59], v[140:143], v[190:193], v[56:59]
	v_mfma_f32_16x16x32_bf16 v[44:47], v[132:135], v[198:201], v[44:47]
	v_mfma_f32_16x16x32_bf16 v[40:43], v[140:143], v[198:201], v[40:43]
	v_mfma_f32_16x16x32_bf16 v[24:27], v[132:135], v[210:213], v[24:27]
	v_mfma_f32_16x16x32_bf16 v[16:19], v[140:143], v[210:213], v[16:19]
	v_mfma_f32_16x16x32_bf16 v[4:7], v[132:135], v[218:221], v[4:7]
	v_mfma_f32_16x16x32_bf16 v[0:3], v[140:143], v[218:221], v[0:3]
	v_mfma_f32_16x16x32_bf16 v[52:55], v[160:163], v[186:189], v[52:55]
	v_mfma_f32_16x16x32_bf16 v[48:51], v[178:181], v[186:189], v[48:51]
	v_mfma_f32_16x16x32_bf16 v[28:31], v[160:163], v[194:197], v[28:31]
	v_mfma_f32_16x16x32_bf16 v[20:23], v[178:181], v[194:197], v[20:23]
	v_mfma_f32_16x16x32_bf16 v[32:35], v[160:163], v[206:209], v[32:35]
	v_mfma_f32_16x16x32_bf16 v[36:39], v[178:181], v[206:209], v[36:39]
	v_mfma_f32_16x16x32_bf16 v[8:11], v[160:163], v[214:217], v[8:11]
	v_mfma_f32_16x16x32_bf16 v[12:15], v[178:181], v[214:217], v[12:15]
	v_mfma_f32_16x16x32_bf16 v[52:55], v[174:177], v[190:193], v[52:55]
	v_mfma_f32_16x16x32_bf16 v[48:51], v[182:185], v[190:193], v[48:51]
	v_mfma_f32_16x16x32_bf16 v[28:31], v[174:177], v[198:201], v[28:31]
	v_mfma_f32_16x16x32_bf16 v[20:23], v[182:185], v[198:201], v[20:23]
	v_mfma_f32_16x16x32_bf16 v[32:35], v[174:177], v[210:213], v[32:35]
	v_mfma_f32_16x16x32_bf16 v[36:39], v[182:185], v[210:213], v[36:39]
	v_mfma_f32_16x16x32_bf16 v[8:11], v[174:177], v[218:221], v[8:11]
	v_mfma_f32_16x16x32_bf16 v[12:15], v[182:185], v[218:221], v[12:15]
	s_barrier
	s_setprio 0
	s_add_i32 s42, 0, 0x18000
	s_add_i32 s93, 0, 0x1c000
	v_add_u32_e32 v140, s42, v168
	v_add_u32_e32 v173, s93, v168
	ds_read_b128 v[128:131], v140
	ds_read_b128 v[132:135], v140 offset:1024
	ds_read_b128 v[136:139], v140 offset:2048
	ds_read_b128 v[140:143], v140 offset:3072
	ds_read_b128 v[160:163], v173
	ds_read_b128 v[174:177], v173 offset:1024
	ds_read_b128 v[178:181], v173 offset:2048
	ds_read_b128 v[182:185], v173 offset:3072
	s_add_u32 s74, s74, 0x80000
	s_addc_u32 s75, s75, 0
	s_mov_b32 m0, s85
	s_nop 0
	ds_read_b128 v[186:189], v172 offset:32768
	ds_read_b128 v[190:193], v172 offset:33792
	ds_read_b128 v[194:197], v172 offset:34816
	ds_read_b128 v[198:201], v172 offset:35840
	ds_read_b128 v[206:209], v172 offset:36864
	ds_read_b128 v[210:213], v172 offset:37888
	ds_read_b128 v[214:217], v172 offset:38912
	ds_read_b128 v[218:221], v172 offset:39936
	global_load_lds_dwordx4 v152, s[74:75]
	s_nop 0
	s_mov_b32 m0, s86
	s_nop 0
	global_load_lds_dwordx4 v154, s[74:75]
	s_waitcnt vmcnt(8)
	s_waitcnt lgkmcnt(0)
	s_setprio 1
	s_barrier
	v_mfma_f32_16x16x32_bf16 v[124:127], v[128:131], v[186:189], v[124:127]
	v_mfma_f32_16x16x32_bf16 v[120:123], v[136:139], v[186:189], v[120:123]
	v_mfma_f32_16x16x32_bf16 v[108:111], v[128:131], v[194:197], v[108:111]
	v_mfma_f32_16x16x32_bf16 v[104:107], v[136:139], v[194:197], v[104:107]
	v_mfma_f32_16x16x32_bf16 v[92:95], v[128:131], v[206:209], v[92:95]
	v_mfma_f32_16x16x32_bf16 v[88:91], v[136:139], v[206:209], v[88:91]
	v_mfma_f32_16x16x32_bf16 v[76:79], v[128:131], v[214:217], v[76:79]
	v_mfma_f32_16x16x32_bf16 v[72:75], v[136:139], v[214:217], v[72:75]
	v_mfma_f32_16x16x32_bf16 v[124:127], v[132:135], v[190:193], v[124:127]
	v_mfma_f32_16x16x32_bf16 v[120:123], v[140:143], v[190:193], v[120:123]
	v_mfma_f32_16x16x32_bf16 v[108:111], v[132:135], v[198:201], v[108:111]
	v_mfma_f32_16x16x32_bf16 v[104:107], v[140:143], v[198:201], v[104:107]
	v_mfma_f32_16x16x32_bf16 v[92:95], v[132:135], v[210:213], v[92:95]
	v_mfma_f32_16x16x32_bf16 v[88:91], v[140:143], v[210:213], v[88:91]
	v_mfma_f32_16x16x32_bf16 v[76:79], v[132:135], v[218:221], v[76:79]
	v_mfma_f32_16x16x32_bf16 v[72:75], v[140:143], v[218:221], v[72:75]
	v_mfma_f32_16x16x32_bf16 v[116:119], v[160:163], v[186:189], v[116:119]
	v_mfma_f32_16x16x32_bf16 v[112:115], v[178:181], v[186:189], v[112:115]
	v_mfma_f32_16x16x32_bf16 v[100:103], v[160:163], v[194:197], v[100:103]
	v_mfma_f32_16x16x32_bf16 v[96:99], v[178:181], v[194:197], v[96:99]
	v_mfma_f32_16x16x32_bf16 v[84:87], v[160:163], v[206:209], v[84:87]
	v_mfma_f32_16x16x32_bf16 v[80:83], v[178:181], v[206:209], v[80:83]
	v_mfma_f32_16x16x32_bf16 v[68:71], v[160:163], v[214:217], v[68:71]
	v_mfma_f32_16x16x32_bf16 v[64:67], v[178:181], v[214:217], v[64:67]
	v_mfma_f32_16x16x32_bf16 v[116:119], v[174:177], v[190:193], v[116:119]
	v_mfma_f32_16x16x32_bf16 v[112:115], v[182:185], v[190:193], v[112:115]
	v_mfma_f32_16x16x32_bf16 v[100:103], v[174:177], v[198:201], v[100:103]
	v_mfma_f32_16x16x32_bf16 v[96:99], v[182:185], v[198:201], v[96:99]
	v_mfma_f32_16x16x32_bf16 v[84:87], v[174:177], v[210:213], v[84:87]
	v_mfma_f32_16x16x32_bf16 v[80:83], v[182:185], v[210:213], v[80:83]
	v_mfma_f32_16x16x32_bf16 v[68:71], v[174:177], v[218:221], v[68:71]
	v_mfma_f32_16x16x32_bf16 v[64:67], v[182:185], v[218:221], v[64:67]
	s_barrier
	s_setprio 0
	s_add_i32 s42, s42, s83
	s_nop 0
	s_add_i32 m0, s42, 0xffffff80
	ds_read_b128 v[186:189], v172 offset:49152
	ds_read_b128 v[190:193], v172 offset:50176
	ds_read_b128 v[194:197], v172 offset:51200
	ds_read_b128 v[198:201], v172 offset:52224
	ds_read_b128 v[206:209], v172 offset:53248
	ds_read_b128 v[210:213], v172 offset:54272
	ds_read_b128 v[214:217], v172 offset:55296
	ds_read_b128 v[218:221], v172 offset:56320
	global_load_lds_dwordx4 v[202:203], off offset:128
	s_add_i32 m0, s42, 0x1f80
	s_add_u32 s72, s72, 0x80080
	s_nop 0
	s_addc_u32 s73, s73, 0
	s_add_i32 s42, s93, s83
	global_load_lds_dwordx4 v[222:223], off offset:128
	s_nop 0
	s_mov_b32 m0, s42
	s_nop 0
	global_load_lds_dwordx4 v144, s[72:73]
	s_nop 0
	s_add_i32 m0, s42, 0x2000
	s_nop 0
	global_load_lds_dwordx4 v156, s[72:73]
	s_nop 0
	s_add_i32 m0, s87, 0xffffff80
	s_nop 0
	global_load_lds_dwordx4 v[224:225], off offset:128
	s_nop 0
	s_add_i32 m0, s88, 0xffffff80
	s_nop 0
	global_load_lds_dwordx4 v[226:227], off offset:128
	s_waitcnt vmcnt(8)
	s_waitcnt lgkmcnt(0)
	s_setprio 1
	s_barrier
	v_mfma_f32_16x16x32_bf16 v[60:63], v[128:131], v[186:189], v[60:63]
	v_mfma_f32_16x16x32_bf16 v[56:59], v[136:139], v[186:189], v[56:59]
	v_mfma_f32_16x16x32_bf16 v[44:47], v[128:131], v[194:197], v[44:47]
	v_mfma_f32_16x16x32_bf16 v[40:43], v[136:139], v[194:197], v[40:43]
	v_mfma_f32_16x16x32_bf16 v[24:27], v[128:131], v[206:209], v[24:27]
	v_mfma_f32_16x16x32_bf16 v[16:19], v[136:139], v[206:209], v[16:19]
	v_mfma_f32_16x16x32_bf16 v[4:7], v[128:131], v[214:217], v[4:7]
	v_mfma_f32_16x16x32_bf16 v[0:3], v[136:139], v[214:217], v[0:3]
	v_mfma_f32_16x16x32_bf16 v[60:63], v[132:135], v[190:193], v[60:63]
	v_mfma_f32_16x16x32_bf16 v[56:59], v[140:143], v[190:193], v[56:59]
	v_mfma_f32_16x16x32_bf16 v[44:47], v[132:135], v[198:201], v[44:47]
	v_mfma_f32_16x16x32_bf16 v[40:43], v[140:143], v[198:201], v[40:43]
	v_mfma_f32_16x16x32_bf16 v[24:27], v[132:135], v[210:213], v[24:27]
	v_mfma_f32_16x16x32_bf16 v[16:19], v[140:143], v[210:213], v[16:19]
	v_mfma_f32_16x16x32_bf16 v[4:7], v[132:135], v[218:221], v[4:7]
	v_mfma_f32_16x16x32_bf16 v[0:3], v[140:143], v[218:221], v[0:3]
	v_mfma_f32_16x16x32_bf16 v[52:55], v[160:163], v[186:189], v[52:55]
	v_mfma_f32_16x16x32_bf16 v[48:51], v[178:181], v[186:189], v[48:51]
	v_mfma_f32_16x16x32_bf16 v[28:31], v[160:163], v[194:197], v[28:31]
	v_mfma_f32_16x16x32_bf16 v[20:23], v[178:181], v[194:197], v[20:23]
	v_mfma_f32_16x16x32_bf16 v[32:35], v[160:163], v[206:209], v[32:35]
	v_mfma_f32_16x16x32_bf16 v[36:39], v[178:181], v[206:209], v[36:39]
	v_mfma_f32_16x16x32_bf16 v[8:11], v[160:163], v[214:217], v[8:11]
	v_mfma_f32_16x16x32_bf16 v[12:15], v[178:181], v[214:217], v[12:15]
	v_mfma_f32_16x16x32_bf16 v[52:55], v[174:177], v[190:193], v[52:55]
	v_mfma_f32_16x16x32_bf16 v[48:51], v[182:185], v[190:193], v[48:51]
	v_mfma_f32_16x16x32_bf16 v[28:31], v[174:177], v[198:201], v[28:31]
	v_mfma_f32_16x16x32_bf16 v[20:23], v[182:185], v[198:201], v[20:23]
	v_mfma_f32_16x16x32_bf16 v[32:35], v[174:177], v[210:213], v[32:35]
	v_mfma_f32_16x16x32_bf16 v[36:39], v[182:185], v[210:213], v[36:39]
	v_mfma_f32_16x16x32_bf16 v[8:11], v[174:177], v[218:221], v[8:11]
	v_mfma_f32_16x16x32_bf16 v[12:15], v[182:185], v[218:221], v[12:15]
	s_barrier
	s_setprio 0
	s_cmp_gt_u32 s69, 29
	s_cbranch_scc1 .LBB0_7547
	s_mov_b32 s69, s44
	s_branch .LBB0_7533

.LBB0_7633:
	s_add_i32 vcc_hi, s26, 2
	s_add_u32 s94, s22, 0x80
	s_addc_u32 s27, s23, 0
	s_add_i32 s93, 0, 0x10000
	s_cmp_eq_u32 s90, s26
	s_cselect_b32 s27, s44, s27
	s_cselect_b32 s26, s57, s94
	v_add_u32_e32 v155, s93, v143
	s_cselect_b32 s95, s62, vcc_lo
	s_cselect_b32 s94, s63, s91
	s_add_i32 s42, 0, 0x14000
	ds_read_b128 v[138:141], v155
	ds_read_b128 v[156:159], v155 offset:1024
	ds_read_b128 v[160:163], v155 offset:2048
	ds_read_b128 v[166:169], v155 offset:3072
	v_add_u32_e32 v155, s42, v143
	ds_read_b128 v[170:173], v155
	ds_read_b128 v[174:177], v155 offset:1024
	ds_read_b128 v[178:181], v155 offset:2048
	ds_read_b128 v[182:185], v155 offset:3072
	s_nop 0
	s_add_i32 m0, s73, 0xc000
	ds_read_b128 v[186:189], v154
	ds_read_b128 v[190:193], v154 offset:1024
	ds_read_b128 v[194:197], v154 offset:2048
	ds_read_b128 v[198:201], v154 offset:3072
	ds_read_b128 v[206:209], v154 offset:4096
	ds_read_b128 v[210:213], v154 offset:5120
	ds_read_b128 v[214:217], v154 offset:6144
	ds_read_b128 v[218:221], v154 offset:7168
	global_load_lds_dwordx4 v136, s[22:23]
	s_nop 0
	s_add_i32 m0, s73, 0xe000
	s_nop 0
	global_load_lds_dwordx4 v134, s[22:23]
	s_waitcnt vmcnt(8)
	s_waitcnt lgkmcnt(0)
	s_setprio 1
	s_barrier
	v_mfma_f32_16x16x32_bf16 v[124:127], v[138:141], v[186:189], v[124:127]
	v_mfma_f32_16x16x32_bf16 v[120:123], v[160:163], v[186:189], v[120:123]
	v_mfma_f32_16x16x32_bf16 v[108:111], v[138:141], v[194:197], v[108:111]
	v_mfma_f32_16x16x32_bf16 v[104:107], v[160:163], v[194:197], v[104:107]
	v_mfma_f32_16x16x32_bf16 v[92:95], v[138:141], v[206:209], v[92:95]
	v_mfma_f32_16x16x32_bf16 v[88:91], v[160:163], v[206:209], v[88:91]
	v_mfma_f32_16x16x32_bf16 v[76:79], v[138:141], v[214:217], v[76:79]
	v_mfma_f32_16x16x32_bf16 v[72:75], v[160:163], v[214:217], v[72:75]
	v_mfma_f32_16x16x32_bf16 v[124:127], v[156:159], v[190:193], v[124:127]
	v_mfma_f32_16x16x32_bf16 v[120:123], v[166:169], v[190:193], v[120:123]
	v_mfma_f32_16x16x32_bf16 v[108:111], v[156:159], v[198:201], v[108:111]
	v_mfma_f32_16x16x32_bf16 v[104:107], v[166:169], v[198:201], v[104:107]
	v_mfma_f32_16x16x32_bf16 v[92:95], v[156:159], v[210:213], v[92:95]
	v_mfma_f32_16x16x32_bf16 v[88:91], v[166:169], v[210:213], v[88:91]
	v_mfma_f32_16x16x32_bf16 v[76:79], v[156:159], v[218:221], v[76:79]
	v_mfma_f32_16x16x32_bf16 v[72:75], v[166:169], v[218:221], v[72:75]
	v_mfma_f32_16x16x32_bf16 v[116:119], v[170:173], v[186:189], v[116:119]
	v_mfma_f32_16x16x32_bf16 v[112:115], v[178:181], v[186:189], v[112:115]
	v_mfma_f32_16x16x32_bf16 v[100:103], v[170:173], v[194:197], v[100:103]
	v_mfma_f32_16x16x32_bf16 v[96:99], v[178:181], v[194:197], v[96:99]
	v_mfma_f32_16x16x32_bf16 v[84:87], v[170:173], v[206:209], v[84:87]
	v_mfma_f32_16x16x32_bf16 v[80:83], v[178:181], v[206:209], v[80:83]
	v_mfma_f32_16x16x32_bf16 v[68:71], v[170:173], v[214:217], v[68:71]
	v_mfma_f32_16x16x32_bf16 v[64:67], v[178:181], v[214:217], v[64:67]
	v_mfma_f32_16x16x32_bf16 v[116:119], v[174:177], v[190:193], v[116:119]
	v_mfma_f32_16x16x32_bf16 v[112:115], v[182:185], v[190:193], v[112:115]
	v_mfma_f32_16x16x32_bf16 v[100:103], v[174:177], v[198:201], v[100:103]
	v_mfma_f32_16x16x32_bf16 v[96:99], v[182:185], v[198:201], v[96:99]
	v_mfma_f32_16x16x32_bf16 v[84:87], v[174:177], v[210:213], v[84:87]
	v_mfma_f32_16x16x32_bf16 v[80:83], v[182:185], v[210:213], v[80:83]
	v_mfma_f32_16x16x32_bf16 v[68:71], v[174:177], v[218:221], v[68:71]
	v_mfma_f32_16x16x32_bf16 v[64:67], v[182:185], v[218:221], v[64:67]
	s_barrier
	s_setprio 0
	s_add_i32 s93, s93, s72
	v_lshl_add_u64 v[202:203], s[94:95], 0, v[144:145]
	s_mov_b32 m0, s93
	ds_read_b128 v[186:189], v154 offset:16384
	ds_read_b128 v[190:193], v154 offset:17408
	ds_read_b128 v[194:197], v154 offset:18432
	ds_read_b128 v[198:201], v154 offset:19456
	ds_read_b128 v[206:209], v154 offset:20480
	ds_read_b128 v[210:213], v154 offset:21504
	ds_read_b128 v[214:217], v154 offset:22528
	ds_read_b128 v[218:221], v154 offset:23552
	global_load_lds_dwordx4 v[202:203], off
	s_add_i32 m0, s93, 0x2000
	v_lshl_add_u64 v[222:223], s[94:95], 0, v[132:133]
	s_add_u32 s94, s94, s20
	s_addc_u32 s95, s95, 0
	s_add_i32 s42, s42, s72
	global_load_lds_dwordx4 v[222:223], off
	v_lshl_add_u64 v[224:225], s[94:95], 0, v[144:145]
	s_mov_b32 m0, s42
	v_lshl_add_u64 v[226:227], s[94:95], 0, v[132:133]
	global_load_lds_dwordx4 v[224:225], off
	s_add_i32 m0, s42, 0x2000
	v_lshl_add_u64 v[228:229], s[26:27], 0, v[128:129]
	global_load_lds_dwordx4 v[226:227], off
	s_mov_b32 m0, s73
	v_lshl_add_u64 v[230:231], s[26:27], 0, v[130:131]
	global_load_lds_dwordx4 v[228:229], off
	s_mov_b32 m0, s74
	s_nop 0
	global_load_lds_dwordx4 v[230:231], off
	s_waitcnt vmcnt(8)
	s_waitcnt lgkmcnt(0)
	s_setprio 1
	s_barrier
	v_mfma_f32_16x16x32_bf16 v[60:63], v[138:141], v[186:189], v[60:63]
	v_mfma_f32_16x16x32_bf16 v[56:59], v[160:163], v[186:189], v[56:59]
	v_mfma_f32_16x16x32_bf16 v[44:47], v[138:141], v[194:197], v[44:47]
	v_mfma_f32_16x16x32_bf16 v[40:43], v[160:163], v[194:197], v[40:43]
	v_mfma_f32_16x16x32_bf16 v[28:31], v[138:141], v[206:209], v[28:31]
	v_mfma_f32_16x16x32_bf16 v[24:27], v[160:163], v[206:209], v[24:27]
	v_mfma_f32_16x16x32_bf16 v[12:15], v[138:141], v[214:217], v[12:15]
	v_mfma_f32_16x16x32_bf16 v[8:11], v[160:163], v[214:217], v[8:11]
	v_mfma_f32_16x16x32_bf16 v[60:63], v[156:159], v[190:193], v[60:63]
	v_mfma_f32_16x16x32_bf16 v[56:59], v[166:169], v[190:193], v[56:59]
	v_mfma_f32_16x16x32_bf16 v[44:47], v[156:159], v[198:201], v[44:47]
	v_mfma_f32_16x16x32_bf16 v[40:43], v[166:169], v[198:201], v[40:43]
	v_mfma_f32_16x16x32_bf16 v[28:31], v[156:159], v[210:213], v[28:31]
	v_mfma_f32_16x16x32_bf16 v[24:27], v[166:169], v[210:213], v[24:27]
	v_mfma_f32_16x16x32_bf16 v[12:15], v[156:159], v[218:221], v[12:15]
	v_mfma_f32_16x16x32_bf16 v[8:11], v[166:169], v[218:221], v[8:11]
	v_mfma_f32_16x16x32_bf16 v[52:55], v[170:173], v[186:189], v[52:55]
	v_mfma_f32_16x16x32_bf16 v[48:51], v[178:181], v[186:189], v[48:51]
	v_mfma_f32_16x16x32_bf16 v[36:39], v[170:173], v[194:197], v[36:39]
	v_mfma_f32_16x16x32_bf16 v[32:35], v[178:181], v[194:197], v[32:35]
	v_mfma_f32_16x16x32_bf16 v[20:23], v[170:173], v[206:209], v[20:23]
	v_mfma_f32_16x16x32_bf16 v[16:19], v[178:181], v[206:209], v[16:19]
	v_mfma_f32_16x16x32_bf16 v[4:7], v[170:173], v[214:217], v[4:7]
	v_mfma_f32_16x16x32_bf16 v[0:3], v[178:181], v[214:217], v[0:3]
	v_mfma_f32_16x16x32_bf16 v[52:55], v[174:177], v[190:193], v[52:55]
	v_mfma_f32_16x16x32_bf16 v[48:51], v[182:185], v[190:193], v[48:51]
	v_mfma_f32_16x16x32_bf16 v[36:39], v[174:177], v[198:201], v[36:39]
	v_mfma_f32_16x16x32_bf16 v[32:35], v[182:185], v[198:201], v[32:35]
	v_mfma_f32_16x16x32_bf16 v[20:23], v[174:177], v[210:213], v[20:23]
	v_mfma_f32_16x16x32_bf16 v[16:19], v[182:185], v[210:213], v[16:19]
	v_mfma_f32_16x16x32_bf16 v[4:7], v[174:177], v[218:221], v[4:7]
	v_mfma_f32_16x16x32_bf16 v[0:3], v[182:185], v[218:221], v[0:3]
	s_barrier
	s_setprio 0
	s_add_i32 s42, 0, 0x18000
	v_add_u32_e32 v155, s42, v143
	s_add_i32 s93, 0, 0x1c000
	ds_read_b128 v[138:141], v155
	ds_read_b128 v[156:159], v155 offset:1024
	ds_read_b128 v[160:163], v155 offset:2048
	ds_read_b128 v[166:169], v155 offset:3072
	v_add_u32_e32 v155, s93, v143
	ds_read_b128 v[170:173], v155
	ds_read_b128 v[174:177], v155 offset:1024
	ds_read_b128 v[178:181], v155 offset:2048
	ds_read_b128 v[182:185], v155 offset:3072
	s_add_u32 s26, s26, s20
	s_addc_u32 s27, s27, 0
	s_mov_b32 m0, s75
	s_nop 0
	ds_read_b128 v[186:189], v154 offset:32768
	ds_read_b128 v[190:193], v154 offset:33792
	ds_read_b128 v[194:197], v154 offset:34816
	ds_read_b128 v[198:201], v154 offset:35840
	ds_read_b128 v[206:209], v154 offset:36864
	ds_read_b128 v[210:213], v154 offset:37888
	ds_read_b128 v[214:217], v154 offset:38912
	ds_read_b128 v[218:221], v154 offset:39936
	global_load_lds_dwordx4 v128, s[26:27]
	s_nop 0
	s_mov_b32 m0, s80
	s_nop 0
	global_load_lds_dwordx4 v130, s[26:27]
	s_waitcnt vmcnt(8)
	s_waitcnt lgkmcnt(0)
	s_setprio 1
	s_barrier
	v_mfma_f32_16x16x32_bf16 v[124:127], v[138:141], v[186:189], v[124:127]
	v_mfma_f32_16x16x32_bf16 v[120:123], v[160:163], v[186:189], v[120:123]
	v_mfma_f32_16x16x32_bf16 v[108:111], v[138:141], v[194:197], v[108:111]
	v_mfma_f32_16x16x32_bf16 v[104:107], v[160:163], v[194:197], v[104:107]
	v_mfma_f32_16x16x32_bf16 v[92:95], v[138:141], v[206:209], v[92:95]
	v_mfma_f32_16x16x32_bf16 v[88:91], v[160:163], v[206:209], v[88:91]
	v_mfma_f32_16x16x32_bf16 v[76:79], v[138:141], v[214:217], v[76:79]
	v_mfma_f32_16x16x32_bf16 v[72:75], v[160:163], v[214:217], v[72:75]
	v_mfma_f32_16x16x32_bf16 v[124:127], v[156:159], v[190:193], v[124:127]
	v_mfma_f32_16x16x32_bf16 v[120:123], v[166:169], v[190:193], v[120:123]
	v_mfma_f32_16x16x32_bf16 v[108:111], v[156:159], v[198:201], v[108:111]
	v_mfma_f32_16x16x32_bf16 v[104:107], v[166:169], v[198:201], v[104:107]
	v_mfma_f32_16x16x32_bf16 v[92:95], v[156:159], v[210:213], v[92:95]
	v_mfma_f32_16x16x32_bf16 v[88:91], v[166:169], v[210:213], v[88:91]
	v_mfma_f32_16x16x32_bf16 v[76:79], v[156:159], v[218:221], v[76:79]
	v_mfma_f32_16x16x32_bf16 v[72:75], v[166:169], v[218:221], v[72:75]
	v_mfma_f32_16x16x32_bf16 v[116:119], v[170:173], v[186:189], v[116:119]
	v_mfma_f32_16x16x32_bf16 v[112:115], v[178:181], v[186:189], v[112:115]
	v_mfma_f32_16x16x32_bf16 v[100:103], v[170:173], v[194:197], v[100:103]
	v_mfma_f32_16x16x32_bf16 v[96:99], v[178:181], v[194:197], v[96:99]
	v_mfma_f32_16x16x32_bf16 v[84:87], v[170:173], v[206:209], v[84:87]
	v_mfma_f32_16x16x32_bf16 v[80:83], v[178:181], v[206:209], v[80:83]
	v_mfma_f32_16x16x32_bf16 v[68:71], v[170:173], v[214:217], v[68:71]
	v_mfma_f32_16x16x32_bf16 v[64:67], v[178:181], v[214:217], v[64:67]
	v_mfma_f32_16x16x32_bf16 v[116:119], v[174:177], v[190:193], v[116:119]
	v_mfma_f32_16x16x32_bf16 v[112:115], v[182:185], v[190:193], v[112:115]
	v_mfma_f32_16x16x32_bf16 v[100:103], v[174:177], v[198:201], v[100:103]
	v_mfma_f32_16x16x32_bf16 v[96:99], v[182:185], v[198:201], v[96:99]
	v_mfma_f32_16x16x32_bf16 v[84:87], v[174:177], v[210:213], v[84:87]
	v_mfma_f32_16x16x32_bf16 v[80:83], v[182:185], v[210:213], v[80:83]
	v_mfma_f32_16x16x32_bf16 v[68:71], v[174:177], v[218:221], v[68:71]
	v_mfma_f32_16x16x32_bf16 v[64:67], v[182:185], v[218:221], v[64:67]
	s_barrier
	s_setprio 0
	s_add_i32 s26, s42, s72
	s_nop 0
	s_add_i32 m0, s26, 0xffffff80
	ds_read_b128 v[186:189], v154 offset:49152
	ds_read_b128 v[190:193], v154 offset:50176
	ds_read_b128 v[194:197], v154 offset:51200
	ds_read_b128 v[198:201], v154 offset:52224
	ds_read_b128 v[206:209], v154 offset:53248
	ds_read_b128 v[210:213], v154 offset:54272
	ds_read_b128 v[214:217], v154 offset:55296
	ds_read_b128 v[218:221], v154 offset:56320
	global_load_lds_dwordx4 v[202:203], off offset:128
	s_nop 0
	s_add_i32 m0, s26, 0x1f80
	s_add_i32 s26, s93, s72
	global_load_lds_dwordx4 v[222:223], off offset:128
	s_nop 0
	s_add_i32 m0, s26, 0xffffff80
	s_nop 0
	global_load_lds_dwordx4 v[224:225], off offset:128
	s_nop 0
	s_add_i32 m0, s26, 0x1f80
	s_nop 0
	global_load_lds_dwordx4 v[226:227], off offset:128
	s_nop 0
	s_add_i32 m0, s85, 0xffffff80
	s_nop 0
	global_load_lds_dwordx4 v[228:229], off offset:128
	s_nop 0
	s_add_i32 m0, s86, 0xffffff80
	s_nop 0
	global_load_lds_dwordx4 v[230:231], off offset:128
	s_waitcnt vmcnt(8)
	s_waitcnt lgkmcnt(0)
	s_setprio 1
	s_barrier
	v_mfma_f32_16x16x32_bf16 v[60:63], v[138:141], v[186:189], v[60:63]
	v_mfma_f32_16x16x32_bf16 v[56:59], v[160:163], v[186:189], v[56:59]
	v_mfma_f32_16x16x32_bf16 v[44:47], v[138:141], v[194:197], v[44:47]
	v_mfma_f32_16x16x32_bf16 v[40:43], v[160:163], v[194:197], v[40:43]
	v_mfma_f32_16x16x32_bf16 v[28:31], v[138:141], v[206:209], v[28:31]
	v_mfma_f32_16x16x32_bf16 v[24:27], v[160:163], v[206:209], v[24:27]
	v_mfma_f32_16x16x32_bf16 v[12:15], v[138:141], v[214:217], v[12:15]
	v_mfma_f32_16x16x32_bf16 v[8:11], v[160:163], v[214:217], v[8:11]
	v_mfma_f32_16x16x32_bf16 v[60:63], v[156:159], v[190:193], v[60:63]
	v_mfma_f32_16x16x32_bf16 v[56:59], v[166:169], v[190:193], v[56:59]
	v_mfma_f32_16x16x32_bf16 v[44:47], v[156:159], v[198:201], v[44:47]
	v_mfma_f32_16x16x32_bf16 v[40:43], v[166:169], v[198:201], v[40:43]
	v_mfma_f32_16x16x32_bf16 v[28:31], v[156:159], v[210:213], v[28:31]
	v_mfma_f32_16x16x32_bf16 v[24:27], v[166:169], v[210:213], v[24:27]
	v_mfma_f32_16x16x32_bf16 v[12:15], v[156:159], v[218:221], v[12:15]
	v_mfma_f32_16x16x32_bf16 v[8:11], v[166:169], v[218:221], v[8:11]
	v_mfma_f32_16x16x32_bf16 v[52:55], v[170:173], v[186:189], v[52:55]
	v_mfma_f32_16x16x32_bf16 v[48:51], v[178:181], v[186:189], v[48:51]
	v_mfma_f32_16x16x32_bf16 v[36:39], v[170:173], v[194:197], v[36:39]
	v_mfma_f32_16x16x32_bf16 v[32:35], v[178:181], v[194:197], v[32:35]
	v_mfma_f32_16x16x32_bf16 v[20:23], v[170:173], v[206:209], v[20:23]
	v_mfma_f32_16x16x32_bf16 v[16:19], v[178:181], v[206:209], v[16:19]
	v_mfma_f32_16x16x32_bf16 v[4:7], v[170:173], v[214:217], v[4:7]
	v_mfma_f32_16x16x32_bf16 v[0:3], v[178:181], v[214:217], v[0:3]
	v_mfma_f32_16x16x32_bf16 v[52:55], v[174:177], v[190:193], v[52:55]
	v_mfma_f32_16x16x32_bf16 v[48:51], v[182:185], v[190:193], v[48:51]
	v_mfma_f32_16x16x32_bf16 v[36:39], v[174:177], v[198:201], v[36:39]
	v_mfma_f32_16x16x32_bf16 v[32:35], v[182:185], v[198:201], v[32:35]
	v_mfma_f32_16x16x32_bf16 v[20:23], v[174:177], v[210:213], v[20:23]
	v_mfma_f32_16x16x32_bf16 v[16:19], v[182:185], v[210:213], v[16:19]
	v_mfma_f32_16x16x32_bf16 v[4:7], v[174:177], v[218:221], v[4:7]
	v_mfma_f32_16x16x32_bf16 v[0:3], v[182:185], v[218:221], v[0:3]
	s_barrier
	s_setprio 0
	s_add_u32 s91, s91, 0x100
	s_addc_u32 vcc_lo, vcc_lo, 0
	s_add_u32 s22, s22, 0x100
	s_addc_u32 s23, s23, 0
	s_cmp_ge_i32 vcc_hi, s1
	s_mov_b32 s26, vcc_hi
	s_cbranch_scc0 .LBB0_7633
	s_and_b64 vcc, exec, s[50:51]
	s_cbranch_vccz .LBB0_7636
	s_barrier
